# NA attention hand-written (two LDS phases, chunked online softmax, 4 barriers/unit); dense loop: exp and its add/cvt consumers one MFMA gap apart
# speedup vs baseline: 1.0134x; 1.0042x over previous
.LBB0_301:
	s_add_i32 s30, s27, s19
	s_cmpk_gt_i32 s30, 0x1ff
	s_mov_b64 s[12:13], -1
	s_cbranch_scc1 .LBB0_300
	s_ashr_i32 s28, s30, 8
	s_and_b32 s31, s26, 0x80
	s_mul_i32 s13, s28, 0x6000000
	s_mul_hi_i32 s12, s28, 0x6000000
	s_add_u32 s33, s37, s13
	s_addc_u32 s35, s40, s12
	s_lshl_b32 s12, s30, 1
	s_and_b32 s29, s12, 0x1c0
	s_lshl_b32 s12, s29, 1
	s_add_u32 s12, s33, s12
	s_addc_u32 s13, s35, 0
	s_and_b32 s34, s30, 0x80
	s_add_u32 s34, s33, s34
	s_addc_u32 s35, s35, 0
	s_lshl_b32 s30, s30, 9
	v_mov_b32_e32 v14, v0
	s_and_b32 s30, s30, 0x3e00
	v_mov_b32_e32 v11, v171
	v_readfirstlane_b32 s33, v14
	s_andn2_b32 s33, s33, 63
	v_and_or_b32 v2, v14, 31, s30
	v_bfe_u32 v15, v14, 5, 1
	v_add_u32_e32 v172, s33, v2
	v_mov_b64_e32 v[2:3], s[12:13]
	v_mad_i64_i32 v[2:3], s[12:13], v172, s20, v[2:3]
	v_lshlrev_b32_e32 v170, 4, v15
	v_lshl_add_u64 v[2:3], v[2:3], 0, v[170:171]
	v_lshl_add_u64 v[4:5], v[2:3], 0, s[6:7]
	v_add_co_u32_e32 v6, vcc, s21, v2
	v_ashrrev_i32_e32 v16, 3, v14
	s_nop 0
	v_addc_co_u32_e32 v7, vcc, 0, v3, vcc
	global_load_dwordx4 v[130:133], v[2:3], off
	global_load_dwordx4 v[134:137], v[2:3], off offset:32
	global_load_dwordx4 v[138:141], v[4:5], off offset:32
	global_load_dwordx4 v[142:145], v[4:5], off offset:64
	global_load_dwordx4 v[146:149], v[2:3], off offset:64
	global_load_dwordx4 v[150:153], v[2:3], off offset:96
	global_load_dwordx4 v[154:157], v[6:7], off
	global_load_dwordx4 v[158:161], v[4:5], off offset:96
	v_mov_b64_e32 v[2:3], s[34:35]
	v_lshlrev_b32_e32 v4, 4, v14
	v_mad_i64_i32 v[2:3], s[12:13], v16, s20, v[2:3]
	v_and_b32_e32 v10, 0x70, v4
	v_lshl_add_u64 v[12:13], v[2:3], 0, v[10:11]
	global_load_dwordx4 v[2:5], v[12:13], off offset:1024
	global_load_dwordx4 v[6:9], v[12:13], off offset:1280
	v_add_co_u32_e32 v12, vcc, s23, v12
	s_waitcnt lgkmcnt(0)
	s_nop 0
	v_addc_co_u32_e32 v13, vcc, 0, v13, vcc
	s_barrier
	global_load_dwordx4 v[162:165], v[12:13], off offset:1024
	global_load_dwordx4 v[166:169], v[12:13], off offset:1280
	v_lshlrev_b32_e32 v12, 1, v14
	v_lshrrev_b32_e32 v13, 1, v14
	v_lshlrev_b32_e32 v174, 3, v15
	v_and_b32_e32 v15, 8, v12
	v_and_b32_e32 v18, 4, v13
	v_and_b32_e32 v173, 32, v12
	v_mad_i64_i32 v[12:13], s[12:13], v16, s20, 0
	v_and_b32_e32 v11, 19, v14
	v_lshrrev_b32_e32 v17, 2, v14
	v_lshlrev_b32_e32 v14, 3, v14
	v_mul_lo_u32 v19, v16, s22
	v_mad_i64_i32 v[12:13], s[12:13], s28, v1, v[12:13]
	v_mov_b32_e32 v50, 0
	v_and_b32_e32 v175, 24, v14
	v_or3_b32 v11, v11, v15, v18
	v_and_or_b32 v14, v17, 3, v174
	v_add3_u32 v180, 0, v19, v10
	v_or3_b32 v12, v12, s31, v10
	s_mov_b32 s33, 0
	s_mov_b32 s30, 0
	v_mov_b32_e32 v51, v50
	v_mov_b32_e32 v52, v50
	v_mov_b32_e32 v53, v50
	v_mov_b32_e32 v54, v50
	v_mov_b32_e32 v55, v50
	v_mov_b32_e32 v56, v50
	v_mov_b32_e32 v57, v50
	v_mov_b32_e32 v58, v50
	v_mul_u32_u24_e32 v181, 0x90, v11
	v_mul_u32_u24_e32 v182, 0x90, v14
	v_lshl_add_u64 v[176:177], s[4:5], 0, v[12:13]
	v_mov_b32_e32 v59, v50
	v_mov_b32_e32 v60, v50
	v_mov_b32_e32 v61, v50
	v_mov_b32_e32 v62, v50
	v_mov_b32_e32 v63, v50
	v_mov_b32_e32 v64, v50
	v_mov_b32_e32 v65, v50
	v_mov_b32_e32 v34, v50
	v_mov_b32_e32 v35, v50
	v_mov_b32_e32 v36, v50
	v_mov_b32_e32 v37, v50
	v_mov_b32_e32 v38, v50
	v_mov_b32_e32 v39, v50
	v_mov_b32_e32 v40, v50
	v_mov_b32_e32 v41, v50
	v_mov_b32_e32 v42, v50
	v_mov_b32_e32 v43, v50
	s_waitcnt vmcnt(3)
	ds_write_b128 v180, v[2:5]
	s_waitcnt vmcnt(2)
	ds_write_b128 v180, v[6:9] offset:9216
	s_waitcnt vmcnt(1)
	ds_write_b128 v180, v[162:165] offset:18432
	s_waitcnt vmcnt(0)
	ds_write_b128 v180, v[166:169] offset:27648
	v_mov_b32_e32 v44, v50
	v_mov_b32_e32 v45, v50
	v_mov_b32_e32 v46, v50
	v_mov_b32_e32 v47, v50
	v_mov_b32_e32 v48, v50
	v_mov_b32_e32 v49, v50
	v_mov_b32_e32 v2, v50
	v_mov_b32_e32 v3, v50
	v_mov_b32_e32 v4, v50
	v_mov_b32_e32 v5, v50
	v_mov_b32_e32 v6, v50
	v_mov_b32_e32 v7, v50
	v_mov_b32_e32 v8, v50
	v_mov_b32_e32 v9, v50
	v_mov_b32_e32 v10, v50
	v_mov_b32_e32 v11, v50
	v_mov_b32_e32 v12, v50
	v_mov_b32_e32 v13, v50
	v_mov_b32_e32 v14, v50
	v_mov_b32_e32 v15, v50
	v_mov_b32_e32 v16, v50
	v_mov_b32_e32 v17, v50
	v_mov_b32_e32 v18, v50
	v_mov_b32_e32 v19, v50
	v_mov_b32_e32 v20, v50
	v_mov_b32_e32 v21, v50
	v_mov_b32_e32 v22, v50
	v_mov_b32_e32 v23, v50
	v_mov_b32_e32 v24, v50
	v_mov_b32_e32 v25, v50
	v_mov_b32_e32 v26, v50
	v_mov_b32_e32 v27, v50
	v_mov_b32_e32 v28, v50
	v_mov_b32_e32 v29, v50
	v_mov_b32_e32 v30, v50
	v_mov_b32_e32 v31, v50
	v_mov_b32_e32 v32, v50
	v_mov_b32_e32 v33, v50
	v_mov_b32_e32 v178, v50
	v_mov_b32_e32 v179, v50
	v_mov_b32_e32 v218, 0
	v_mov_b32_e32 v219, 0
	v_mov_b32_e32 v220, 0
	v_mov_b32_e32 v221, 0
	v_mov_b32_e32 v222, 0
	v_mov_b32_e32 v223, 0
	v_mov_b32_e32 v208, 0
	v_mov_b32_e32 v209, 0
	v_mov_b32_e32 v210, 0
	v_mov_b32_e32 v211, 0
	v_mov_b32_e32 v212, 0
	v_mov_b32_e32 v213, 0
	v_mov_b32_e32 v214, 0
	v_mov_b32_e32 v215, 0
	v_mov_b32_e32 v106, 0
	v_mov_b32_e32 v107, 0
	v_mov_b32_e32 v108, 0
	v_mov_b32_e32 v109, 0
	v_mov_b32_e32 v122, 0
	v_mov_b32_e32 v123, 0
	v_mov_b32_e32 v124, 0
	v_mov_b32_e32 v125, 0
	v_mov_b32_e32 v128, 0
	v_mov_b32_e32 v129, 0
	s_waitcnt lgkmcnt(0)
	s_barrier
	v_add_u32_e32 v183, v181, v170
	v_add3_u32 v216, v182, v173, v175
	ds_read_b128 v[184:187], v183
	ds_read_b128 v[188:191], v183 offset:32
	ds_read_b128 v[192:195], v183 offset:64
	ds_read_b128 v[196:199], v183 offset:96
	s_waitcnt lgkmcnt(3)
	v_mfma_f32_32x32x16_bf16 v[66:81], v[184:187], v[130:133], 0
	s_waitcnt lgkmcnt(2)
	v_mfma_f32_32x32x16_bf16 v[66:81], v[188:191], v[134:137], v[66:81]
	s_waitcnt lgkmcnt(1)
	v_mfma_f32_32x32x16_bf16 v[66:81], v[192:195], v[146:149], v[66:81]
	s_waitcnt lgkmcnt(0)
	v_mfma_f32_32x32x16_bf16 v[66:81], v[196:199], v[150:153], v[66:81]
	v_mfma_f32_32x32x16_bf16 v[82:97], v[184:187], v[154:157], 0
	v_mfma_f32_32x32x16_bf16 v[82:97], v[188:191], v[138:141], v[82:97]
	v_mfma_f32_32x32x16_bf16 v[82:97], v[192:195], v[142:145], v[82:97]
	v_mfma_f32_32x32x16_bf16 v[82:97], v[196:199], v[158:161], v[82:97]
	s_branch .Lat_enter

.Lat_enter:
	global_load_dwordx4 v[162:165], v[176:177], off
	global_load_dwordx4 v[166:169], v[176:177], off offset:256
	ds_read_b128 v[184:187], v183 offset:4608
	ds_read_b128 v[188:191], v183 offset:4640
	ds_read_b128 v[192:195], v183 offset:4672
	ds_read_b128 v[196:199], v183 offset:4704
	v_exp_f32_e32 v66, v66
	v_exp_f32_e32 v67, v67
	v_add_f32_e32 v222, v222, v128
	v_add_f32_e32 v223, v223, v129
	v_cvt_pk_bf16_f32 v125, v128, v129
	v_mfma_f32_32x32x16_bf16 v[50:65], v[208:211], v[106:109], v[50:65]
	v_exp_f32_e32 v68, v68
	v_exp_f32_e32 v69, v69
	v_add_f32_e32 v178, v178, v66
	v_add_f32_e32 v218, v218, v67
	v_cvt_pk_bf16_f32 v66, v66, v67
	v_mfma_f32_32x32x16_bf16 v[34:49], v[212:215], v[106:109], v[34:49]
	v_lshl_add_u64 v[176:177], v[176:177], 0, s[8:9]
	v_exp_f32_e32 v70, v70
	v_exp_f32_e32 v71, v71
	v_add_f32_e32 v219, v219, v68
	v_add_f32_e32 v220, v220, v69
	v_cvt_pk_bf16_f32 v67, v68, v69
	v_mfma_f32_32x32x16_bf16 v[18:33], v[208:211], v[122:125], v[18:33]
	v_exp_f32_e32 v72, v72
	v_exp_f32_e32 v73, v73
	v_add_f32_e32 v178, v178, v70
	v_add_f32_e32 v218, v218, v71
	v_cvt_pk_bf16_f32 v68, v70, v71
	v_mfma_f32_32x32x16_bf16 v[2:17], v[212:215], v[122:125], v[2:17]
	v_exp_f32_e32 v82, v82
	v_exp_f32_e32 v83, v83
	v_add_f32_e32 v219, v219, v72
	v_add_f32_e32 v220, v220, v73
	v_cvt_pk_bf16_f32 v69, v72, v73
	s_waitcnt lgkmcnt(0)
	v_mfma_f32_32x32x16_bf16 v[98:113], v[184:187], v[130:133], 0
	ds_read_b64_tr_b16 v[200:201], v216 offset:9216
	ds_read_b64_tr_b16 v[202:203], v216 offset:9792
	ds_read_b64_tr_b16 v[204:205], v216 offset:9280
	ds_read_b64_tr_b16 v[206:207], v216 offset:9856
	v_exp_f32_e32 v84, v84
	v_exp_f32_e32 v85, v85
	v_add_f32_e32 v179, v179, v82
	v_add_f32_e32 v221, v221, v83
	v_cvt_pk_bf16_f32 v82, v82, v83
	v_mfma_f32_32x32x16_bf16 v[98:113], v[188:191], v[134:137], v[98:113]
	ds_read_b64_tr_b16 v[208:209], v216 offset:11520
	ds_read_b64_tr_b16 v[210:211], v216 offset:12096
	ds_read_b64_tr_b16 v[212:213], v216 offset:11584
	ds_read_b64_tr_b16 v[214:215], v216 offset:12160
	v_exp_f32_e32 v86, v86
	v_exp_f32_e32 v87, v87
	v_add_f32_e32 v222, v222, v84
	v_add_f32_e32 v223, v223, v85
	v_cvt_pk_bf16_f32 v83, v84, v85
	v_mfma_f32_32x32x16_bf16 v[98:113], v[192:195], v[146:149], v[98:113]
	v_exp_f32_e32 v88, v88
	v_exp_f32_e32 v89, v89
	v_add_f32_e32 v179, v179, v86
	v_add_f32_e32 v221, v221, v87
	v_cvt_pk_bf16_f32 v84, v86, v87
	v_mfma_f32_32x32x16_bf16 v[98:113], v[196:199], v[150:153], v[98:113]
	v_exp_f32_e32 v74, v74
	v_exp_f32_e32 v75, v75
	v_add_f32_e32 v222, v222, v88
	v_add_f32_e32 v223, v223, v89
	v_cvt_pk_bf16_f32 v85, v88, v89
	v_mfma_f32_32x32x16_bf16 v[114:129], v[184:187], v[154:157], 0
	v_exp_f32_e32 v76, v76
	v_exp_f32_e32 v77, v77
	v_add_f32_e32 v178, v178, v74
	v_add_f32_e32 v218, v218, v75
	v_cvt_pk_bf16_f32 v74, v74, v75
	v_mfma_f32_32x32x16_bf16 v[114:129], v[188:191], v[138:141], v[114:129]
	v_exp_f32_e32 v78, v78
	v_exp_f32_e32 v79, v79
	v_add_f32_e32 v219, v219, v76
	v_add_f32_e32 v220, v220, v77
	v_cvt_pk_bf16_f32 v75, v76, v77
	v_mfma_f32_32x32x16_bf16 v[114:129], v[192:195], v[142:145], v[114:129]
	v_exp_f32_e32 v80, v80
	v_exp_f32_e32 v81, v81
	v_add_f32_e32 v178, v178, v78
	v_add_f32_e32 v218, v218, v79
	v_cvt_pk_bf16_f32 v76, v78, v79
	v_mfma_f32_32x32x16_bf16 v[114:129], v[196:199], v[158:161], v[114:129]
	v_exp_f32_e32 v90, v90
	v_exp_f32_e32 v91, v91
	v_add_f32_e32 v219, v219, v80
	v_add_f32_e32 v220, v220, v81
	v_cvt_pk_bf16_f32 v77, v80, v81
	s_waitcnt lgkmcnt(4)
	v_mfma_f32_32x32x16_bf16 v[50:65], v[200:203], v[66:69], v[50:65]
	ds_read_b128 v[184:187], v183 offset:18432
	ds_read_b128 v[188:191], v183 offset:18464
	ds_read_b128 v[192:195], v183 offset:18496
	ds_read_b128 v[196:199], v183 offset:18528
	v_exp_f32_e32 v92, v92
	v_exp_f32_e32 v93, v93
	v_add_f32_e32 v179, v179, v90
	v_add_f32_e32 v221, v221, v91
	v_cvt_pk_bf16_f32 v90, v90, v91
	v_mfma_f32_32x32x16_bf16 v[34:49], v[204:207], v[66:69], v[34:49]
	v_exp_f32_e32 v94, v94
	v_exp_f32_e32 v95, v95
	v_add_f32_e32 v222, v222, v92
	v_add_f32_e32 v223, v223, v93
	v_cvt_pk_bf16_f32 v91, v92, v93
	v_mfma_f32_32x32x16_bf16 v[18:33], v[200:203], v[82:85], v[18:33]
	v_exp_f32_e32 v96, v96
	v_exp_f32_e32 v97, v97
	v_add_f32_e32 v179, v179, v94
	v_add_f32_e32 v221, v221, v95
	v_cvt_pk_bf16_f32 v92, v94, v95
	v_mfma_f32_32x32x16_bf16 v[2:17], v[204:207], v[82:85], v[2:17]
	v_exp_f32_e32 v98, v98
	v_exp_f32_e32 v99, v99
	v_add_f32_e32 v222, v222, v96
	v_add_f32_e32 v223, v223, v97
	v_cvt_pk_bf16_f32 v93, v96, v97
	s_waitcnt lgkmcnt(4)
	v_mfma_f32_32x32x16_bf16 v[50:65], v[208:211], v[74:77], v[50:65]
	ds_read_b64_tr_b16 v[200:201], v216 offset:13824
	ds_read_b64_tr_b16 v[202:203], v216 offset:14400
	ds_read_b64_tr_b16 v[204:205], v216 offset:13888
	ds_read_b64_tr_b16 v[206:207], v216 offset:14464
	v_exp_f32_e32 v100, v100
	v_exp_f32_e32 v101, v101
	v_add_f32_e32 v178, v178, v98
	v_add_f32_e32 v218, v218, v99
	v_cvt_pk_bf16_f32 v98, v98, v99
	v_mfma_f32_32x32x16_bf16 v[34:49], v[212:215], v[74:77], v[34:49]
	v_exp_f32_e32 v102, v102
	v_exp_f32_e32 v103, v103
	v_add_f32_e32 v219, v219, v100
	v_add_f32_e32 v220, v220, v101
	v_cvt_pk_bf16_f32 v99, v100, v101
	v_mfma_f32_32x32x16_bf16 v[18:33], v[208:211], v[90:93], v[18:33]
	v_exp_f32_e32 v104, v104
	v_exp_f32_e32 v105, v105
	v_add_f32_e32 v178, v178, v102
	v_add_f32_e32 v218, v218, v103
	v_cvt_pk_bf16_f32 v100, v102, v103
	v_mfma_f32_32x32x16_bf16 v[2:17], v[212:215], v[90:93], v[2:17]
	v_exp_f32_e32 v114, v114
	v_exp_f32_e32 v115, v115
	v_add_f32_e32 v219, v219, v104
	v_add_f32_e32 v220, v220, v105
	v_cvt_pk_bf16_f32 v101, v104, v105
	s_waitcnt lgkmcnt(4)
	v_mfma_f32_32x32x16_bf16 v[66:81], v[184:187], v[130:133], 0
	ds_read_b64_tr_b16 v[208:209], v216 offset:16128
	ds_read_b64_tr_b16 v[210:211], v216 offset:16704
	ds_read_b64_tr_b16 v[212:213], v216 offset:16192
	ds_read_b64_tr_b16 v[214:215], v216 offset:16768
	v_exp_f32_e32 v116, v116
	v_exp_f32_e32 v117, v117
	v_add_f32_e32 v179, v179, v114
	v_add_f32_e32 v221, v221, v115
	v_cvt_pk_bf16_f32 v114, v114, v115
	v_mfma_f32_32x32x16_bf16 v[66:81], v[188:191], v[134:137], v[66:81]
	v_exp_f32_e32 v118, v118
	v_exp_f32_e32 v119, v119
	v_add_f32_e32 v222, v222, v116
	v_add_f32_e32 v223, v223, v117
	v_cvt_pk_bf16_f32 v115, v116, v117
	v_mfma_f32_32x32x16_bf16 v[66:81], v[192:195], v[146:149], v[66:81]
	v_exp_f32_e32 v120, v120
	v_exp_f32_e32 v121, v121
	v_add_f32_e32 v179, v179, v118
	v_add_f32_e32 v221, v221, v119
	v_cvt_pk_bf16_f32 v116, v118, v119
	v_mfma_f32_32x32x16_bf16 v[66:81], v[196:199], v[150:153], v[66:81]
	v_exp_f32_e32 v106, v106
	v_exp_f32_e32 v107, v107
	v_add_f32_e32 v222, v222, v120
	v_add_f32_e32 v223, v223, v121
	v_cvt_pk_bf16_f32 v117, v120, v121
	s_waitcnt lgkmcnt(4)
	v_mfma_f32_32x32x16_bf16 v[50:65], v[200:203], v[98:101], v[50:65]
	v_exp_f32_e32 v108, v108
	v_exp_f32_e32 v109, v109
	v_add_f32_e32 v178, v178, v106
	v_add_f32_e32 v218, v218, v107
	v_cvt_pk_bf16_f32 v106, v106, v107
	v_mfma_f32_32x32x16_bf16 v[34:49], v[204:207], v[98:101], v[34:49]
	v_exp_f32_e32 v110, v110
	v_exp_f32_e32 v111, v111
	v_add_f32_e32 v219, v219, v108
	v_add_f32_e32 v220, v220, v109
	v_cvt_pk_bf16_f32 v107, v108, v109
	v_mfma_f32_32x32x16_bf16 v[18:33], v[200:203], v[114:117], v[18:33]
	s_waitcnt vmcnt(0)
	ds_write_b128 v180, v[162:165] offset:36864
	ds_write_b128 v180, v[166:169] offset:46080
	v_exp_f32_e32 v112, v112
	v_exp_f32_e32 v113, v113
	v_add_f32_e32 v178, v178, v110
	v_add_f32_e32 v218, v218, v111
	v_cvt_pk_bf16_f32 v108, v110, v111
	v_mfma_f32_32x32x16_bf16 v[2:17], v[204:207], v[114:117], v[2:17]
	v_exp_f32_e32 v122, v122
	v_exp_f32_e32 v123, v123
	v_add_f32_e32 v219, v219, v112
	v_add_f32_e32 v220, v220, v113
	v_cvt_pk_bf16_f32 v109, v112, v113
	v_mfma_f32_32x32x16_bf16 v[82:97], v[184:187], v[154:157], 0
	v_exp_f32_e32 v124, v124
	v_exp_f32_e32 v125, v125
	v_add_f32_e32 v179, v179, v122
	v_add_f32_e32 v221, v221, v123
	v_cvt_pk_bf16_f32 v122, v122, v123
	v_mfma_f32_32x32x16_bf16 v[82:97], v[188:191], v[138:141], v[82:97]
	v_exp_f32_e32 v126, v126
	v_exp_f32_e32 v127, v127
	v_add_f32_e32 v222, v222, v124
	v_add_f32_e32 v223, v223, v125
	v_cvt_pk_bf16_f32 v123, v124, v125
	v_mfma_f32_32x32x16_bf16 v[82:97], v[192:195], v[142:145], v[82:97]
	v_exp_f32_e32 v128, v128
	v_exp_f32_e32 v129, v129
	v_add_f32_e32 v179, v179, v126
	v_add_f32_e32 v221, v221, v127
	v_cvt_pk_bf16_f32 v124, v126, v127
	v_mfma_f32_32x32x16_bf16 v[82:97], v[196:199], v[158:161], v[82:97]
	s_waitcnt lgkmcnt(0)
	s_barrier
	global_load_dwordx4 v[162:165], v[176:177], off
	global_load_dwordx4 v[166:169], v[176:177], off offset:256
	ds_read_b128 v[184:187], v183 offset:23040
	ds_read_b128 v[188:191], v183 offset:23072
	ds_read_b128 v[192:195], v183 offset:23104
	ds_read_b128 v[196:199], v183 offset:23136
	v_exp_f32_e32 v66, v66
	v_exp_f32_e32 v67, v67
	v_add_f32_e32 v222, v222, v128
	v_add_f32_e32 v223, v223, v129
	v_cvt_pk_bf16_f32 v125, v128, v129
	v_mfma_f32_32x32x16_bf16 v[50:65], v[208:211], v[106:109], v[50:65]
	v_exp_f32_e32 v68, v68
	v_exp_f32_e32 v69, v69
	v_add_f32_e32 v178, v178, v66
	v_add_f32_e32 v218, v218, v67
	v_cvt_pk_bf16_f32 v66, v66, v67
	v_mfma_f32_32x32x16_bf16 v[34:49], v[212:215], v[106:109], v[34:49]
	v_lshl_add_u64 v[176:177], v[176:177], 0, s[8:9]
	v_exp_f32_e32 v70, v70
	v_exp_f32_e32 v71, v71
	v_add_f32_e32 v219, v219, v68
	v_add_f32_e32 v220, v220, v69
	v_cvt_pk_bf16_f32 v67, v68, v69
	v_mfma_f32_32x32x16_bf16 v[18:33], v[208:211], v[122:125], v[18:33]
	v_exp_f32_e32 v72, v72
	v_exp_f32_e32 v73, v73
	v_add_f32_e32 v178, v178, v70
	v_add_f32_e32 v218, v218, v71
	v_cvt_pk_bf16_f32 v68, v70, v71
	v_mfma_f32_32x32x16_bf16 v[2:17], v[212:215], v[122:125], v[2:17]
	v_exp_f32_e32 v82, v82
	v_exp_f32_e32 v83, v83
	v_add_f32_e32 v219, v219, v72
	v_add_f32_e32 v220, v220, v73
	v_cvt_pk_bf16_f32 v69, v72, v73
	s_waitcnt lgkmcnt(0)
	v_mfma_f32_32x32x16_bf16 v[98:113], v[184:187], v[130:133], 0
	ds_read_b64_tr_b16 v[200:201], v216 offset:27648
	ds_read_b64_tr_b16 v[202:203], v216 offset:28224
	ds_read_b64_tr_b16 v[204:205], v216 offset:27712
	ds_read_b64_tr_b16 v[206:207], v216 offset:28288
	v_exp_f32_e32 v84, v84
	v_exp_f32_e32 v85, v85
	v_add_f32_e32 v179, v179, v82
	v_add_f32_e32 v221, v221, v83
	v_cvt_pk_bf16_f32 v82, v82, v83
	v_mfma_f32_32x32x16_bf16 v[98:113], v[188:191], v[134:137], v[98:113]
	ds_read_b64_tr_b16 v[208:209], v216 offset:29952
	ds_read_b64_tr_b16 v[210:211], v216 offset:30528
	ds_read_b64_tr_b16 v[212:213], v216 offset:30016
	ds_read_b64_tr_b16 v[214:215], v216 offset:30592
	v_exp_f32_e32 v86, v86
	v_exp_f32_e32 v87, v87
	v_add_f32_e32 v222, v222, v84
	v_add_f32_e32 v223, v223, v85
	v_cvt_pk_bf16_f32 v83, v84, v85
	v_mfma_f32_32x32x16_bf16 v[98:113], v[192:195], v[146:149], v[98:113]
	v_exp_f32_e32 v88, v88
	v_exp_f32_e32 v89, v89
	v_add_f32_e32 v179, v179, v86
	v_add_f32_e32 v221, v221, v87
	v_cvt_pk_bf16_f32 v84, v86, v87
	v_mfma_f32_32x32x16_bf16 v[98:113], v[196:199], v[150:153], v[98:113]
	v_exp_f32_e32 v74, v74
	v_exp_f32_e32 v75, v75
	v_add_f32_e32 v222, v222, v88
	v_add_f32_e32 v223, v223, v89
	v_cvt_pk_bf16_f32 v85, v88, v89
	v_mfma_f32_32x32x16_bf16 v[114:129], v[184:187], v[154:157], 0
	v_exp_f32_e32 v76, v76
	v_exp_f32_e32 v77, v77
	v_add_f32_e32 v178, v178, v74
	v_add_f32_e32 v218, v218, v75
	v_cvt_pk_bf16_f32 v74, v74, v75
	v_mfma_f32_32x32x16_bf16 v[114:129], v[188:191], v[138:141], v[114:129]
	v_exp_f32_e32 v78, v78
	v_exp_f32_e32 v79, v79
	v_add_f32_e32 v219, v219, v76
	v_add_f32_e32 v220, v220, v77
	v_cvt_pk_bf16_f32 v75, v76, v77
	v_mfma_f32_32x32x16_bf16 v[114:129], v[192:195], v[142:145], v[114:129]
	v_exp_f32_e32 v80, v80
	v_exp_f32_e32 v81, v81
	v_add_f32_e32 v178, v178, v78
	v_add_f32_e32 v218, v218, v79
	v_cvt_pk_bf16_f32 v76, v78, v79
	v_mfma_f32_32x32x16_bf16 v[114:129], v[196:199], v[158:161], v[114:129]
	v_exp_f32_e32 v90, v90
	v_exp_f32_e32 v91, v91
	v_add_f32_e32 v219, v219, v80
	v_add_f32_e32 v220, v220, v81
	v_cvt_pk_bf16_f32 v77, v80, v81
	s_waitcnt lgkmcnt(4)
	v_mfma_f32_32x32x16_bf16 v[50:65], v[200:203], v[66:69], v[50:65]
	ds_read_b128 v[184:187], v183 offset:36864
	ds_read_b128 v[188:191], v183 offset:36896
	ds_read_b128 v[192:195], v183 offset:36928
	ds_read_b128 v[196:199], v183 offset:36960
	v_exp_f32_e32 v92, v92
	v_exp_f32_e32 v93, v93
	v_add_f32_e32 v179, v179, v90
	v_add_f32_e32 v221, v221, v91
	v_cvt_pk_bf16_f32 v90, v90, v91
	v_mfma_f32_32x32x16_bf16 v[34:49], v[204:207], v[66:69], v[34:49]
	v_exp_f32_e32 v94, v94
	v_exp_f32_e32 v95, v95
	v_add_f32_e32 v222, v222, v92
	v_add_f32_e32 v223, v223, v93
	v_cvt_pk_bf16_f32 v91, v92, v93
	v_mfma_f32_32x32x16_bf16 v[18:33], v[200:203], v[82:85], v[18:33]
	v_exp_f32_e32 v96, v96
	v_exp_f32_e32 v97, v97
	v_add_f32_e32 v179, v179, v94
	v_add_f32_e32 v221, v221, v95
	v_cvt_pk_bf16_f32 v92, v94, v95
	v_mfma_f32_32x32x16_bf16 v[2:17], v[204:207], v[82:85], v[2:17]
	v_exp_f32_e32 v98, v98
	v_exp_f32_e32 v99, v99
	v_add_f32_e32 v222, v222, v96
	v_add_f32_e32 v223, v223, v97
	v_cvt_pk_bf16_f32 v93, v96, v97
	s_waitcnt lgkmcnt(4)
	v_mfma_f32_32x32x16_bf16 v[50:65], v[208:211], v[74:77], v[50:65]
	ds_read_b64_tr_b16 v[200:201], v216 offset:32256
	ds_read_b64_tr_b16 v[202:203], v216 offset:32832
	ds_read_b64_tr_b16 v[204:205], v216 offset:32320
	ds_read_b64_tr_b16 v[206:207], v216 offset:32896
	v_exp_f32_e32 v100, v100
	v_exp_f32_e32 v101, v101
	v_add_f32_e32 v178, v178, v98
	v_add_f32_e32 v218, v218, v99
	v_cvt_pk_bf16_f32 v98, v98, v99
	v_mfma_f32_32x32x16_bf16 v[34:49], v[212:215], v[74:77], v[34:49]
	v_exp_f32_e32 v102, v102
	v_exp_f32_e32 v103, v103
	v_add_f32_e32 v219, v219, v100
	v_add_f32_e32 v220, v220, v101
	v_cvt_pk_bf16_f32 v99, v100, v101
	v_mfma_f32_32x32x16_bf16 v[18:33], v[208:211], v[90:93], v[18:33]
	v_exp_f32_e32 v104, v104
	v_exp_f32_e32 v105, v105
	v_add_f32_e32 v178, v178, v102
	v_add_f32_e32 v218, v218, v103
	v_cvt_pk_bf16_f32 v100, v102, v103
	v_mfma_f32_32x32x16_bf16 v[2:17], v[212:215], v[90:93], v[2:17]
	v_exp_f32_e32 v114, v114
	v_exp_f32_e32 v115, v115
	v_add_f32_e32 v219, v219, v104
	v_add_f32_e32 v220, v220, v105
	v_cvt_pk_bf16_f32 v101, v104, v105
	s_waitcnt lgkmcnt(4)
	v_mfma_f32_32x32x16_bf16 v[66:81], v[184:187], v[130:133], 0
	ds_read_b64_tr_b16 v[208:209], v216 offset:34560
	ds_read_b64_tr_b16 v[210:211], v216 offset:35136
	ds_read_b64_tr_b16 v[212:213], v216 offset:34624
	ds_read_b64_tr_b16 v[214:215], v216 offset:35200
	v_exp_f32_e32 v116, v116
	v_exp_f32_e32 v117, v117
	v_add_f32_e32 v179, v179, v114
	v_add_f32_e32 v221, v221, v115
	v_cvt_pk_bf16_f32 v114, v114, v115
	v_mfma_f32_32x32x16_bf16 v[66:81], v[188:191], v[134:137], v[66:81]
	v_exp_f32_e32 v118, v118
	v_exp_f32_e32 v119, v119
	v_add_f32_e32 v222, v222, v116
	v_add_f32_e32 v223, v223, v117
	v_cvt_pk_bf16_f32 v115, v116, v117
	v_mfma_f32_32x32x16_bf16 v[66:81], v[192:195], v[146:149], v[66:81]
	v_exp_f32_e32 v120, v120
	v_exp_f32_e32 v121, v121
	v_add_f32_e32 v179, v179, v118
	v_add_f32_e32 v221, v221, v119
	v_cvt_pk_bf16_f32 v116, v118, v119
	v_mfma_f32_32x32x16_bf16 v[66:81], v[196:199], v[150:153], v[66:81]
	v_exp_f32_e32 v106, v106
	v_exp_f32_e32 v107, v107
	v_add_f32_e32 v222, v222, v120
	v_add_f32_e32 v223, v223, v121
	v_cvt_pk_bf16_f32 v117, v120, v121
	s_waitcnt lgkmcnt(4)
	v_mfma_f32_32x32x16_bf16 v[50:65], v[200:203], v[98:101], v[50:65]
	v_exp_f32_e32 v108, v108
	v_exp_f32_e32 v109, v109
	v_add_f32_e32 v178, v178, v106
	v_add_f32_e32 v218, v218, v107
	v_cvt_pk_bf16_f32 v106, v106, v107
	v_mfma_f32_32x32x16_bf16 v[34:49], v[204:207], v[98:101], v[34:49]
	v_exp_f32_e32 v110, v110
	v_exp_f32_e32 v111, v111
	v_add_f32_e32 v219, v219, v108
	v_add_f32_e32 v220, v220, v109
	v_cvt_pk_bf16_f32 v107, v108, v109
	v_mfma_f32_32x32x16_bf16 v[18:33], v[200:203], v[114:117], v[18:33]
	s_waitcnt vmcnt(0)
	ds_write_b128 v180, v[162:165]
	ds_write_b128 v180, v[166:169] offset:9216
	v_exp_f32_e32 v112, v112
	v_exp_f32_e32 v113, v113
	v_add_f32_e32 v178, v178, v110
	v_add_f32_e32 v218, v218, v111
	v_cvt_pk_bf16_f32 v108, v110, v111
	v_mfma_f32_32x32x16_bf16 v[2:17], v[204:207], v[114:117], v[2:17]
	v_exp_f32_e32 v122, v122
	v_exp_f32_e32 v123, v123
	v_add_f32_e32 v219, v219, v112
	v_add_f32_e32 v220, v220, v113
	v_cvt_pk_bf16_f32 v109, v112, v113
	v_mfma_f32_32x32x16_bf16 v[82:97], v[184:187], v[154:157], 0
	v_exp_f32_e32 v124, v124
	v_exp_f32_e32 v125, v125
	v_add_f32_e32 v179, v179, v122
	v_add_f32_e32 v221, v221, v123
	v_cvt_pk_bf16_f32 v122, v122, v123
	v_mfma_f32_32x32x16_bf16 v[82:97], v[188:191], v[138:141], v[82:97]
	v_exp_f32_e32 v126, v126
	v_exp_f32_e32 v127, v127
	v_add_f32_e32 v222, v222, v124
	v_add_f32_e32 v223, v223, v125
	v_cvt_pk_bf16_f32 v123, v124, v125
	v_mfma_f32_32x32x16_bf16 v[82:97], v[192:195], v[142:145], v[82:97]
	v_exp_f32_e32 v128, v128
	v_exp_f32_e32 v129, v129
	v_add_f32_e32 v179, v179, v126
	v_add_f32_e32 v221, v221, v127
	v_cvt_pk_bf16_f32 v124, v126, v127
	v_mfma_f32_32x32x16_bf16 v[82:97], v[196:199], v[158:161], v[82:97]
	s_waitcnt lgkmcnt(0)
	s_barrier
	global_load_dwordx4 v[162:165], v[176:177], off
	global_load_dwordx4 v[166:169], v[176:177], off offset:256
	ds_read_b128 v[184:187], v183 offset:41472
	ds_read_b128 v[188:191], v183 offset:41504
	ds_read_b128 v[192:195], v183 offset:41536
	ds_read_b128 v[196:199], v183 offset:41568
	v_exp_f32_e32 v66, v66
	v_exp_f32_e32 v67, v67
	v_add_f32_e32 v222, v222, v128
	v_add_f32_e32 v223, v223, v129
	v_cvt_pk_bf16_f32 v125, v128, v129
	v_mfma_f32_32x32x16_bf16 v[50:65], v[208:211], v[106:109], v[50:65]
	v_exp_f32_e32 v68, v68
	v_exp_f32_e32 v69, v69
	v_add_f32_e32 v178, v178, v66
	v_add_f32_e32 v218, v218, v67
	v_cvt_pk_bf16_f32 v66, v66, v67
	v_mfma_f32_32x32x16_bf16 v[34:49], v[212:215], v[106:109], v[34:49]
	v_lshl_add_u64 v[176:177], v[176:177], 0, s[8:9]
	v_exp_f32_e32 v70, v70
	v_exp_f32_e32 v71, v71
	v_add_f32_e32 v219, v219, v68
	v_add_f32_e32 v220, v220, v69
	v_cvt_pk_bf16_f32 v67, v68, v69
	v_mfma_f32_32x32x16_bf16 v[18:33], v[208:211], v[122:125], v[18:33]
	v_exp_f32_e32 v72, v72
	v_exp_f32_e32 v73, v73
	v_add_f32_e32 v178, v178, v70
	v_add_f32_e32 v218, v218, v71
	v_cvt_pk_bf16_f32 v68, v70, v71
	v_mfma_f32_32x32x16_bf16 v[2:17], v[212:215], v[122:125], v[2:17]
	v_exp_f32_e32 v82, v82
	v_exp_f32_e32 v83, v83
	v_add_f32_e32 v219, v219, v72
	v_add_f32_e32 v220, v220, v73
	v_cvt_pk_bf16_f32 v69, v72, v73
	s_waitcnt lgkmcnt(0)
	v_mfma_f32_32x32x16_bf16 v[98:113], v[184:187], v[130:133], 0
	ds_read_b64_tr_b16 v[200:201], v216 offset:46080
	ds_read_b64_tr_b16 v[202:203], v216 offset:46656
	ds_read_b64_tr_b16 v[204:205], v216 offset:46144
	ds_read_b64_tr_b16 v[206:207], v216 offset:46720
	v_exp_f32_e32 v84, v84
	v_exp_f32_e32 v85, v85
	v_add_f32_e32 v179, v179, v82
	v_add_f32_e32 v221, v221, v83
	v_cvt_pk_bf16_f32 v82, v82, v83
	v_mfma_f32_32x32x16_bf16 v[98:113], v[188:191], v[134:137], v[98:113]
	ds_read_b64_tr_b16 v[208:209], v216 offset:48384
	ds_read_b64_tr_b16 v[210:211], v216 offset:48960
	ds_read_b64_tr_b16 v[212:213], v216 offset:48448
	ds_read_b64_tr_b16 v[214:215], v216 offset:49024
	v_exp_f32_e32 v86, v86
	v_exp_f32_e32 v87, v87
	v_add_f32_e32 v222, v222, v84
	v_add_f32_e32 v223, v223, v85
	v_cvt_pk_bf16_f32 v83, v84, v85
	v_mfma_f32_32x32x16_bf16 v[98:113], v[192:195], v[146:149], v[98:113]
	v_exp_f32_e32 v88, v88
	v_exp_f32_e32 v89, v89
	v_add_f32_e32 v179, v179, v86
	v_add_f32_e32 v221, v221, v87
	v_cvt_pk_bf16_f32 v84, v86, v87
	v_mfma_f32_32x32x16_bf16 v[98:113], v[196:199], v[150:153], v[98:113]
	v_exp_f32_e32 v74, v74
	v_exp_f32_e32 v75, v75
	v_add_f32_e32 v222, v222, v88
	v_add_f32_e32 v223, v223, v89
	v_cvt_pk_bf16_f32 v85, v88, v89
	v_mfma_f32_32x32x16_bf16 v[114:129], v[184:187], v[154:157], 0
	v_exp_f32_e32 v76, v76
	v_exp_f32_e32 v77, v77
	v_add_f32_e32 v178, v178, v74
	v_add_f32_e32 v218, v218, v75
	v_cvt_pk_bf16_f32 v74, v74, v75
	v_mfma_f32_32x32x16_bf16 v[114:129], v[188:191], v[138:141], v[114:129]
	v_exp_f32_e32 v78, v78
	v_exp_f32_e32 v79, v79
	v_add_f32_e32 v219, v219, v76
	v_add_f32_e32 v220, v220, v77
	v_cvt_pk_bf16_f32 v75, v76, v77
	v_mfma_f32_32x32x16_bf16 v[114:129], v[192:195], v[142:145], v[114:129]
	v_exp_f32_e32 v80, v80
	v_exp_f32_e32 v81, v81
	v_add_f32_e32 v178, v178, v78
	v_add_f32_e32 v218, v218, v79
	v_cvt_pk_bf16_f32 v76, v78, v79
	v_mfma_f32_32x32x16_bf16 v[114:129], v[196:199], v[158:161], v[114:129]
	v_exp_f32_e32 v90, v90
	v_exp_f32_e32 v91, v91
	v_add_f32_e32 v219, v219, v80
	v_add_f32_e32 v220, v220, v81
	v_cvt_pk_bf16_f32 v77, v80, v81
	s_waitcnt lgkmcnt(4)
	v_mfma_f32_32x32x16_bf16 v[50:65], v[200:203], v[66:69], v[50:65]
	ds_read_b128 v[184:187], v183
	ds_read_b128 v[188:191], v183 offset:32
	ds_read_b128 v[192:195], v183 offset:64
	ds_read_b128 v[196:199], v183 offset:96
	v_exp_f32_e32 v92, v92
	v_exp_f32_e32 v93, v93
	v_add_f32_e32 v179, v179, v90
	v_add_f32_e32 v221, v221, v91
	v_cvt_pk_bf16_f32 v90, v90, v91
	v_mfma_f32_32x32x16_bf16 v[34:49], v[204:207], v[66:69], v[34:49]
	v_exp_f32_e32 v94, v94
	v_exp_f32_e32 v95, v95
	v_add_f32_e32 v222, v222, v92
	v_add_f32_e32 v223, v223, v93
	v_cvt_pk_bf16_f32 v91, v92, v93
	v_mfma_f32_32x32x16_bf16 v[18:33], v[200:203], v[82:85], v[18:33]
	v_exp_f32_e32 v96, v96
	v_exp_f32_e32 v97, v97
	v_add_f32_e32 v179, v179, v94
	v_add_f32_e32 v221, v221, v95
	v_cvt_pk_bf16_f32 v92, v94, v95
	v_mfma_f32_32x32x16_bf16 v[2:17], v[204:207], v[82:85], v[2:17]
	v_exp_f32_e32 v98, v98
	v_exp_f32_e32 v99, v99
	v_add_f32_e32 v222, v222, v96
	v_add_f32_e32 v223, v223, v97
	v_cvt_pk_bf16_f32 v93, v96, v97
	s_waitcnt lgkmcnt(4)
	v_mfma_f32_32x32x16_bf16 v[50:65], v[208:211], v[74:77], v[50:65]
	ds_read_b64_tr_b16 v[200:201], v216 offset:50688
	ds_read_b64_tr_b16 v[202:203], v216 offset:51264
	ds_read_b64_tr_b16 v[204:205], v216 offset:50752
	ds_read_b64_tr_b16 v[206:207], v216 offset:51328
	v_exp_f32_e32 v100, v100
	v_exp_f32_e32 v101, v101
	v_add_f32_e32 v178, v178, v98
	v_add_f32_e32 v218, v218, v99
	v_cvt_pk_bf16_f32 v98, v98, v99
	v_mfma_f32_32x32x16_bf16 v[34:49], v[212:215], v[74:77], v[34:49]
	v_exp_f32_e32 v102, v102
	v_exp_f32_e32 v103, v103
	v_add_f32_e32 v219, v219, v100
	v_add_f32_e32 v220, v220, v101
	v_cvt_pk_bf16_f32 v99, v100, v101
	v_mfma_f32_32x32x16_bf16 v[18:33], v[208:211], v[90:93], v[18:33]
	v_exp_f32_e32 v104, v104
	v_exp_f32_e32 v105, v105
	v_add_f32_e32 v178, v178, v102
	v_add_f32_e32 v218, v218, v103
	v_cvt_pk_bf16_f32 v100, v102, v103
	v_mfma_f32_32x32x16_bf16 v[2:17], v[212:215], v[90:93], v[2:17]
	v_exp_f32_e32 v114, v114
	v_exp_f32_e32 v115, v115
	v_add_f32_e32 v219, v219, v104
	v_add_f32_e32 v220, v220, v105
	v_cvt_pk_bf16_f32 v101, v104, v105
	s_waitcnt lgkmcnt(4)
	v_mfma_f32_32x32x16_bf16 v[66:81], v[184:187], v[130:133], 0
	ds_read_b64_tr_b16 v[208:209], v216 offset:52992
	ds_read_b64_tr_b16 v[210:211], v216 offset:53568
	ds_read_b64_tr_b16 v[212:213], v216 offset:53056
	ds_read_b64_tr_b16 v[214:215], v216 offset:53632
	v_exp_f32_e32 v116, v116
	v_exp_f32_e32 v117, v117
	v_add_f32_e32 v179, v179, v114
	v_add_f32_e32 v221, v221, v115
	v_cvt_pk_bf16_f32 v114, v114, v115
	v_mfma_f32_32x32x16_bf16 v[66:81], v[188:191], v[134:137], v[66:81]
	v_exp_f32_e32 v118, v118
	v_exp_f32_e32 v119, v119
	v_add_f32_e32 v222, v222, v116
	v_add_f32_e32 v223, v223, v117
	v_cvt_pk_bf16_f32 v115, v116, v117
	v_mfma_f32_32x32x16_bf16 v[66:81], v[192:195], v[146:149], v[66:81]
	v_exp_f32_e32 v120, v120
	v_exp_f32_e32 v121, v121
	v_add_f32_e32 v179, v179, v118
	v_add_f32_e32 v221, v221, v119
	v_cvt_pk_bf16_f32 v116, v118, v119
	v_mfma_f32_32x32x16_bf16 v[66:81], v[196:199], v[150:153], v[66:81]
	v_exp_f32_e32 v106, v106
	v_exp_f32_e32 v107, v107
	v_add_f32_e32 v222, v222, v120
	v_add_f32_e32 v223, v223, v121
	v_cvt_pk_bf16_f32 v117, v120, v121
	s_waitcnt lgkmcnt(4)
	v_mfma_f32_32x32x16_bf16 v[50:65], v[200:203], v[98:101], v[50:65]
	v_exp_f32_e32 v108, v108
	v_exp_f32_e32 v109, v109
	v_add_f32_e32 v178, v178, v106
	v_add_f32_e32 v218, v218, v107
	v_cvt_pk_bf16_f32 v106, v106, v107
	v_mfma_f32_32x32x16_bf16 v[34:49], v[204:207], v[98:101], v[34:49]
	v_exp_f32_e32 v110, v110
	v_exp_f32_e32 v111, v111
	v_add_f32_e32 v219, v219, v108
	v_add_f32_e32 v220, v220, v109
	v_cvt_pk_bf16_f32 v107, v108, v109
	v_mfma_f32_32x32x16_bf16 v[18:33], v[200:203], v[114:117], v[18:33]
	s_waitcnt vmcnt(0)
	ds_write_b128 v180, v[162:165] offset:18432
	ds_write_b128 v180, v[166:169] offset:27648
	v_exp_f32_e32 v112, v112
	v_exp_f32_e32 v113, v113
	v_add_f32_e32 v178, v178, v110
	v_add_f32_e32 v218, v218, v111
	v_cvt_pk_bf16_f32 v108, v110, v111
	v_mfma_f32_32x32x16_bf16 v[2:17], v[204:207], v[114:117], v[2:17]
	v_exp_f32_e32 v122, v122
	v_exp_f32_e32 v123, v123
	v_add_f32_e32 v219, v219, v112
	v_add_f32_e32 v220, v220, v113
	v_cvt_pk_bf16_f32 v109, v112, v113
	v_mfma_f32_32x32x16_bf16 v[82:97], v[184:187], v[154:157], 0
	v_exp_f32_e32 v124, v124
	v_exp_f32_e32 v125, v125
	v_add_f32_e32 v179, v179, v122
	v_add_f32_e32 v221, v221, v123
	v_cvt_pk_bf16_f32 v122, v122, v123
	v_mfma_f32_32x32x16_bf16 v[82:97], v[188:191], v[138:141], v[82:97]
	v_exp_f32_e32 v126, v126
	v_exp_f32_e32 v127, v127
	v_add_f32_e32 v222, v222, v124
	v_add_f32_e32 v223, v223, v125
	v_cvt_pk_bf16_f32 v123, v124, v125
	v_mfma_f32_32x32x16_bf16 v[82:97], v[192:195], v[142:145], v[82:97]
	v_exp_f32_e32 v128, v128
	v_exp_f32_e32 v129, v129
	v_add_f32_e32 v179, v179, v126
	v_add_f32_e32 v221, v221, v127
	v_cvt_pk_bf16_f32 v124, v126, v127
	v_mfma_f32_32x32x16_bf16 v[82:97], v[196:199], v[158:161], v[82:97]
	s_add_i32 s30, s30, 1
	s_cmpk_lt_u32 s30, 84
	s_cbranch_scc1 .Lat_loop
	s_waitcnt lgkmcnt(0)
	s_barrier
	global_load_dwordx4 v[162:165], v[176:177], off
	global_load_dwordx4 v[166:169], v[176:177], off offset:256
	ds_read_b128 v[184:187], v183 offset:4608
	ds_read_b128 v[188:191], v183 offset:4640
	ds_read_b128 v[192:195], v183 offset:4672
	ds_read_b128 v[196:199], v183 offset:4704
	v_exp_f32_e32 v66, v66
	v_exp_f32_e32 v67, v67
	v_add_f32_e32 v222, v222, v128
	v_add_f32_e32 v223, v223, v129
	v_cvt_pk_bf16_f32 v125, v128, v129
	v_mfma_f32_32x32x16_bf16 v[50:65], v[208:211], v[106:109], v[50:65]
	v_exp_f32_e32 v68, v68
	v_exp_f32_e32 v69, v69
	v_add_f32_e32 v178, v178, v66
	v_add_f32_e32 v218, v218, v67
	v_cvt_pk_bf16_f32 v66, v66, v67
	v_mfma_f32_32x32x16_bf16 v[34:49], v[212:215], v[106:109], v[34:49]
	v_lshl_add_u64 v[176:177], v[176:177], 0, s[8:9]
	v_exp_f32_e32 v70, v70
	v_exp_f32_e32 v71, v71
	v_add_f32_e32 v219, v219, v68
	v_add_f32_e32 v220, v220, v69
	v_cvt_pk_bf16_f32 v67, v68, v69
	v_mfma_f32_32x32x16_bf16 v[18:33], v[208:211], v[122:125], v[18:33]
	v_exp_f32_e32 v72, v72
	v_exp_f32_e32 v73, v73
	v_add_f32_e32 v178, v178, v70
	v_add_f32_e32 v218, v218, v71
	v_cvt_pk_bf16_f32 v68, v70, v71
	v_mfma_f32_32x32x16_bf16 v[2:17], v[212:215], v[122:125], v[2:17]
	v_exp_f32_e32 v82, v82
	v_exp_f32_e32 v83, v83
	v_add_f32_e32 v219, v219, v72
	v_add_f32_e32 v220, v220, v73
	v_cvt_pk_bf16_f32 v69, v72, v73
	s_waitcnt lgkmcnt(0)
	v_mfma_f32_32x32x16_bf16 v[98:113], v[184:187], v[130:133], 0
	ds_read_b64_tr_b16 v[200:201], v216 offset:9216
	ds_read_b64_tr_b16 v[202:203], v216 offset:9792
	ds_read_b64_tr_b16 v[204:205], v216 offset:9280
	ds_read_b64_tr_b16 v[206:207], v216 offset:9856
	v_exp_f32_e32 v84, v84
	v_exp_f32_e32 v85, v85
	v_add_f32_e32 v179, v179, v82
	v_add_f32_e32 v221, v221, v83
	v_cvt_pk_bf16_f32 v82, v82, v83
	v_mfma_f32_32x32x16_bf16 v[98:113], v[188:191], v[134:137], v[98:113]
	ds_read_b64_tr_b16 v[208:209], v216 offset:11520
	ds_read_b64_tr_b16 v[210:211], v216 offset:12096
	ds_read_b64_tr_b16 v[212:213], v216 offset:11584
	ds_read_b64_tr_b16 v[214:215], v216 offset:12160
	v_exp_f32_e32 v86, v86
	v_exp_f32_e32 v87, v87
	v_add_f32_e32 v222, v222, v84
	v_add_f32_e32 v223, v223, v85
	v_cvt_pk_bf16_f32 v83, v84, v85
	v_mfma_f32_32x32x16_bf16 v[98:113], v[192:195], v[146:149], v[98:113]
	v_exp_f32_e32 v88, v88
	v_exp_f32_e32 v89, v89
	v_add_f32_e32 v179, v179, v86
	v_add_f32_e32 v221, v221, v87
	v_cvt_pk_bf16_f32 v84, v86, v87
	v_mfma_f32_32x32x16_bf16 v[98:113], v[196:199], v[150:153], v[98:113]
	v_exp_f32_e32 v74, v74
	v_exp_f32_e32 v75, v75
	v_add_f32_e32 v222, v222, v88
	v_add_f32_e32 v223, v223, v89
	v_cvt_pk_bf16_f32 v85, v88, v89
	v_mfma_f32_32x32x16_bf16 v[114:129], v[184:187], v[154:157], 0
	v_exp_f32_e32 v76, v76
	v_exp_f32_e32 v77, v77
	v_add_f32_e32 v178, v178, v74
	v_add_f32_e32 v218, v218, v75
	v_cvt_pk_bf16_f32 v74, v74, v75
	v_mfma_f32_32x32x16_bf16 v[114:129], v[188:191], v[138:141], v[114:129]
	v_exp_f32_e32 v78, v78
	v_exp_f32_e32 v79, v79
	v_add_f32_e32 v219, v219, v76
	v_add_f32_e32 v220, v220, v77
	v_cvt_pk_bf16_f32 v75, v76, v77
	v_mfma_f32_32x32x16_bf16 v[114:129], v[192:195], v[142:145], v[114:129]
	v_exp_f32_e32 v80, v80
	v_exp_f32_e32 v81, v81
	v_add_f32_e32 v178, v178, v78
	v_add_f32_e32 v218, v218, v79
	v_cvt_pk_bf16_f32 v76, v78, v79
	v_mfma_f32_32x32x16_bf16 v[114:129], v[196:199], v[158:161], v[114:129]
	v_exp_f32_e32 v90, v90
	v_exp_f32_e32 v91, v91
	v_add_f32_e32 v219, v219, v80
	v_add_f32_e32 v220, v220, v81
	v_cvt_pk_bf16_f32 v77, v80, v81
	s_waitcnt lgkmcnt(4)
	v_mfma_f32_32x32x16_bf16 v[50:65], v[200:203], v[66:69], v[50:65]
	ds_read_b128 v[184:187], v183 offset:18432
	ds_read_b128 v[188:191], v183 offset:18464
	ds_read_b128 v[192:195], v183 offset:18496
	ds_read_b128 v[196:199], v183 offset:18528
	v_exp_f32_e32 v92, v92
	v_exp_f32_e32 v93, v93
	v_add_f32_e32 v179, v179, v90
	v_add_f32_e32 v221, v221, v91
	v_cvt_pk_bf16_f32 v90, v90, v91
	v_mfma_f32_32x32x16_bf16 v[34:49], v[204:207], v[66:69], v[34:49]
	v_exp_f32_e32 v94, v94
	v_exp_f32_e32 v95, v95
	v_add_f32_e32 v222, v222, v92
	v_add_f32_e32 v223, v223, v93
	v_cvt_pk_bf16_f32 v91, v92, v93
	v_mfma_f32_32x32x16_bf16 v[18:33], v[200:203], v[82:85], v[18:33]
	v_exp_f32_e32 v96, v96
	v_exp_f32_e32 v97, v97
	v_add_f32_e32 v179, v179, v94
	v_add_f32_e32 v221, v221, v95
	v_cvt_pk_bf16_f32 v92, v94, v95
	v_mfma_f32_32x32x16_bf16 v[2:17], v[204:207], v[82:85], v[2:17]
	v_exp_f32_e32 v98, v98
	v_exp_f32_e32 v99, v99
	v_add_f32_e32 v222, v222, v96
	v_add_f32_e32 v223, v223, v97
	v_cvt_pk_bf16_f32 v93, v96, v97
	s_waitcnt lgkmcnt(4)
	v_mfma_f32_32x32x16_bf16 v[50:65], v[208:211], v[74:77], v[50:65]
	ds_read_b64_tr_b16 v[200:201], v216 offset:13824
	ds_read_b64_tr_b16 v[202:203], v216 offset:14400
	ds_read_b64_tr_b16 v[204:205], v216 offset:13888
	ds_read_b64_tr_b16 v[206:207], v216 offset:14464
	v_exp_f32_e32 v100, v100
	v_exp_f32_e32 v101, v101
	v_add_f32_e32 v178, v178, v98
	v_add_f32_e32 v218, v218, v99
	v_cvt_pk_bf16_f32 v98, v98, v99
	v_mfma_f32_32x32x16_bf16 v[34:49], v[212:215], v[74:77], v[34:49]
	v_exp_f32_e32 v102, v102
	v_exp_f32_e32 v103, v103
	v_add_f32_e32 v219, v219, v100
	v_add_f32_e32 v220, v220, v101
	v_cvt_pk_bf16_f32 v99, v100, v101
	v_mfma_f32_32x32x16_bf16 v[18:33], v[208:211], v[90:93], v[18:33]
	v_exp_f32_e32 v104, v104
	v_exp_f32_e32 v105, v105
	v_add_f32_e32 v178, v178, v102
	v_add_f32_e32 v218, v218, v103
	v_cvt_pk_bf16_f32 v100, v102, v103
	v_mfma_f32_32x32x16_bf16 v[2:17], v[212:215], v[90:93], v[2:17]
	v_exp_f32_e32 v114, v114
	v_exp_f32_e32 v115, v115
	v_add_f32_e32 v219, v219, v104
	v_add_f32_e32 v220, v220, v105
	v_cvt_pk_bf16_f32 v101, v104, v105
	s_waitcnt lgkmcnt(4)
	v_mfma_f32_32x32x16_bf16 v[66:81], v[184:187], v[130:133], 0
	ds_read_b64_tr_b16 v[208:209], v216 offset:16128
	ds_read_b64_tr_b16 v[210:211], v216 offset:16704
	ds_read_b64_tr_b16 v[212:213], v216 offset:16192
	ds_read_b64_tr_b16 v[214:215], v216 offset:16768
	v_exp_f32_e32 v116, v116
	v_exp_f32_e32 v117, v117
	v_add_f32_e32 v179, v179, v114
	v_add_f32_e32 v221, v221, v115
	v_cvt_pk_bf16_f32 v114, v114, v115
	v_mfma_f32_32x32x16_bf16 v[66:81], v[188:191], v[134:137], v[66:81]
	v_exp_f32_e32 v118, v118
	v_exp_f32_e32 v119, v119
	v_add_f32_e32 v222, v222, v116
	v_add_f32_e32 v223, v223, v117
	v_cvt_pk_bf16_f32 v115, v116, v117
	v_mfma_f32_32x32x16_bf16 v[66:81], v[192:195], v[146:149], v[66:81]
	v_exp_f32_e32 v120, v120
	v_exp_f32_e32 v121, v121
	v_add_f32_e32 v179, v179, v118
	v_add_f32_e32 v221, v221, v119
	v_cvt_pk_bf16_f32 v116, v118, v119
	v_mfma_f32_32x32x16_bf16 v[66:81], v[196:199], v[150:153], v[66:81]
	v_exp_f32_e32 v106, v106
	v_exp_f32_e32 v107, v107
	v_add_f32_e32 v222, v222, v120
	v_add_f32_e32 v223, v223, v121
	v_cvt_pk_bf16_f32 v117, v120, v121
	s_waitcnt lgkmcnt(4)
	v_mfma_f32_32x32x16_bf16 v[50:65], v[200:203], v[98:101], v[50:65]
	v_exp_f32_e32 v108, v108
	v_exp_f32_e32 v109, v109
	v_add_f32_e32 v178, v178, v106
	v_add_f32_e32 v218, v218, v107
	v_cvt_pk_bf16_f32 v106, v106, v107
	v_mfma_f32_32x32x16_bf16 v[34:49], v[204:207], v[98:101], v[34:49]
	v_exp_f32_e32 v110, v110
	v_exp_f32_e32 v111, v111
	v_add_f32_e32 v219, v219, v108
	v_add_f32_e32 v220, v220, v109
	v_cvt_pk_bf16_f32 v107, v108, v109
	v_mfma_f32_32x32x16_bf16 v[18:33], v[200:203], v[114:117], v[18:33]
	s_waitcnt vmcnt(0)
	ds_write_b128 v180, v[162:165] offset:36864
	ds_write_b128 v180, v[166:169] offset:46080
	v_exp_f32_e32 v112, v112
	v_exp_f32_e32 v113, v113
	v_add_f32_e32 v178, v178, v110
	v_add_f32_e32 v218, v218, v111
	v_cvt_pk_bf16_f32 v108, v110, v111
	v_mfma_f32_32x32x16_bf16 v[2:17], v[204:207], v[114:117], v[2:17]
	v_exp_f32_e32 v122, v122
	v_exp_f32_e32 v123, v123
	v_add_f32_e32 v219, v219, v112
	v_add_f32_e32 v220, v220, v113
	v_cvt_pk_bf16_f32 v109, v112, v113
	v_mfma_f32_32x32x16_bf16 v[82:97], v[184:187], v[154:157], 0
	v_exp_f32_e32 v124, v124
	v_exp_f32_e32 v125, v125
	v_add_f32_e32 v179, v179, v122
	v_add_f32_e32 v221, v221, v123
	v_cvt_pk_bf16_f32 v122, v122, v123
	v_mfma_f32_32x32x16_bf16 v[82:97], v[188:191], v[138:141], v[82:97]
	v_exp_f32_e32 v126, v126
	v_exp_f32_e32 v127, v127
	v_add_f32_e32 v222, v222, v124
	v_add_f32_e32 v223, v223, v125
	v_cvt_pk_bf16_f32 v123, v124, v125
	v_mfma_f32_32x32x16_bf16 v[82:97], v[192:195], v[142:145], v[82:97]
	v_exp_f32_e32 v128, v128
	v_exp_f32_e32 v129, v129
	v_add_f32_e32 v179, v179, v126
	v_add_f32_e32 v221, v221, v127
	v_cvt_pk_bf16_f32 v124, v126, v127
	v_mfma_f32_32x32x16_bf16 v[82:97], v[196:199], v[158:161], v[82:97]
	s_waitcnt lgkmcnt(0)
	s_barrier
	global_load_dwordx4 v[162:165], v[176:177], off
	global_load_dwordx4 v[166:169], v[176:177], off offset:256
	ds_read_b128 v[184:187], v183 offset:23040
	ds_read_b128 v[188:191], v183 offset:23072
	ds_read_b128 v[192:195], v183 offset:23104
	ds_read_b128 v[196:199], v183 offset:23136
	v_exp_f32_e32 v66, v66
	v_exp_f32_e32 v67, v67
	v_add_f32_e32 v222, v222, v128
	v_add_f32_e32 v223, v223, v129
	v_cvt_pk_bf16_f32 v125, v128, v129
	v_mfma_f32_32x32x16_bf16 v[50:65], v[208:211], v[106:109], v[50:65]
	v_exp_f32_e32 v68, v68
	v_exp_f32_e32 v69, v69
	v_add_f32_e32 v178, v178, v66
	v_add_f32_e32 v218, v218, v67
	v_cvt_pk_bf16_f32 v66, v66, v67
	v_mfma_f32_32x32x16_bf16 v[34:49], v[212:215], v[106:109], v[34:49]
	v_lshl_add_u64 v[176:177], v[176:177], 0, s[8:9]
	v_exp_f32_e32 v70, v70
	v_exp_f32_e32 v71, v71
	v_add_f32_e32 v219, v219, v68
	v_add_f32_e32 v220, v220, v69
	v_cvt_pk_bf16_f32 v67, v68, v69
	v_mfma_f32_32x32x16_bf16 v[18:33], v[208:211], v[122:125], v[18:33]
	v_exp_f32_e32 v72, v72
	v_exp_f32_e32 v73, v73
	v_add_f32_e32 v178, v178, v70
	v_add_f32_e32 v218, v218, v71
	v_cvt_pk_bf16_f32 v68, v70, v71
	v_mfma_f32_32x32x16_bf16 v[2:17], v[212:215], v[122:125], v[2:17]
	v_exp_f32_e32 v82, v82
	v_exp_f32_e32 v83, v83
	v_add_f32_e32 v219, v219, v72
	v_add_f32_e32 v220, v220, v73
	v_cvt_pk_bf16_f32 v69, v72, v73
	s_waitcnt lgkmcnt(0)
	v_mfma_f32_32x32x16_bf16 v[98:113], v[184:187], v[130:133], 0
	ds_read_b64_tr_b16 v[200:201], v216 offset:27648
	ds_read_b64_tr_b16 v[202:203], v216 offset:28224
	ds_read_b64_tr_b16 v[204:205], v216 offset:27712
	ds_read_b64_tr_b16 v[206:207], v216 offset:28288
	v_exp_f32_e32 v84, v84
	v_exp_f32_e32 v85, v85
	v_add_f32_e32 v179, v179, v82
	v_add_f32_e32 v221, v221, v83
	v_cvt_pk_bf16_f32 v82, v82, v83
	v_mfma_f32_32x32x16_bf16 v[98:113], v[188:191], v[134:137], v[98:113]
	ds_read_b64_tr_b16 v[208:209], v216 offset:29952
	ds_read_b64_tr_b16 v[210:211], v216 offset:30528
	ds_read_b64_tr_b16 v[212:213], v216 offset:30016
	ds_read_b64_tr_b16 v[214:215], v216 offset:30592
	v_exp_f32_e32 v86, v86
	v_exp_f32_e32 v87, v87
	v_add_f32_e32 v222, v222, v84
	v_add_f32_e32 v223, v223, v85
	v_cvt_pk_bf16_f32 v83, v84, v85
	v_mfma_f32_32x32x16_bf16 v[98:113], v[192:195], v[146:149], v[98:113]
	v_exp_f32_e32 v88, v88
	v_exp_f32_e32 v89, v89
	v_add_f32_e32 v179, v179, v86
	v_add_f32_e32 v221, v221, v87
	v_cvt_pk_bf16_f32 v84, v86, v87
	v_mfma_f32_32x32x16_bf16 v[98:113], v[196:199], v[150:153], v[98:113]
	v_exp_f32_e32 v74, v74
	v_exp_f32_e32 v75, v75
	v_add_f32_e32 v222, v222, v88
	v_add_f32_e32 v223, v223, v89
	v_cvt_pk_bf16_f32 v85, v88, v89
	v_mfma_f32_32x32x16_bf16 v[114:129], v[184:187], v[154:157], 0
	v_exp_f32_e32 v76, v76
	v_exp_f32_e32 v77, v77
	v_add_f32_e32 v178, v178, v74
	v_add_f32_e32 v218, v218, v75
	v_cvt_pk_bf16_f32 v74, v74, v75
	v_mfma_f32_32x32x16_bf16 v[114:129], v[188:191], v[138:141], v[114:129]
	v_exp_f32_e32 v78, v78
	v_exp_f32_e32 v79, v79
	v_add_f32_e32 v219, v219, v76
	v_add_f32_e32 v220, v220, v77
	v_cvt_pk_bf16_f32 v75, v76, v77
	v_mfma_f32_32x32x16_bf16 v[114:129], v[192:195], v[142:145], v[114:129]
	v_exp_f32_e32 v80, v80
	v_exp_f32_e32 v81, v81
	v_add_f32_e32 v178, v178, v78
	v_add_f32_e32 v218, v218, v79
	v_cvt_pk_bf16_f32 v76, v78, v79
	v_mfma_f32_32x32x16_bf16 v[114:129], v[196:199], v[158:161], v[114:129]
	v_exp_f32_e32 v90, v90
	v_exp_f32_e32 v91, v91
	v_add_f32_e32 v219, v219, v80
	v_add_f32_e32 v220, v220, v81
	v_cvt_pk_bf16_f32 v77, v80, v81
	s_waitcnt lgkmcnt(4)
	v_mfma_f32_32x32x16_bf16 v[50:65], v[200:203], v[66:69], v[50:65]
	ds_read_b128 v[184:187], v183 offset:36864
	ds_read_b128 v[188:191], v183 offset:36896
	ds_read_b128 v[192:195], v183 offset:36928
	ds_read_b128 v[196:199], v183 offset:36960
	v_exp_f32_e32 v92, v92
	v_exp_f32_e32 v93, v93
	v_add_f32_e32 v179, v179, v90
	v_add_f32_e32 v221, v221, v91
	v_cvt_pk_bf16_f32 v90, v90, v91
	v_mfma_f32_32x32x16_bf16 v[34:49], v[204:207], v[66:69], v[34:49]
	v_exp_f32_e32 v94, v94
	v_exp_f32_e32 v95, v95
	v_add_f32_e32 v222, v222, v92
	v_add_f32_e32 v223, v223, v93
	v_cvt_pk_bf16_f32 v91, v92, v93
	v_mfma_f32_32x32x16_bf16 v[18:33], v[200:203], v[82:85], v[18:33]
	v_exp_f32_e32 v96, v96
	v_exp_f32_e32 v97, v97
	v_add_f32_e32 v179, v179, v94
	v_add_f32_e32 v221, v221, v95
	v_cvt_pk_bf16_f32 v92, v94, v95
	v_mfma_f32_32x32x16_bf16 v[2:17], v[204:207], v[82:85], v[2:17]
	v_exp_f32_e32 v98, v98
	v_exp_f32_e32 v99, v99
	v_add_f32_e32 v222, v222, v96
	v_add_f32_e32 v223, v223, v97
	v_cvt_pk_bf16_f32 v93, v96, v97
	s_waitcnt lgkmcnt(4)
	v_mfma_f32_32x32x16_bf16 v[50:65], v[208:211], v[74:77], v[50:65]
	ds_read_b64_tr_b16 v[200:201], v216 offset:32256
	ds_read_b64_tr_b16 v[202:203], v216 offset:32832
	ds_read_b64_tr_b16 v[204:205], v216 offset:32320
	ds_read_b64_tr_b16 v[206:207], v216 offset:32896
	v_exp_f32_e32 v100, v100
	v_exp_f32_e32 v101, v101
	v_add_f32_e32 v178, v178, v98
	v_add_f32_e32 v218, v218, v99
	v_cvt_pk_bf16_f32 v98, v98, v99
	v_mfma_f32_32x32x16_bf16 v[34:49], v[212:215], v[74:77], v[34:49]
	v_exp_f32_e32 v102, v102
	v_exp_f32_e32 v103, v103
	v_add_f32_e32 v219, v219, v100
	v_add_f32_e32 v220, v220, v101
	v_cvt_pk_bf16_f32 v99, v100, v101
	v_mfma_f32_32x32x16_bf16 v[18:33], v[208:211], v[90:93], v[18:33]
	v_exp_f32_e32 v104, v104
	v_exp_f32_e32 v105, v105
	v_add_f32_e32 v178, v178, v102
	v_add_f32_e32 v218, v218, v103
	v_cvt_pk_bf16_f32 v100, v102, v103
	v_mfma_f32_32x32x16_bf16 v[2:17], v[212:215], v[90:93], v[2:17]
	v_exp_f32_e32 v114, v114
	v_exp_f32_e32 v115, v115
	v_add_f32_e32 v219, v219, v104
	v_add_f32_e32 v220, v220, v105
	v_cvt_pk_bf16_f32 v101, v104, v105
	s_waitcnt lgkmcnt(4)
	v_mfma_f32_32x32x16_bf16 v[66:81], v[184:187], v[130:133], 0
	ds_read_b64_tr_b16 v[208:209], v216 offset:34560
	ds_read_b64_tr_b16 v[210:211], v216 offset:35136
	ds_read_b64_tr_b16 v[212:213], v216 offset:34624
	ds_read_b64_tr_b16 v[214:215], v216 offset:35200
	v_exp_f32_e32 v116, v116
	v_exp_f32_e32 v117, v117
	v_add_f32_e32 v179, v179, v114
	v_add_f32_e32 v221, v221, v115
	v_cvt_pk_bf16_f32 v114, v114, v115
	v_mfma_f32_32x32x16_bf16 v[66:81], v[188:191], v[134:137], v[66:81]
	v_exp_f32_e32 v118, v118
	v_exp_f32_e32 v119, v119
	v_add_f32_e32 v222, v222, v116
	v_add_f32_e32 v223, v223, v117
	v_cvt_pk_bf16_f32 v115, v116, v117
	v_mfma_f32_32x32x16_bf16 v[66:81], v[192:195], v[146:149], v[66:81]
	v_exp_f32_e32 v120, v120
	v_exp_f32_e32 v121, v121
	v_add_f32_e32 v179, v179, v118
	v_add_f32_e32 v221, v221, v119
	v_cvt_pk_bf16_f32 v116, v118, v119
	v_mfma_f32_32x32x16_bf16 v[66:81], v[196:199], v[150:153], v[66:81]
	v_exp_f32_e32 v106, v106
	v_exp_f32_e32 v107, v107
	v_add_f32_e32 v222, v222, v120
	v_add_f32_e32 v223, v223, v121
	v_cvt_pk_bf16_f32 v117, v120, v121
	s_waitcnt lgkmcnt(4)
	v_mfma_f32_32x32x16_bf16 v[50:65], v[200:203], v[98:101], v[50:65]
	v_exp_f32_e32 v108, v108
	v_exp_f32_e32 v109, v109
	v_add_f32_e32 v178, v178, v106
	v_add_f32_e32 v218, v218, v107
	v_cvt_pk_bf16_f32 v106, v106, v107
	v_mfma_f32_32x32x16_bf16 v[34:49], v[204:207], v[98:101], v[34:49]
	v_exp_f32_e32 v110, v110
	v_exp_f32_e32 v111, v111
	v_add_f32_e32 v219, v219, v108
	v_add_f32_e32 v220, v220, v109
	v_cvt_pk_bf16_f32 v107, v108, v109
	v_mfma_f32_32x32x16_bf16 v[18:33], v[200:203], v[114:117], v[18:33]
	s_waitcnt vmcnt(0)
	ds_write_b128 v180, v[162:165]
	ds_write_b128 v180, v[166:169] offset:9216
	v_exp_f32_e32 v112, v112
	v_exp_f32_e32 v113, v113
	v_add_f32_e32 v178, v178, v110
	v_add_f32_e32 v218, v218, v111
	v_cvt_pk_bf16_f32 v108, v110, v111
	v_mfma_f32_32x32x16_bf16 v[2:17], v[204:207], v[114:117], v[2:17]
	v_exp_f32_e32 v122, v122
	v_exp_f32_e32 v123, v123
	v_add_f32_e32 v219, v219, v112
	v_add_f32_e32 v220, v220, v113
	v_cvt_pk_bf16_f32 v109, v112, v113
	v_mfma_f32_32x32x16_bf16 v[82:97], v[184:187], v[154:157], 0
	v_exp_f32_e32 v124, v124
	v_exp_f32_e32 v125, v125
	v_add_f32_e32 v179, v179, v122
	v_add_f32_e32 v221, v221, v123
	v_cvt_pk_bf16_f32 v122, v122, v123
	v_mfma_f32_32x32x16_bf16 v[82:97], v[188:191], v[138:141], v[82:97]
	v_exp_f32_e32 v126, v126
	v_exp_f32_e32 v127, v127
	v_add_f32_e32 v222, v222, v124
	v_add_f32_e32 v223, v223, v125
	v_cvt_pk_bf16_f32 v123, v124, v125
	v_mfma_f32_32x32x16_bf16 v[82:97], v[192:195], v[142:145], v[82:97]
	v_exp_f32_e32 v128, v128
	v_exp_f32_e32 v129, v129
	v_add_f32_e32 v179, v179, v126
	v_add_f32_e32 v221, v221, v127
	v_cvt_pk_bf16_f32 v124, v126, v127
	v_mfma_f32_32x32x16_bf16 v[82:97], v[196:199], v[158:161], v[82:97]
	s_waitcnt lgkmcnt(0)
	s_barrier
	ds_read_b128 v[184:187], v183 offset:41472
	ds_read_b128 v[188:191], v183 offset:41504
	ds_read_b128 v[192:195], v183 offset:41536
	ds_read_b128 v[196:199], v183 offset:41568
	v_exp_f32_e32 v66, v66
	v_exp_f32_e32 v67, v67
	v_add_f32_e32 v222, v222, v128
	v_add_f32_e32 v223, v223, v129
	v_cvt_pk_bf16_f32 v125, v128, v129
	v_mfma_f32_32x32x16_bf16 v[50:65], v[208:211], v[106:109], v[50:65]
	v_exp_f32_e32 v68, v68
	v_exp_f32_e32 v69, v69
	v_add_f32_e32 v178, v178, v66
	v_add_f32_e32 v218, v218, v67
	v_cvt_pk_bf16_f32 v66, v66, v67
	v_mfma_f32_32x32x16_bf16 v[34:49], v[212:215], v[106:109], v[34:49]
	v_exp_f32_e32 v70, v70
	v_exp_f32_e32 v71, v71
	v_add_f32_e32 v219, v219, v68
	v_add_f32_e32 v220, v220, v69
	v_cvt_pk_bf16_f32 v67, v68, v69
	v_mfma_f32_32x32x16_bf16 v[18:33], v[208:211], v[122:125], v[18:33]
	v_exp_f32_e32 v72, v72
	v_exp_f32_e32 v73, v73
	v_add_f32_e32 v178, v178, v70
	v_add_f32_e32 v218, v218, v71
	v_cvt_pk_bf16_f32 v68, v70, v71
	v_mfma_f32_32x32x16_bf16 v[2:17], v[212:215], v[122:125], v[2:17]
	v_exp_f32_e32 v82, v82
	v_exp_f32_e32 v83, v83
	v_add_f32_e32 v219, v219, v72
	v_add_f32_e32 v220, v220, v73
	v_cvt_pk_bf16_f32 v69, v72, v73
	s_waitcnt lgkmcnt(0)
	v_mfma_f32_32x32x16_bf16 v[98:113], v[184:187], v[130:133], 0
	ds_read_b64_tr_b16 v[200:201], v216 offset:46080
	ds_read_b64_tr_b16 v[202:203], v216 offset:46656
	ds_read_b64_tr_b16 v[204:205], v216 offset:46144
	ds_read_b64_tr_b16 v[206:207], v216 offset:46720
	v_exp_f32_e32 v84, v84
	v_exp_f32_e32 v85, v85
	v_add_f32_e32 v179, v179, v82
	v_add_f32_e32 v221, v221, v83
	v_cvt_pk_bf16_f32 v82, v82, v83
	v_mfma_f32_32x32x16_bf16 v[98:113], v[188:191], v[134:137], v[98:113]
	ds_read_b64_tr_b16 v[208:209], v216 offset:48384
	ds_read_b64_tr_b16 v[210:211], v216 offset:48960
	ds_read_b64_tr_b16 v[212:213], v216 offset:48448
	ds_read_b64_tr_b16 v[214:215], v216 offset:49024
	v_exp_f32_e32 v86, v86
	v_exp_f32_e32 v87, v87
	v_add_f32_e32 v222, v222, v84
	v_add_f32_e32 v223, v223, v85
	v_cvt_pk_bf16_f32 v83, v84, v85
	v_mfma_f32_32x32x16_bf16 v[98:113], v[192:195], v[146:149], v[98:113]
	v_exp_f32_e32 v88, v88
	v_exp_f32_e32 v89, v89
	v_add_f32_e32 v179, v179, v86
	v_add_f32_e32 v221, v221, v87
	v_cvt_pk_bf16_f32 v84, v86, v87
	v_mfma_f32_32x32x16_bf16 v[98:113], v[196:199], v[150:153], v[98:113]
	v_exp_f32_e32 v74, v74
	v_exp_f32_e32 v75, v75
	v_add_f32_e32 v222, v222, v88
	v_add_f32_e32 v223, v223, v89
	v_cvt_pk_bf16_f32 v85, v88, v89
	v_mfma_f32_32x32x16_bf16 v[114:129], v[184:187], v[154:157], 0
	v_exp_f32_e32 v76, v76
	v_exp_f32_e32 v77, v77
	v_add_f32_e32 v178, v178, v74
	v_add_f32_e32 v218, v218, v75
	v_cvt_pk_bf16_f32 v74, v74, v75
	v_mfma_f32_32x32x16_bf16 v[114:129], v[188:191], v[138:141], v[114:129]
	v_exp_f32_e32 v78, v78
	v_exp_f32_e32 v79, v79
	v_add_f32_e32 v219, v219, v76
	v_add_f32_e32 v220, v220, v77
	v_cvt_pk_bf16_f32 v75, v76, v77
	v_mfma_f32_32x32x16_bf16 v[114:129], v[192:195], v[142:145], v[114:129]
	v_exp_f32_e32 v80, v80
	v_exp_f32_e32 v81, v81
	v_add_f32_e32 v178, v178, v78
	v_add_f32_e32 v218, v218, v79
	v_cvt_pk_bf16_f32 v76, v78, v79
	v_mfma_f32_32x32x16_bf16 v[114:129], v[196:199], v[158:161], v[114:129]
	v_exp_f32_e32 v90, v90
	v_exp_f32_e32 v91, v91
	v_add_f32_e32 v219, v219, v80
	v_add_f32_e32 v220, v220, v81
	v_cvt_pk_bf16_f32 v77, v80, v81
	s_waitcnt lgkmcnt(4)
	v_mfma_f32_32x32x16_bf16 v[50:65], v[200:203], v[66:69], v[50:65]
	ds_read_b128 v[184:187], v183
	ds_read_b128 v[188:191], v183 offset:32
	ds_read_b128 v[192:195], v183 offset:64
	ds_read_b128 v[196:199], v183 offset:96
	v_exp_f32_e32 v92, v92
	v_exp_f32_e32 v93, v93
	v_add_f32_e32 v179, v179, v90
	v_add_f32_e32 v221, v221, v91
	v_cvt_pk_bf16_f32 v90, v90, v91
	v_mfma_f32_32x32x16_bf16 v[34:49], v[204:207], v[66:69], v[34:49]
	v_exp_f32_e32 v94, v94
	v_exp_f32_e32 v95, v95
	v_add_f32_e32 v222, v222, v92
	v_add_f32_e32 v223, v223, v93
	v_cvt_pk_bf16_f32 v91, v92, v93
	v_mfma_f32_32x32x16_bf16 v[18:33], v[200:203], v[82:85], v[18:33]
	v_exp_f32_e32 v96, v96
	v_exp_f32_e32 v97, v97
	v_add_f32_e32 v179, v179, v94
	v_add_f32_e32 v221, v221, v95
	v_cvt_pk_bf16_f32 v92, v94, v95
	v_mfma_f32_32x32x16_bf16 v[2:17], v[204:207], v[82:85], v[2:17]
	v_exp_f32_e32 v98, v98
	v_exp_f32_e32 v99, v99
	v_add_f32_e32 v222, v222, v96
	v_add_f32_e32 v223, v223, v97
	v_cvt_pk_bf16_f32 v93, v96, v97
	s_waitcnt lgkmcnt(4)
	v_mfma_f32_32x32x16_bf16 v[50:65], v[208:211], v[74:77], v[50:65]
	ds_read_b64_tr_b16 v[200:201], v216 offset:50688
	ds_read_b64_tr_b16 v[202:203], v216 offset:51264
	ds_read_b64_tr_b16 v[204:205], v216 offset:50752
	ds_read_b64_tr_b16 v[206:207], v216 offset:51328
	v_exp_f32_e32 v100, v100
	v_exp_f32_e32 v101, v101
	v_add_f32_e32 v178, v178, v98
	v_add_f32_e32 v218, v218, v99
	v_cvt_pk_bf16_f32 v98, v98, v99
	v_mfma_f32_32x32x16_bf16 v[34:49], v[212:215], v[74:77], v[34:49]
	v_exp_f32_e32 v102, v102
	v_exp_f32_e32 v103, v103
	v_add_f32_e32 v219, v219, v100
	v_add_f32_e32 v220, v220, v101
	v_cvt_pk_bf16_f32 v99, v100, v101
	v_mfma_f32_32x32x16_bf16 v[18:33], v[208:211], v[90:93], v[18:33]
	v_exp_f32_e32 v104, v104
	v_exp_f32_e32 v105, v105
	v_add_f32_e32 v178, v178, v102
	v_add_f32_e32 v218, v218, v103
	v_cvt_pk_bf16_f32 v100, v102, v103
	v_mfma_f32_32x32x16_bf16 v[2:17], v[212:215], v[90:93], v[2:17]
	v_exp_f32_e32 v114, v114
	v_exp_f32_e32 v115, v115
	v_add_f32_e32 v219, v219, v104
	v_add_f32_e32 v220, v220, v105
	v_cvt_pk_bf16_f32 v101, v104, v105
	s_waitcnt lgkmcnt(4)
	v_mfma_f32_32x32x16_bf16 v[66:81], v[184:187], v[130:133], 0
	ds_read_b64_tr_b16 v[208:209], v216 offset:52992
	ds_read_b64_tr_b16 v[210:211], v216 offset:53568
	ds_read_b64_tr_b16 v[212:213], v216 offset:53056
	ds_read_b64_tr_b16 v[214:215], v216 offset:53632
	v_exp_f32_e32 v116, v116
	v_exp_f32_e32 v117, v117
	v_add_f32_e32 v179, v179, v114
	v_add_f32_e32 v221, v221, v115
	v_cvt_pk_bf16_f32 v114, v114, v115
	v_mfma_f32_32x32x16_bf16 v[66:81], v[188:191], v[134:137], v[66:81]
	v_exp_f32_e32 v118, v118
	v_exp_f32_e32 v119, v119
	v_add_f32_e32 v222, v222, v116
	v_add_f32_e32 v223, v223, v117
	v_cvt_pk_bf16_f32 v115, v116, v117
	v_mfma_f32_32x32x16_bf16 v[66:81], v[192:195], v[146:149], v[66:81]
	v_exp_f32_e32 v120, v120
	v_exp_f32_e32 v121, v121
	v_add_f32_e32 v179, v179, v118
	v_add_f32_e32 v221, v221, v119
	v_cvt_pk_bf16_f32 v116, v118, v119
	v_mfma_f32_32x32x16_bf16 v[66:81], v[196:199], v[150:153], v[66:81]
	v_exp_f32_e32 v106, v106
	v_exp_f32_e32 v107, v107
	v_add_f32_e32 v222, v222, v120
	v_add_f32_e32 v223, v223, v121
	v_cvt_pk_bf16_f32 v117, v120, v121
	s_waitcnt lgkmcnt(4)
	v_mfma_f32_32x32x16_bf16 v[50:65], v[200:203], v[98:101], v[50:65]
	v_exp_f32_e32 v108, v108
	v_exp_f32_e32 v109, v109
	v_add_f32_e32 v178, v178, v106
	v_add_f32_e32 v218, v218, v107
	v_cvt_pk_bf16_f32 v106, v106, v107
	v_mfma_f32_32x32x16_bf16 v[34:49], v[204:207], v[98:101], v[34:49]
	v_exp_f32_e32 v110, v110
	v_exp_f32_e32 v111, v111
	v_add_f32_e32 v219, v219, v108
	v_add_f32_e32 v220, v220, v109
	v_cvt_pk_bf16_f32 v107, v108, v109
	v_mfma_f32_32x32x16_bf16 v[18:33], v[200:203], v[114:117], v[18:33]
	v_exp_f32_e32 v112, v112
	v_exp_f32_e32 v113, v113
	v_add_f32_e32 v178, v178, v110
	v_add_f32_e32 v218, v218, v111
	v_cvt_pk_bf16_f32 v108, v110, v111
	v_mfma_f32_32x32x16_bf16 v[2:17], v[204:207], v[114:117], v[2:17]
	v_exp_f32_e32 v122, v122
	v_exp_f32_e32 v123, v123
	v_add_f32_e32 v219, v219, v112
	v_add_f32_e32 v220, v220, v113
	v_cvt_pk_bf16_f32 v109, v112, v113
	v_mfma_f32_32x32x16_bf16 v[82:97], v[184:187], v[154:157], 0
	v_exp_f32_e32 v124, v124
	v_exp_f32_e32 v125, v125
	v_add_f32_e32 v179, v179, v122
	v_add_f32_e32 v221, v221, v123
	v_cvt_pk_bf16_f32 v122, v122, v123
	v_mfma_f32_32x32x16_bf16 v[82:97], v[188:191], v[138:141], v[82:97]
	v_exp_f32_e32 v126, v126
	v_exp_f32_e32 v127, v127
	v_add_f32_e32 v222, v222, v124
	v_add_f32_e32 v223, v223, v125
	v_cvt_pk_bf16_f32 v123, v124, v125
	v_mfma_f32_32x32x16_bf16 v[82:97], v[192:195], v[142:145], v[82:97]
	v_exp_f32_e32 v128, v128
	v_exp_f32_e32 v129, v129
	v_add_f32_e32 v179, v179, v126
	v_add_f32_e32 v221, v221, v127
	v_cvt_pk_bf16_f32 v124, v126, v127
	v_mfma_f32_32x32x16_bf16 v[82:97], v[196:199], v[158:161], v[82:97]
	s_waitcnt lgkmcnt(0)
	s_barrier
	ds_read_b128 v[184:187], v183 offset:4608
	ds_read_b128 v[188:191], v183 offset:4640
	ds_read_b128 v[192:195], v183 offset:4672
	ds_read_b128 v[196:199], v183 offset:4704
	v_exp_f32_e32 v66, v66
	v_exp_f32_e32 v67, v67
	v_add_f32_e32 v222, v222, v128
	v_add_f32_e32 v223, v223, v129
	v_cvt_pk_bf16_f32 v125, v128, v129
	v_mfma_f32_32x32x16_bf16 v[50:65], v[208:211], v[106:109], v[50:65]
	v_exp_f32_e32 v68, v68
	v_exp_f32_e32 v69, v69
	v_add_f32_e32 v178, v178, v66
	v_add_f32_e32 v218, v218, v67
	v_cvt_pk_bf16_f32 v66, v66, v67
	v_mfma_f32_32x32x16_bf16 v[34:49], v[212:215], v[106:109], v[34:49]
	v_exp_f32_e32 v70, v70
	v_exp_f32_e32 v71, v71
	v_add_f32_e32 v219, v219, v68
	v_add_f32_e32 v220, v220, v69
	v_cvt_pk_bf16_f32 v67, v68, v69
	v_mfma_f32_32x32x16_bf16 v[18:33], v[208:211], v[122:125], v[18:33]
	v_exp_f32_e32 v72, v72
	v_exp_f32_e32 v73, v73
	v_add_f32_e32 v178, v178, v70
	v_add_f32_e32 v218, v218, v71
	v_cvt_pk_bf16_f32 v68, v70, v71
	v_mfma_f32_32x32x16_bf16 v[2:17], v[212:215], v[122:125], v[2:17]
	v_exp_f32_e32 v82, v82
	v_exp_f32_e32 v83, v83
	v_add_f32_e32 v219, v219, v72
	v_add_f32_e32 v220, v220, v73
	v_cvt_pk_bf16_f32 v69, v72, v73
	s_waitcnt lgkmcnt(0)
	v_mfma_f32_32x32x16_bf16 v[98:113], v[184:187], v[130:133], 0
	ds_read_b64_tr_b16 v[200:201], v216 offset:9216
	ds_read_b64_tr_b16 v[202:203], v216 offset:9792
	ds_read_b64_tr_b16 v[204:205], v216 offset:9280
	ds_read_b64_tr_b16 v[206:207], v216 offset:9856
	v_exp_f32_e32 v84, v84
	v_exp_f32_e32 v85, v85
	v_add_f32_e32 v179, v179, v82
	v_add_f32_e32 v221, v221, v83
	v_cvt_pk_bf16_f32 v82, v82, v83
	v_mfma_f32_32x32x16_bf16 v[98:113], v[188:191], v[134:137], v[98:113]
	ds_read_b64_tr_b16 v[208:209], v216 offset:11520
	ds_read_b64_tr_b16 v[210:211], v216 offset:12096
	ds_read_b64_tr_b16 v[212:213], v216 offset:11584
	ds_read_b64_tr_b16 v[214:215], v216 offset:12160
	v_exp_f32_e32 v86, v86
	v_exp_f32_e32 v87, v87
	v_add_f32_e32 v222, v222, v84
	v_add_f32_e32 v223, v223, v85
	v_cvt_pk_bf16_f32 v83, v84, v85
	v_mfma_f32_32x32x16_bf16 v[98:113], v[192:195], v[146:149], v[98:113]
	v_exp_f32_e32 v88, v88
	v_exp_f32_e32 v89, v89
	v_add_f32_e32 v179, v179, v86
	v_add_f32_e32 v221, v221, v87
	v_cvt_pk_bf16_f32 v84, v86, v87
	v_mfma_f32_32x32x16_bf16 v[98:113], v[196:199], v[150:153], v[98:113]
	v_exp_f32_e32 v74, v74
	v_exp_f32_e32 v75, v75
	v_add_f32_e32 v222, v222, v88
	v_add_f32_e32 v223, v223, v89
	v_cvt_pk_bf16_f32 v85, v88, v89
	v_mfma_f32_32x32x16_bf16 v[114:129], v[184:187], v[154:157], 0
	v_exp_f32_e32 v76, v76
	v_exp_f32_e32 v77, v77
	v_add_f32_e32 v178, v178, v74
	v_add_f32_e32 v218, v218, v75
	v_cvt_pk_bf16_f32 v74, v74, v75
	v_mfma_f32_32x32x16_bf16 v[114:129], v[188:191], v[138:141], v[114:129]
	v_exp_f32_e32 v78, v78
	v_exp_f32_e32 v79, v79
	v_add_f32_e32 v219, v219, v76
	v_add_f32_e32 v220, v220, v77
	v_cvt_pk_bf16_f32 v75, v76, v77
	v_mfma_f32_32x32x16_bf16 v[114:129], v[192:195], v[142:145], v[114:129]
	v_exp_f32_e32 v80, v80
	v_exp_f32_e32 v81, v81
	v_add_f32_e32 v178, v178, v78
	v_add_f32_e32 v218, v218, v79
	v_cvt_pk_bf16_f32 v76, v78, v79
	v_mfma_f32_32x32x16_bf16 v[114:129], v[196:199], v[158:161], v[114:129]
	v_exp_f32_e32 v90, v90
	v_exp_f32_e32 v91, v91
	v_add_f32_e32 v219, v219, v80
	v_add_f32_e32 v220, v220, v81
	v_cvt_pk_bf16_f32 v77, v80, v81
	s_waitcnt lgkmcnt(4)
	v_mfma_f32_32x32x16_bf16 v[50:65], v[200:203], v[66:69], v[50:65]
	ds_read_b128 v[184:187], v183 offset:18432
	ds_read_b128 v[188:191], v183 offset:18464
	ds_read_b128 v[192:195], v183 offset:18496
	ds_read_b128 v[196:199], v183 offset:18528
	v_exp_f32_e32 v92, v92
	v_exp_f32_e32 v93, v93
	v_add_f32_e32 v179, v179, v90
	v_add_f32_e32 v221, v221, v91
	v_cvt_pk_bf16_f32 v90, v90, v91
	v_mfma_f32_32x32x16_bf16 v[34:49], v[204:207], v[66:69], v[34:49]
	v_exp_f32_e32 v94, v94
	v_exp_f32_e32 v95, v95
	v_add_f32_e32 v222, v222, v92
	v_add_f32_e32 v223, v223, v93
	v_cvt_pk_bf16_f32 v91, v92, v93
	v_mfma_f32_32x32x16_bf16 v[18:33], v[200:203], v[82:85], v[18:33]
	v_exp_f32_e32 v96, v96
	v_exp_f32_e32 v97, v97
	v_add_f32_e32 v179, v179, v94
	v_add_f32_e32 v221, v221, v95
	v_cvt_pk_bf16_f32 v92, v94, v95
	v_mfma_f32_32x32x16_bf16 v[2:17], v[204:207], v[82:85], v[2:17]
	v_exp_f32_e32 v98, v98
	v_exp_f32_e32 v99, v99
	v_add_f32_e32 v222, v222, v96
	v_add_f32_e32 v223, v223, v97
	v_cvt_pk_bf16_f32 v93, v96, v97
	s_waitcnt lgkmcnt(4)
	v_mfma_f32_32x32x16_bf16 v[50:65], v[208:211], v[74:77], v[50:65]
	ds_read_b64_tr_b16 v[200:201], v216 offset:13824
	ds_read_b64_tr_b16 v[202:203], v216 offset:14400
	ds_read_b64_tr_b16 v[204:205], v216 offset:13888
	ds_read_b64_tr_b16 v[206:207], v216 offset:14464
	v_exp_f32_e32 v100, v100
	v_exp_f32_e32 v101, v101
	v_add_f32_e32 v178, v178, v98
	v_add_f32_e32 v218, v218, v99
	v_cvt_pk_bf16_f32 v98, v98, v99
	v_mfma_f32_32x32x16_bf16 v[34:49], v[212:215], v[74:77], v[34:49]
	v_exp_f32_e32 v102, v102
	v_exp_f32_e32 v103, v103
	v_add_f32_e32 v219, v219, v100
	v_add_f32_e32 v220, v220, v101
	v_cvt_pk_bf16_f32 v99, v100, v101
	v_mfma_f32_32x32x16_bf16 v[18:33], v[208:211], v[90:93], v[18:33]
	v_exp_f32_e32 v104, v104
	v_exp_f32_e32 v105, v105
	v_add_f32_e32 v178, v178, v102
	v_add_f32_e32 v218, v218, v103
	v_cvt_pk_bf16_f32 v100, v102, v103
	v_mfma_f32_32x32x16_bf16 v[2:17], v[212:215], v[90:93], v[2:17]
	v_exp_f32_e32 v114, v114
	v_exp_f32_e32 v115, v115
	v_add_f32_e32 v219, v219, v104
	v_add_f32_e32 v220, v220, v105
	v_cvt_pk_bf16_f32 v101, v104, v105
	s_waitcnt lgkmcnt(4)
	v_mfma_f32_32x32x16_bf16 v[66:81], v[184:187], v[130:133], 0
	ds_read_b64_tr_b16 v[208:209], v216 offset:16128
	ds_read_b64_tr_b16 v[210:211], v216 offset:16704
	ds_read_b64_tr_b16 v[212:213], v216 offset:16192
	ds_read_b64_tr_b16 v[214:215], v216 offset:16768
	v_exp_f32_e32 v116, v116
	v_exp_f32_e32 v117, v117
	v_add_f32_e32 v179, v179, v114
	v_add_f32_e32 v221, v221, v115
	v_cvt_pk_bf16_f32 v114, v114, v115
	v_mfma_f32_32x32x16_bf16 v[66:81], v[188:191], v[134:137], v[66:81]
	v_exp_f32_e32 v118, v118
	v_exp_f32_e32 v119, v119
	v_add_f32_e32 v222, v222, v116
	v_add_f32_e32 v223, v223, v117
	v_cvt_pk_bf16_f32 v115, v116, v117
	v_mfma_f32_32x32x16_bf16 v[66:81], v[192:195], v[146:149], v[66:81]
	v_exp_f32_e32 v120, v120
	v_exp_f32_e32 v121, v121
	v_add_f32_e32 v179, v179, v118
	v_add_f32_e32 v221, v221, v119
	v_cvt_pk_bf16_f32 v116, v118, v119
	v_mfma_f32_32x32x16_bf16 v[66:81], v[196:199], v[150:153], v[66:81]
	v_exp_f32_e32 v106, v106
	v_exp_f32_e32 v107, v107
	v_add_f32_e32 v222, v222, v120
	v_add_f32_e32 v223, v223, v121
	v_cvt_pk_bf16_f32 v117, v120, v121
	s_waitcnt lgkmcnt(4)
	v_mfma_f32_32x32x16_bf16 v[50:65], v[200:203], v[98:101], v[50:65]
	v_exp_f32_e32 v108, v108
	v_exp_f32_e32 v109, v109
	v_add_f32_e32 v178, v178, v106
	v_add_f32_e32 v218, v218, v107
	v_cvt_pk_bf16_f32 v106, v106, v107
	v_mfma_f32_32x32x16_bf16 v[34:49], v[204:207], v[98:101], v[34:49]
	v_exp_f32_e32 v110, v110
	v_exp_f32_e32 v111, v111
	v_add_f32_e32 v219, v219, v108
	v_add_f32_e32 v220, v220, v109
	v_cvt_pk_bf16_f32 v107, v108, v109
	v_mfma_f32_32x32x16_bf16 v[18:33], v[200:203], v[114:117], v[18:33]
	v_exp_f32_e32 v112, v112
	v_exp_f32_e32 v113, v113
	v_add_f32_e32 v178, v178, v110
	v_add_f32_e32 v218, v218, v111
	v_cvt_pk_bf16_f32 v108, v110, v111
	v_mfma_f32_32x32x16_bf16 v[2:17], v[204:207], v[114:117], v[2:17]
	v_exp_f32_e32 v122, v122
	v_exp_f32_e32 v123, v123
	v_add_f32_e32 v219, v219, v112
	v_add_f32_e32 v220, v220, v113
	v_cvt_pk_bf16_f32 v109, v112, v113
	v_mfma_f32_32x32x16_bf16 v[82:97], v[184:187], v[154:157], 0
	v_exp_f32_e32 v124, v124
	v_exp_f32_e32 v125, v125
	v_add_f32_e32 v179, v179, v122
	v_add_f32_e32 v221, v221, v123
	v_cvt_pk_bf16_f32 v122, v122, v123
	v_mfma_f32_32x32x16_bf16 v[82:97], v[188:191], v[138:141], v[82:97]
	v_exp_f32_e32 v126, v126
	v_exp_f32_e32 v127, v127
	v_add_f32_e32 v222, v222, v124
	v_add_f32_e32 v223, v223, v125
	v_cvt_pk_bf16_f32 v123, v124, v125
	v_mfma_f32_32x32x16_bf16 v[82:97], v[192:195], v[142:145], v[82:97]
	v_exp_f32_e32 v128, v128
	v_exp_f32_e32 v129, v129
	v_add_f32_e32 v179, v179, v126
	v_add_f32_e32 v221, v221, v127
	v_cvt_pk_bf16_f32 v124, v126, v127
	v_mfma_f32_32x32x16_bf16 v[82:97], v[196:199], v[158:161], v[82:97]
	v_add_f32_e32 v222, v222, v128
	v_add_f32_e32 v223, v223, v129
	v_cvt_pk_bf16_f32 v125, v128, v129
	s_waitcnt lgkmcnt(0)
	v_mfma_f32_32x32x16_bf16 v[50:65], v[208:211], v[106:109], v[50:65]
	v_mfma_f32_32x32x16_bf16 v[34:49], v[212:215], v[106:109], v[34:49]
	v_mfma_f32_32x32x16_bf16 v[18:33], v[208:211], v[122:125], v[18:33]
	v_mfma_f32_32x32x16_bf16 v[2:17], v[212:215], v[122:125], v[2:17]
	v_add_f32_e32 v178, v178, v218
	v_add_f32_e32 v219, v219, v220
	v_add_f32_e32 v179, v179, v221
	v_add_f32_e32 v222, v222, v223
	v_add_f32_e32 v178, v178, v219
	v_add_f32_e32 v179, v179, v222
	s_branch .LBB0_299

.LBB0_915:
	s_abs_i32 s1, s74
	v_cvt_f32_u32_e32 v1, s1
	s_sub_i32 s5, 0, s1
	s_add_i32 s3, s74, 0x7ff
	s_xor_b32 s4, s3, s74
	v_rcp_iflag_f32_e32 v1, v1
	s_abs_i32 s3, s3
	s_ashr_i32 s4, s4, 31
	v_mul_f32_e32 v1, 0x4f7ffffe, v1
	v_cvt_u32_f32_e32 v1, v1
	s_nop 0
	v_readfirstlane_b32 s6, v1
	s_mul_i32 s5, s5, s6
	s_mul_hi_u32 s5, s6, s5
	s_add_i32 s6, s6, s5
	s_mul_hi_u32 s5, s3, s6
	s_mul_i32 s6, s5, s1
	s_sub_i32 s3, s3, s6
	s_add_i32 s7, s5, 1
	s_sub_i32 s6, s3, s1
	s_cmp_ge_u32 s3, s1
	s_cselect_b32 s5, s7, s5
	s_cselect_b32 s3, s6, s3
	s_add_i32 s6, s5, 1
	s_cmp_ge_u32 s3, s1
	s_cselect_b32 s1, s6, s5
	s_xor_b32 s1, s1, s4
	s_sub_i32 s3, s1, s4
	s_cmp_lt_i32 s3, 1
	s_cbranch_scc1 .LBB0_963
	v_and_b32_e32 v196, 31, v0
	v_bfe_u32 v197, v0, 5, 1
	v_readfirstlane_b32 s31, v0
	s_nop 3
	s_lshr_b32 s31, s31, 6
	s_lshr_b32 s30, s31, 2
	s_and_b32 s29, s31, 3
	s_lshl_b32 s28, s29, 3
	s_cmp_ge_u32 s29, 2
	s_cselect_b32 s6, 8, 0
	s_add_i32 s28, s28, s6
	s_mov_b32 s14, 0x3e38aa3b
	s_mov_b32 s13, 0x3fb8aa3b
	s_movk_i32 s15, 0x1d0
	s_movk_i32 s18, 0xf8
	v_and_b32_e32 v217, 15, v196
	s_lshl_b32 s6, s29, 4
	v_add_u32_e32 v198, s6, v217
	v_add_u32_e32 v217, -8, v198
	v_med3_i32 v217, v217, 0, 48
	v_lshl_add_u32 v218, v197, 3, s28
	v_sub_u32_e32 v219, v218, v217
	v_mov_b32_e32 v229, 0xff800000
	v_add_u32_e32 v220, 0, v219
	v_cmp_gt_u32_e32 vcc, 16, v220
	s_nop 1
	v_cndmask_b32_e64 v98, v229, 0, vcc
	v_add_u32_e32 v220, 1, v219
	v_cmp_gt_u32_e32 vcc, 16, v220
	s_nop 1
	v_cndmask_b32_e64 v99, v229, 0, vcc
	v_add_u32_e32 v220, 2, v219
	v_cmp_gt_u32_e32 vcc, 16, v220
	s_nop 1
	v_cndmask_b32_e64 v100, v229, 0, vcc
	v_add_u32_e32 v220, 3, v219
	v_cmp_gt_u32_e32 vcc, 16, v220
	s_nop 1
	v_cndmask_b32_e64 v101, v229, 0, vcc
	v_add_u32_e32 v220, 4, v219
	v_cmp_gt_u32_e32 vcc, 16, v220
	s_nop 1
	v_cndmask_b32_e64 v102, v229, 0, vcc
	v_add_u32_e32 v220, 5, v219
	v_cmp_gt_u32_e32 vcc, 16, v220
	s_nop 1
	v_cndmask_b32_e64 v103, v229, 0, vcc
	v_add_u32_e32 v220, 6, v219
	v_cmp_gt_u32_e32 vcc, 16, v220
	s_nop 1
	v_cndmask_b32_e64 v104, v229, 0, vcc
	v_add_u32_e32 v220, 7, v219
	v_cmp_gt_u32_e32 vcc, 16, v220
	s_nop 1
	v_cndmask_b32_e64 v105, v229, 0, vcc
	v_add_u32_e32 v220, 16, v219
	v_cmp_gt_u32_e32 vcc, 16, v220
	s_nop 1
	v_cndmask_b32_e64 v106, v229, 0, vcc
	v_add_u32_e32 v220, 17, v219
	v_cmp_gt_u32_e32 vcc, 16, v220
	s_nop 1
	v_cndmask_b32_e64 v107, v229, 0, vcc
	v_add_u32_e32 v220, 18, v219
	v_cmp_gt_u32_e32 vcc, 16, v220
	s_nop 1
	v_cndmask_b32_e64 v108, v229, 0, vcc
	v_add_u32_e32 v220, 19, v219
	v_cmp_gt_u32_e32 vcc, 16, v220
	s_nop 1
	v_cndmask_b32_e64 v109, v229, 0, vcc
	v_add_u32_e32 v220, 20, v219
	v_cmp_gt_u32_e32 vcc, 16, v220
	s_nop 1
	v_cndmask_b32_e64 v110, v229, 0, vcc
	v_add_u32_e32 v220, 21, v219
	v_cmp_gt_u32_e32 vcc, 16, v220
	s_nop 1
	v_cndmask_b32_e64 v111, v229, 0, vcc
	v_add_u32_e32 v220, 22, v219
	v_cmp_gt_u32_e32 vcc, 16, v220
	s_nop 1
	v_cndmask_b32_e64 v112, v229, 0, vcc
	v_add_u32_e32 v220, 23, v219
	v_cmp_gt_u32_e32 vcc, 16, v220
	s_nop 1
	v_cndmask_b32_e64 v113, v229, 0, vcc
	v_sub_u32_e32 v199, v218, v198
	v_add_u32_e32 v199, 15, v199
	v_and_b32_e32 v217, 0x13, v196
	v_and_b32_e32 v218, 4, v196
	v_and_b32_e32 v219, 8, v196
	v_lshlrev_b32_e32 v218, 1, v218
	v_lshrrev_b32_e32 v219, 1, v219
	v_or3_b32 v217, v217, v218, v219
	v_add_u32_e32 v217, s28, v217
	v_mul_u32_u24_e32 v200, 0x90, v217
	v_lshl_add_u32 v200, v197, 4, v200
	v_add_u32_e32 v242, 0xd800, v200
	v_bfe_u32 v217, v0, 2, 2
	v_lshl_add_u32 v217, v197, 3, v217
	v_add_u32_e32 v217, s28, v217
	v_mul_u32_u24_e32 v201, 0x90, v217
	v_bfe_u32 v218, v0, 4, 1
	v_lshl_add_u32 v201, v218, 5, v201
	v_and_b32_e32 v218, 3, v0
	v_lshl_add_u32 v201, v218, 3, v201
	v_add_u32_e32 v243, 0xd800, v201
	v_lshrrev_b32_e32 v204, 3, v0
	v_and_b32_e32 v218, 7, v0
	v_lshlrev_b32_e32 v205, 4, v218
	v_mul_u32_u24_e32 v202, 0x90, v204
	v_add_u32_e32 v202, v202, v205
	v_add_u32_e32 v203, 0xd800, v202
	v_mul_u32_u24_e32 v231, 0x1800, v204
	v_add_u32_e32 v231, v231, v205
	v_mov_b32_e32 v244, 112964
	v_add_u32_e32 v217, 0x200, v0
	v_min_u32_e32 v217, 0x290, v217
	v_lshlrev_b32_e32 v245, 2, v0
	v_add_u32_e32 v245, 110592, v245
	v_add_u32_e32 v218, -64, v0
	v_med3_i32 v219, v218, 0, s15
	v_lshlrev_b32_e32 v247, 2, v219
	v_mov_b32_e32 v249, 0
	v_cmp_gt_u32_e32 vcc, 0x1d1, v218
	s_nop 1
	v_cndmask_b32_e64 v249, v249, 1, vcc
	v_cmp_lt_i32_e32 vcc, 0x210, v218
	s_nop 1
	v_cndmask_b32_e64 v249, v249, 2, vcc
	v_lshlrev_b32_e32 v246, 2, v217
	v_add_u32_e32 v246, 110592, v246
	v_add_u32_e32 v218, -64, v217
	v_med3_i32 v219, v218, 0, s15
	v_lshlrev_b32_e32 v248, 2, v219
	v_mov_b32_e32 v250, 0
	v_cmp_gt_u32_e32 vcc, 0x1d1, v218
	s_nop 1
	v_cndmask_b32_e64 v250, v250, 1, vcc
	v_cmp_lt_i32_e32 vcc, 0x210, v218
	s_nop 1
	v_cndmask_b32_e64 v250, v250, 2, vcc
	s_mov_b32 s20, s3
	s_mul_i32 s21, s3, s0
	s_cmpk_gt_i32 s21, 0x7ff
	s_cbranch_scc1 .Lna_done
	s_lshr_b32 s6, s21, 6
	s_and_b32 s7, s21, 63
	s_lshr_b32 s8, s6, 4
	s_and_b32 s9, s6, 15
	s_lshl_b32 s10, s7, 2
	s_add_i32 s22, s10, -4
	s_max_i32 s22, s22, 0
	s_min_i32 s22, s22, 0xf8
	s_mul_i32 s11, s8, 0x6000000
	s_lshl_b32 s12, s9, 7
	s_add_u32 s4, s94, 0x7800000
	s_addc_u32 s5, s95, 0
	s_add_u32 s4, s4, s11
	s_addc_u32 s5, s5, 0
	s_add_u32 s4, s4, s12
	s_addc_u32 s5, s5, 0
	s_add_u32 s34, s4, 0x800
	s_addc_u32 s35, s5, 0
	s_add_u32 s36, s4, 0x1000
	s_addc_u32 s37, s5, 0
	s_mul_i32 s11, s9, 0x744
	s_add_u32 s38, s86, s11
	s_addc_u32 s39, s87, 0
	s_lshl_b32 s26, s30, 1
	s_add_i32 s26, s26, s10
	v_lshrrev_b32_e32 v217, 4, v196
	v_add_u32_e32 v217, s26, v217
	v_lshl_add_u32 v217, v217, 6, v198
	v_mul_u32_u24_e32 v217, 0x1800, v217
	v_lshl_add_u32 v217, v197, 4, v217
	global_load_dwordx4 v[82:85], v217, s[4:5]
	global_load_dwordx4 v[86:89], v217, s[4:5] offset:32
	global_load_dwordx4 v[90:93], v217, s[4:5] offset:64
	global_load_dwordx4 v[94:97], v217, s[4:5] offset:96
	s_add_i32 s27, s22, 0
	s_min_i32 s27, s27, 0xff
	s_mul_i32 s27, s27, 0x60000
	v_add_u32_e32 v223, s27, v231
	global_load_dwordx4 v[146:149], v223, s[34:35]
	global_load_dwordx4 v[150:153], v223, s[36:37]
	s_add_i32 s27, s22, 1
	s_min_i32 s27, s27, 0xff
	s_mul_i32 s27, s27, 0x60000
	v_add_u32_e32 v224, s27, v231
	global_load_dwordx4 v[154:157], v224, s[34:35]
	global_load_dwordx4 v[158:161], v224, s[36:37]
	s_add_i32 s27, s22, 2
	s_min_i32 s27, s27, 0xff
	s_mul_i32 s27, s27, 0x60000
	v_add_u32_e32 v225, s27, v231
	global_load_dwordx4 v[162:165], v225, s[34:35]
	global_load_dwordx4 v[166:169], v225, s[36:37]
	s_add_i32 s27, s22, 3
	s_min_i32 s27, s27, 0xff
	s_mul_i32 s27, s27, 0x60000
	v_add_u32_e32 v226, s27, v231
	global_load_dwordx4 v[170:173], v226, s[34:35]
	global_load_dwordx4 v[174:177], v226, s[36:37]
	s_add_i32 s27, s22, 4
	s_min_i32 s27, s27, 0xff
	s_mul_i32 s27, s27, 0x60000
	v_add_u32_e32 v227, s27, v231
	global_load_dwordx4 v[178:181], v227, s[34:35]
	global_load_dwordx4 v[182:185], v227, s[36:37]
	s_add_i32 s27, s22, 5
	s_min_i32 s27, s27, 0xff
	s_mul_i32 s27, s27, 0x60000
	v_add_u32_e32 v228, s27, v231
	global_load_dwordx4 v[186:189], v228, s[34:35]
	global_load_dwordx4 v[190:193], v228, s[36:37]
	global_load_dword v194, v247, s[38:39]
	global_load_dword v195, v248, s[38:39]
.Lna_unit:
	s_lshr_b32 s54, s21, 6
	s_and_b32 s55, s21, 63
	s_lshr_b32 s56, s54, 4
	s_and_b32 s57, s54, 15
	s_lshl_b32 s58, s55, 2
	s_add_i32 s59, s58, -4
	s_max_i32 s59, s59, 0
	s_min_i32 s59, s59, 0xf8
	s_lshl_b32 s25, s30, 1
	s_add_i32 s25, s25, s58
	s_add_i32 s23, s25, -4
	s_max_i32 s23, s23, 0
	s_min_i32 s23, s23, 0xf8
	s_sub_i32 s24, s23, s59
	s_lshl_b32 s60, s56, 25
	s_lshl_b32 s61, s57, 7
	s_add_i32 s60, s60, s61
	s_add_u32 s16, s94, 0x17800000
	s_addc_u32 s17, s95, 0
	s_add_u32 s16, s16, s60
	s_addc_u32 s17, s17, 0
	v_lshrrev_b32_e32 v206, 4, v196
	v_add_u32_e32 v206, s25, v206
	v_add_u32_e32 v207, -4, v206
	v_med3_i32 v207, v207, 0, s18
	v_lshl_add_u32 v208, v206, 6, v198
	v_mov_b32_e32 v209, 0xf149f2ca
	s_waitcnt vmcnt(0)
	v_mul_f32_e32 v194, s13, v194
	v_cmp_eq_u32_e32 vcc, 1, v249
	s_nop 1
	v_cndmask_b32_e32 v194, 0, v194, vcc
	v_cmp_eq_u32_e32 vcc, 2, v249
	s_nop 1
	v_cndmask_b32_e32 v194, v194, v229, vcc
	v_mul_f32_e32 v195, s13, v195
	v_cmp_eq_u32_e32 vcc, 1, v250
	s_nop 1
	v_cndmask_b32_e32 v195, 0, v195, vcc
	v_cmp_eq_u32_e32 vcc, 2, v250
	s_nop 1
	v_cndmask_b32_e32 v195, v195, v229, vcc
	s_barrier
	ds_write_b128 v202, v[146:149]
	ds_write_b128 v202, v[150:153] offset:9216
	ds_write_b128 v202, v[154:157] offset:18432
	ds_write_b128 v202, v[158:161] offset:27648
	ds_write_b128 v202, v[162:165] offset:36864
	ds_write_b128 v202, v[166:169] offset:46080
	ds_write_b128 v203, v[170:173]
	ds_write_b128 v203, v[174:177] offset:9216
	ds_write_b128 v203, v[178:181] offset:18432
	ds_write_b128 v203, v[182:185] offset:27648
	ds_write_b128 v203, v[186:189] offset:36864
	ds_write_b128 v203, v[190:193] offset:46080
	ds_write_b32 v245, v194
	ds_write_b32 v246, v195
	s_waitcnt lgkmcnt(0)
	s_barrier
	s_add_i32 s27, s22, 6
	s_min_i32 s27, s27, 0xff
	s_mul_i32 s27, s27, 0x60000
	v_add_u32_e32 v223, s27, v231
	global_load_dwordx4 v[146:149], v223, s[34:35]
	global_load_dwordx4 v[150:153], v223, s[36:37]
	s_add_i32 s27, s22, 7
	s_min_i32 s27, s27, 0xff
	s_mul_i32 s27, s27, 0x60000
	v_add_u32_e32 v224, s27, v231
	global_load_dwordx4 v[154:157], v224, s[34:35]
	global_load_dwordx4 v[158:161], v224, s[36:37]
	s_add_i32 s27, s22, 8
	s_min_i32 s27, s27, 0xff
	s_mul_i32 s27, s27, 0x60000
	v_add_u32_e32 v225, s27, v231
	global_load_dwordx4 v[162:165], v225, s[34:35]
	global_load_dwordx4 v[166:169], v225, s[36:37]
	s_add_i32 s27, s22, 9
	s_min_i32 s27, s27, 0xff
	s_mul_i32 s27, s27, 0x60000
	v_add_u32_e32 v226, s27, v231
	global_load_dwordx4 v[170:173], v226, s[34:35]
	global_load_dwordx4 v[174:177], v226, s[36:37]
	s_add_i32 s27, s22, 10
	s_min_i32 s27, s27, 0xff
	s_mul_i32 s27, s27, 0x60000
	v_add_u32_e32 v227, s27, v231
	global_load_dwordx4 v[178:181], v227, s[34:35]
	global_load_dwordx4 v[182:185], v227, s[36:37]
	s_cmp_lg_u32 s24, 0
	s_cbranch_scc1 .Lna_p1_d2
	s_nop 7
	s_nop 4
	ds_read_b128 v[114:117], v200
	ds_read_b128 v[118:121], v200 offset:32
	ds_read_b128 v[122:125], v200 offset:64
	ds_read_b128 v[126:129], v200 offset:96
	ds_read_b128 v[130:133], v200 offset:18432
	ds_read_b128 v[134:137], v200 offset:18464
	ds_read_b128 v[138:141], v200 offset:18496
	ds_read_b128 v[142:145], v200 offset:18528
	s_waitcnt lgkmcnt(7)
	v_mfma_f32_32x32x16_bf16 v[2:17], v[114:117], v[82:85], v[98:113]
	s_waitcnt lgkmcnt(6)
	v_mfma_f32_32x32x16_bf16 v[2:17], v[118:121], v[86:89], v[2:17]
	s_waitcnt lgkmcnt(5)
	v_mfma_f32_32x32x16_bf16 v[2:17], v[122:125], v[90:93], v[2:17]
	s_waitcnt lgkmcnt(4)
	v_mfma_f32_32x32x16_bf16 v[2:17], v[126:129], v[94:97], v[2:17]
	ds_read_b128 v[114:117], v200 offset:36864
	ds_read_b128 v[118:121], v200 offset:36896
	ds_read_b128 v[122:125], v200 offset:36928
	ds_read_b128 v[126:129], v200 offset:36960
	s_waitcnt lgkmcnt(7)
	v_mfma_f32_32x32x16_bf16 v[18:33], v[130:133], v[82:85], v[98:113]
	s_waitcnt lgkmcnt(6)
	v_mfma_f32_32x32x16_bf16 v[18:33], v[134:137], v[86:89], v[18:33]
	s_waitcnt lgkmcnt(5)
	v_mfma_f32_32x32x16_bf16 v[18:33], v[138:141], v[90:93], v[18:33]
	s_waitcnt lgkmcnt(4)
	v_mfma_f32_32x32x16_bf16 v[18:33], v[142:145], v[94:97], v[18:33]
	s_waitcnt lgkmcnt(3)
	v_mfma_f32_32x32x16_bf16 v[34:49], v[114:117], v[82:85], v[98:113]
	s_waitcnt lgkmcnt(2)
	v_mfma_f32_32x32x16_bf16 v[34:49], v[118:121], v[86:89], v[34:49]
	s_waitcnt lgkmcnt(1)
	v_mfma_f32_32x32x16_bf16 v[34:49], v[122:125], v[90:93], v[34:49]
	s_waitcnt lgkmcnt(0)
	v_mfma_f32_32x32x16_bf16 v[34:49], v[126:129], v[94:97], v[34:49]
	s_add_i32 s62, s23, 0
	s_add_i32 s63, s62, 7
	v_sub_u32_e32 v217, s63, v206
	v_med3_i32 v217, v217, 0, 14
	v_mul_u32_u24_e32 v217, 31, v217
	v_add_u32_e32 v217, v217, v199
	v_lshlrev_b32_e32 v217, 2, v217
	v_add_u32_e32 v217, 110848, v217
	v_sub_u32_e32 v218, s62, v207
	v_cmp_gt_u32_e64 s[40:41], 8, v218
	s_nop 1
	v_cndmask_b32_e64 v230, v244, v217, s[40:41]
	ds_read2_b32 v[114:115], v230 offset0:0 offset1:1
	ds_read2_b32 v[116:117], v230 offset0:2 offset1:3
	ds_read2_b32 v[118:119], v230 offset0:4 offset1:5
	ds_read2_b32 v[120:121], v230 offset0:6 offset1:7
	ds_read2_b32 v[122:123], v230 offset0:16 offset1:17
	ds_read2_b32 v[124:125], v230 offset0:18 offset1:19
	ds_read2_b32 v[126:127], v230 offset0:20 offset1:21
	ds_read2_b32 v[128:129], v230 offset0:22 offset1:23
	s_waitcnt lgkmcnt(7)
	v_fma_f32 v2, v2, s14, v114
	v_fma_f32 v3, v3, s14, v115
	s_waitcnt lgkmcnt(6)
	v_fma_f32 v4, v4, s14, v116
	v_fma_f32 v5, v5, s14, v117
	s_waitcnt lgkmcnt(5)
	v_fma_f32 v6, v6, s14, v118
	v_fma_f32 v7, v7, s14, v119
	s_waitcnt lgkmcnt(4)
	v_fma_f32 v8, v8, s14, v120
	v_fma_f32 v9, v9, s14, v121
	s_waitcnt lgkmcnt(3)
	v_fma_f32 v10, v10, s14, v122
	v_fma_f32 v11, v11, s14, v123
	s_waitcnt lgkmcnt(2)
	v_fma_f32 v12, v12, s14, v124
	v_fma_f32 v13, v13, s14, v125
	s_waitcnt lgkmcnt(1)
	v_fma_f32 v14, v14, s14, v126
	v_fma_f32 v15, v15, s14, v127
	s_waitcnt lgkmcnt(0)
	v_fma_f32 v16, v16, s14, v128
	v_fma_f32 v17, v17, s14, v129
	s_add_i32 s62, s23, 1
	s_add_i32 s63, s62, 7
	v_sub_u32_e32 v217, s63, v206
	v_med3_i32 v217, v217, 0, 14
	v_mul_u32_u24_e32 v217, 31, v217
	v_add_u32_e32 v217, v217, v199
	v_lshlrev_b32_e32 v217, 2, v217
	v_add_u32_e32 v217, 110848, v217
	v_sub_u32_e32 v218, s62, v207
	v_cmp_gt_u32_e64 s[40:41], 8, v218
	s_nop 1
	v_cndmask_b32_e64 v230, v244, v217, s[40:41]
	ds_read2_b32 v[130:131], v230 offset0:0 offset1:1
	ds_read2_b32 v[132:133], v230 offset0:2 offset1:3
	ds_read2_b32 v[134:135], v230 offset0:4 offset1:5
	ds_read2_b32 v[136:137], v230 offset0:6 offset1:7
	ds_read2_b32 v[138:139], v230 offset0:16 offset1:17
	ds_read2_b32 v[140:141], v230 offset0:18 offset1:19
	ds_read2_b32 v[142:143], v230 offset0:20 offset1:21
	ds_read2_b32 v[144:145], v230 offset0:22 offset1:23
	s_waitcnt lgkmcnt(7)
	v_fma_f32 v18, v18, s14, v130
	v_fma_f32 v19, v19, s14, v131
	s_waitcnt lgkmcnt(6)
	v_fma_f32 v20, v20, s14, v132
	v_fma_f32 v21, v21, s14, v133
	s_waitcnt lgkmcnt(5)
	v_fma_f32 v22, v22, s14, v134
	v_fma_f32 v23, v23, s14, v135
	s_waitcnt lgkmcnt(4)
	v_fma_f32 v24, v24, s14, v136
	v_fma_f32 v25, v25, s14, v137
	s_waitcnt lgkmcnt(3)
	v_fma_f32 v26, v26, s14, v138
	v_fma_f32 v27, v27, s14, v139
	s_waitcnt lgkmcnt(2)
	v_fma_f32 v28, v28, s14, v140
	v_fma_f32 v29, v29, s14, v141
	s_waitcnt lgkmcnt(1)
	v_fma_f32 v30, v30, s14, v142
	v_fma_f32 v31, v31, s14, v143
	s_waitcnt lgkmcnt(0)
	v_fma_f32 v32, v32, s14, v144
	v_fma_f32 v33, v33, s14, v145
	s_add_i32 s62, s23, 2
	s_add_i32 s63, s62, 7
	v_sub_u32_e32 v217, s63, v206
	v_med3_i32 v217, v217, 0, 14
	v_mul_u32_u24_e32 v217, 31, v217
	v_add_u32_e32 v217, v217, v199
	v_lshlrev_b32_e32 v217, 2, v217
	v_add_u32_e32 v217, 110848, v217
	v_sub_u32_e32 v218, s62, v207
	v_cmp_gt_u32_e64 s[40:41], 8, v218
	s_nop 1
	v_cndmask_b32_e64 v230, v244, v217, s[40:41]
	ds_read2_b32 v[114:115], v230 offset0:0 offset1:1
	ds_read2_b32 v[116:117], v230 offset0:2 offset1:3
	ds_read2_b32 v[118:119], v230 offset0:4 offset1:5
	ds_read2_b32 v[120:121], v230 offset0:6 offset1:7
	ds_read2_b32 v[122:123], v230 offset0:16 offset1:17
	ds_read2_b32 v[124:125], v230 offset0:18 offset1:19
	ds_read2_b32 v[126:127], v230 offset0:20 offset1:21
	ds_read2_b32 v[128:129], v230 offset0:22 offset1:23
	s_waitcnt lgkmcnt(7)
	v_fma_f32 v34, v34, s14, v114
	v_fma_f32 v35, v35, s14, v115
	s_waitcnt lgkmcnt(6)
	v_fma_f32 v36, v36, s14, v116
	v_fma_f32 v37, v37, s14, v117
	s_waitcnt lgkmcnt(5)
	v_fma_f32 v38, v38, s14, v118
	v_fma_f32 v39, v39, s14, v119
	s_waitcnt lgkmcnt(4)
	v_fma_f32 v40, v40, s14, v120
	v_fma_f32 v41, v41, s14, v121
	s_waitcnt lgkmcnt(3)
	v_fma_f32 v42, v42, s14, v122
	v_fma_f32 v43, v43, s14, v123
	s_waitcnt lgkmcnt(2)
	v_fma_f32 v44, v44, s14, v124
	v_fma_f32 v45, v45, s14, v125
	s_waitcnt lgkmcnt(1)
	v_fma_f32 v46, v46, s14, v126
	v_fma_f32 v47, v47, s14, v127
	s_waitcnt lgkmcnt(0)
	v_fma_f32 v48, v48, s14, v128
	v_fma_f32 v49, v49, s14, v129
	v_max3_f32 v210, v2, v3, v4
	v_max3_f32 v219, v5, v6, v7
	v_max3_f32 v210, v210, v8, v9
	v_max3_f32 v219, v219, v10, v11
	v_max3_f32 v210, v210, v12, v13
	v_max3_f32 v219, v219, v14, v15
	v_max3_f32 v210, v210, v16, v17
	v_max3_f32 v219, v219, v18, v19
	v_max3_f32 v210, v210, v20, v21
	v_max3_f32 v219, v219, v22, v23
	v_max3_f32 v210, v210, v24, v25
	v_max3_f32 v219, v219, v26, v27
	v_max3_f32 v210, v210, v28, v29
	v_max3_f32 v219, v219, v30, v31
	v_max3_f32 v210, v210, v32, v33
	v_max3_f32 v219, v219, v34, v35
	v_max3_f32 v210, v210, v36, v37
	v_max3_f32 v219, v219, v38, v39
	v_max3_f32 v210, v210, v40, v41
	v_max3_f32 v219, v219, v42, v43
	v_max3_f32 v210, v210, v44, v45
	v_max3_f32 v219, v219, v46, v47
	v_max3_f32 v210, v210, v48, v49
	v_max_f32_e32 v210, v210, v219
	v_mov_b32_e32 v219, v210
	s_nop 1
	v_permlane32_swap_b32_e32 v210, v219
	v_max_f32_e32 v210, v210, v219
	v_max_f32_e32 v210, v210, v209
	v_mov_b32_e32 v209, v210
	v_mov_b32_e32 v213, 0
	v_mov_b32_e32 v214, 0
	v_mov_b32_e32 v215, 0
	v_mov_b32_e32 v216, 0
	v_sub_f32_e32 v2, v2, v209
	v_sub_f32_e32 v3, v3, v209
	v_exp_f32_e32 v2, v2
	v_exp_f32_e32 v3, v3
	v_add_f32_e32 v213, v213, v2
	v_add_f32_e32 v214, v214, v3
	v_cvt_pk_bf16_f32 v2, v2, v3
	v_sub_f32_e32 v4, v4, v209
	v_sub_f32_e32 v5, v5, v209
	v_exp_f32_e32 v4, v4
	v_exp_f32_e32 v5, v5
	v_add_f32_e32 v215, v215, v4
	v_add_f32_e32 v216, v216, v5
	v_cvt_pk_bf16_f32 v3, v4, v5
	v_sub_f32_e32 v6, v6, v209
	v_sub_f32_e32 v7, v7, v209
	v_exp_f32_e32 v6, v6
	v_exp_f32_e32 v7, v7
	v_add_f32_e32 v213, v213, v6
	v_add_f32_e32 v214, v214, v7
	v_cvt_pk_bf16_f32 v4, v6, v7
	v_sub_f32_e32 v8, v8, v209
	v_sub_f32_e32 v9, v9, v209
	v_exp_f32_e32 v8, v8
	v_exp_f32_e32 v9, v9
	v_add_f32_e32 v215, v215, v8
	v_add_f32_e32 v216, v216, v9
	v_cvt_pk_bf16_f32 v5, v8, v9
	v_sub_f32_e32 v10, v10, v209
	v_sub_f32_e32 v11, v11, v209
	v_exp_f32_e32 v10, v10
	v_exp_f32_e32 v11, v11
	v_add_f32_e32 v213, v213, v10
	v_add_f32_e32 v214, v214, v11
	v_cvt_pk_bf16_f32 v10, v10, v11
	v_sub_f32_e32 v12, v12, v209
	v_sub_f32_e32 v13, v13, v209
	v_exp_f32_e32 v12, v12
	v_exp_f32_e32 v13, v13
	v_add_f32_e32 v215, v215, v12
	v_add_f32_e32 v216, v216, v13
	v_cvt_pk_bf16_f32 v11, v12, v13
	v_sub_f32_e32 v14, v14, v209
	v_sub_f32_e32 v15, v15, v209
	v_exp_f32_e32 v14, v14
	v_exp_f32_e32 v15, v15
	v_add_f32_e32 v213, v213, v14
	v_add_f32_e32 v214, v214, v15
	v_cvt_pk_bf16_f32 v12, v14, v15
	v_sub_f32_e32 v16, v16, v209
	v_sub_f32_e32 v17, v17, v209
	v_exp_f32_e32 v16, v16
	v_exp_f32_e32 v17, v17
	v_add_f32_e32 v215, v215, v16
	v_add_f32_e32 v216, v216, v17
	v_cvt_pk_bf16_f32 v13, v16, v17
	v_sub_f32_e32 v18, v18, v209
	v_sub_f32_e32 v19, v19, v209
	v_exp_f32_e32 v18, v18
	v_exp_f32_e32 v19, v19
	v_add_f32_e32 v213, v213, v18
	v_add_f32_e32 v214, v214, v19
	v_cvt_pk_bf16_f32 v18, v18, v19
	v_sub_f32_e32 v20, v20, v209
	v_sub_f32_e32 v21, v21, v209
	v_exp_f32_e32 v20, v20
	v_exp_f32_e32 v21, v21
	v_add_f32_e32 v215, v215, v20
	v_add_f32_e32 v216, v216, v21
	v_cvt_pk_bf16_f32 v19, v20, v21
	v_sub_f32_e32 v22, v22, v209
	v_sub_f32_e32 v23, v23, v209
	v_exp_f32_e32 v22, v22
	v_exp_f32_e32 v23, v23
	v_add_f32_e32 v213, v213, v22
	v_add_f32_e32 v214, v214, v23
	v_cvt_pk_bf16_f32 v20, v22, v23
	v_sub_f32_e32 v24, v24, v209
	v_sub_f32_e32 v25, v25, v209
	v_exp_f32_e32 v24, v24
	v_exp_f32_e32 v25, v25
	v_add_f32_e32 v215, v215, v24
	v_add_f32_e32 v216, v216, v25
	v_cvt_pk_bf16_f32 v21, v24, v25
	v_sub_f32_e32 v26, v26, v209
	v_sub_f32_e32 v27, v27, v209
	v_exp_f32_e32 v26, v26
	v_exp_f32_e32 v27, v27
	v_add_f32_e32 v213, v213, v26
	v_add_f32_e32 v214, v214, v27
	v_cvt_pk_bf16_f32 v26, v26, v27
	v_sub_f32_e32 v28, v28, v209
	v_sub_f32_e32 v29, v29, v209
	v_exp_f32_e32 v28, v28
	v_exp_f32_e32 v29, v29
	v_add_f32_e32 v215, v215, v28
	v_add_f32_e32 v216, v216, v29
	v_cvt_pk_bf16_f32 v27, v28, v29
	v_sub_f32_e32 v30, v30, v209
	v_sub_f32_e32 v31, v31, v209
	v_exp_f32_e32 v30, v30
	v_exp_f32_e32 v31, v31
	v_add_f32_e32 v213, v213, v30
	v_add_f32_e32 v214, v214, v31
	v_cvt_pk_bf16_f32 v28, v30, v31
	v_sub_f32_e32 v32, v32, v209
	v_sub_f32_e32 v33, v33, v209
	v_exp_f32_e32 v32, v32
	v_exp_f32_e32 v33, v33
	v_add_f32_e32 v215, v215, v32
	v_add_f32_e32 v216, v216, v33
	v_cvt_pk_bf16_f32 v29, v32, v33
	v_sub_f32_e32 v34, v34, v209
	v_sub_f32_e32 v35, v35, v209
	v_exp_f32_e32 v34, v34
	v_exp_f32_e32 v35, v35
	v_add_f32_e32 v213, v213, v34
	v_add_f32_e32 v214, v214, v35
	v_cvt_pk_bf16_f32 v34, v34, v35
	v_sub_f32_e32 v36, v36, v209
	v_sub_f32_e32 v37, v37, v209
	v_exp_f32_e32 v36, v36
	v_exp_f32_e32 v37, v37
	v_add_f32_e32 v215, v215, v36
	v_add_f32_e32 v216, v216, v37
	v_cvt_pk_bf16_f32 v35, v36, v37
	v_sub_f32_e32 v38, v38, v209
	v_sub_f32_e32 v39, v39, v209
	v_exp_f32_e32 v38, v38
	v_exp_f32_e32 v39, v39
	v_add_f32_e32 v213, v213, v38
	v_add_f32_e32 v214, v214, v39
	v_cvt_pk_bf16_f32 v36, v38, v39
	v_sub_f32_e32 v40, v40, v209
	v_sub_f32_e32 v41, v41, v209
	v_exp_f32_e32 v40, v40
	v_exp_f32_e32 v41, v41
	v_add_f32_e32 v215, v215, v40
	v_add_f32_e32 v216, v216, v41
	v_cvt_pk_bf16_f32 v37, v40, v41
	v_sub_f32_e32 v42, v42, v209
	v_sub_f32_e32 v43, v43, v209
	v_exp_f32_e32 v42, v42
	v_exp_f32_e32 v43, v43
	v_add_f32_e32 v213, v213, v42
	v_add_f32_e32 v214, v214, v43
	v_cvt_pk_bf16_f32 v42, v42, v43
	v_sub_f32_e32 v44, v44, v209
	v_sub_f32_e32 v45, v45, v209
	v_exp_f32_e32 v44, v44
	v_exp_f32_e32 v45, v45
	v_add_f32_e32 v215, v215, v44
	v_add_f32_e32 v216, v216, v45
	v_cvt_pk_bf16_f32 v43, v44, v45
	v_sub_f32_e32 v46, v46, v209
	v_sub_f32_e32 v47, v47, v209
	v_exp_f32_e32 v46, v46
	v_exp_f32_e32 v47, v47
	v_add_f32_e32 v213, v213, v46
	v_add_f32_e32 v214, v214, v47
	v_cvt_pk_bf16_f32 v44, v46, v47
	v_sub_f32_e32 v48, v48, v209
	v_sub_f32_e32 v49, v49, v209
	v_exp_f32_e32 v48, v48
	v_exp_f32_e32 v49, v49
	v_add_f32_e32 v215, v215, v48
	v_add_f32_e32 v216, v216, v49
	v_cvt_pk_bf16_f32 v45, v48, v49
	v_add_f32_e32 v213, v213, v214
	v_add_f32_e32 v215, v215, v216
	v_add_f32_e32 v213, v213, v215
	v_mov_b32_e32 v212, v213
	ds_read_b64_tr_b16 v[114:115], v201 offset:9216
	ds_read_b64_tr_b16 v[116:117], v201 offset:9792
	ds_read_b64_tr_b16 v[118:119], v201 offset:9280
	ds_read_b64_tr_b16 v[120:121], v201 offset:9856
	ds_read_b64_tr_b16 v[122:123], v201 offset:11520
	ds_read_b64_tr_b16 v[124:125], v201 offset:12096
	ds_read_b64_tr_b16 v[126:127], v201 offset:11584
	ds_read_b64_tr_b16 v[128:129], v201 offset:12160
	ds_read_b64_tr_b16 v[130:131], v201 offset:27648
	ds_read_b64_tr_b16 v[132:133], v201 offset:28224
	ds_read_b64_tr_b16 v[134:135], v201 offset:27712
	ds_read_b64_tr_b16 v[136:137], v201 offset:28288
	s_waitcnt lgkmcnt(10)
	v_mfma_f32_32x32x16_bf16 v[50:65], v[114:117], v[2:5], 0
	s_waitcnt lgkmcnt(8)
	v_mfma_f32_32x32x16_bf16 v[66:81], v[118:121], v[2:5], 0
	ds_read_b64_tr_b16 v[138:139], v201 offset:29952
	ds_read_b64_tr_b16 v[140:141], v201 offset:30528
	ds_read_b64_tr_b16 v[142:143], v201 offset:30016
	ds_read_b64_tr_b16 v[144:145], v201 offset:30592
	s_waitcnt lgkmcnt(10)
	v_mfma_f32_32x32x16_bf16 v[50:65], v[122:125], v[10:13], v[50:65]
	s_waitcnt lgkmcnt(8)
	v_mfma_f32_32x32x16_bf16 v[66:81], v[126:129], v[10:13], v[66:81]
	ds_read_b64_tr_b16 v[114:115], v201 offset:46080
	ds_read_b64_tr_b16 v[116:117], v201 offset:46656
	ds_read_b64_tr_b16 v[118:119], v201 offset:46144
	ds_read_b64_tr_b16 v[120:121], v201 offset:46720
	s_waitcnt lgkmcnt(10)
	v_mfma_f32_32x32x16_bf16 v[50:65], v[130:133], v[18:21], v[50:65]
	s_waitcnt lgkmcnt(8)
	v_mfma_f32_32x32x16_bf16 v[66:81], v[134:137], v[18:21], v[66:81]
	ds_read_b64_tr_b16 v[122:123], v201 offset:48384
	ds_read_b64_tr_b16 v[124:125], v201 offset:48960
	ds_read_b64_tr_b16 v[126:127], v201 offset:48448
	ds_read_b64_tr_b16 v[128:129], v201 offset:49024
	s_waitcnt lgkmcnt(10)
	v_mfma_f32_32x32x16_bf16 v[50:65], v[138:141], v[26:29], v[50:65]
	s_waitcnt lgkmcnt(8)
	v_mfma_f32_32x32x16_bf16 v[66:81], v[142:145], v[26:29], v[66:81]
	s_waitcnt lgkmcnt(6)
	v_mfma_f32_32x32x16_bf16 v[50:65], v[114:117], v[34:37], v[50:65]
	s_waitcnt lgkmcnt(4)
	v_mfma_f32_32x32x16_bf16 v[66:81], v[118:121], v[34:37], v[66:81]
	s_waitcnt lgkmcnt(2)
	v_mfma_f32_32x32x16_bf16 v[50:65], v[122:125], v[42:45], v[50:65]
	s_waitcnt lgkmcnt(0)
	v_mfma_f32_32x32x16_bf16 v[66:81], v[126:129], v[42:45], v[66:81]
	s_nop 7
	s_nop 4
	ds_read_b128 v[114:117], v242
	ds_read_b128 v[118:121], v242 offset:32
	ds_read_b128 v[122:125], v242 offset:64
	ds_read_b128 v[126:129], v242 offset:96
	ds_read_b128 v[130:133], v242 offset:18432
	ds_read_b128 v[134:137], v242 offset:18464
	ds_read_b128 v[138:141], v242 offset:18496
	ds_read_b128 v[142:145], v242 offset:18528
	s_waitcnt lgkmcnt(7)
	v_mfma_f32_32x32x16_bf16 v[2:17], v[114:117], v[82:85], v[98:113]
	s_waitcnt lgkmcnt(6)
	v_mfma_f32_32x32x16_bf16 v[2:17], v[118:121], v[86:89], v[2:17]
	s_waitcnt lgkmcnt(5)
	v_mfma_f32_32x32x16_bf16 v[2:17], v[122:125], v[90:93], v[2:17]
	s_waitcnt lgkmcnt(4)
	v_mfma_f32_32x32x16_bf16 v[2:17], v[126:129], v[94:97], v[2:17]
	ds_read_b128 v[114:117], v242 offset:36864
	ds_read_b128 v[118:121], v242 offset:36896
	ds_read_b128 v[122:125], v242 offset:36928
	ds_read_b128 v[126:129], v242 offset:36960
	s_waitcnt lgkmcnt(7)
	v_mfma_f32_32x32x16_bf16 v[18:33], v[130:133], v[82:85], v[98:113]
	s_waitcnt lgkmcnt(6)
	v_mfma_f32_32x32x16_bf16 v[18:33], v[134:137], v[86:89], v[18:33]
	s_waitcnt lgkmcnt(5)
	v_mfma_f32_32x32x16_bf16 v[18:33], v[138:141], v[90:93], v[18:33]
	s_waitcnt lgkmcnt(4)
	v_mfma_f32_32x32x16_bf16 v[18:33], v[142:145], v[94:97], v[18:33]
	s_waitcnt lgkmcnt(3)
	v_mfma_f32_32x32x16_bf16 v[34:49], v[114:117], v[82:85], v[98:113]
	s_waitcnt lgkmcnt(2)
	v_mfma_f32_32x32x16_bf16 v[34:49], v[118:121], v[86:89], v[34:49]
	s_waitcnt lgkmcnt(1)
	v_mfma_f32_32x32x16_bf16 v[34:49], v[122:125], v[90:93], v[34:49]
	s_waitcnt lgkmcnt(0)
	v_mfma_f32_32x32x16_bf16 v[34:49], v[126:129], v[94:97], v[34:49]
	s_add_i32 s62, s23, 3
	s_add_i32 s63, s62, 7
	v_sub_u32_e32 v217, s63, v206
	v_med3_i32 v217, v217, 0, 14
	v_mul_u32_u24_e32 v217, 31, v217
	v_add_u32_e32 v217, v217, v199
	v_lshlrev_b32_e32 v217, 2, v217
	v_add_u32_e32 v217, 110848, v217
	v_sub_u32_e32 v218, s62, v207
	v_cmp_gt_u32_e64 s[40:41], 8, v218
	s_nop 1
	v_cndmask_b32_e64 v230, v244, v217, s[40:41]
	ds_read2_b32 v[114:115], v230 offset0:0 offset1:1
	ds_read2_b32 v[116:117], v230 offset0:2 offset1:3
	ds_read2_b32 v[118:119], v230 offset0:4 offset1:5
	ds_read2_b32 v[120:121], v230 offset0:6 offset1:7
	ds_read2_b32 v[122:123], v230 offset0:16 offset1:17
	ds_read2_b32 v[124:125], v230 offset0:18 offset1:19
	ds_read2_b32 v[126:127], v230 offset0:20 offset1:21
	ds_read2_b32 v[128:129], v230 offset0:22 offset1:23
	s_waitcnt lgkmcnt(7)
	v_fma_f32 v2, v2, s14, v114
	v_fma_f32 v3, v3, s14, v115
	s_waitcnt lgkmcnt(6)
	v_fma_f32 v4, v4, s14, v116
	v_fma_f32 v5, v5, s14, v117
	s_waitcnt lgkmcnt(5)
	v_fma_f32 v6, v6, s14, v118
	v_fma_f32 v7, v7, s14, v119
	s_waitcnt lgkmcnt(4)
	v_fma_f32 v8, v8, s14, v120
	v_fma_f32 v9, v9, s14, v121
	s_waitcnt lgkmcnt(3)
	v_fma_f32 v10, v10, s14, v122
	v_fma_f32 v11, v11, s14, v123
	s_waitcnt lgkmcnt(2)
	v_fma_f32 v12, v12, s14, v124
	v_fma_f32 v13, v13, s14, v125
	s_waitcnt lgkmcnt(1)
	v_fma_f32 v14, v14, s14, v126
	v_fma_f32 v15, v15, s14, v127
	s_waitcnt lgkmcnt(0)
	v_fma_f32 v16, v16, s14, v128
	v_fma_f32 v17, v17, s14, v129
	s_add_i32 s62, s23, 4
	s_add_i32 s63, s62, 7
	v_sub_u32_e32 v217, s63, v206
	v_med3_i32 v217, v217, 0, 14
	v_mul_u32_u24_e32 v217, 31, v217
	v_add_u32_e32 v217, v217, v199
	v_lshlrev_b32_e32 v217, 2, v217
	v_add_u32_e32 v217, 110848, v217
	v_sub_u32_e32 v218, s62, v207
	v_cmp_gt_u32_e64 s[40:41], 8, v218
	s_nop 1
	v_cndmask_b32_e64 v230, v244, v217, s[40:41]
	ds_read2_b32 v[130:131], v230 offset0:0 offset1:1
	ds_read2_b32 v[132:133], v230 offset0:2 offset1:3
	ds_read2_b32 v[134:135], v230 offset0:4 offset1:5
	ds_read2_b32 v[136:137], v230 offset0:6 offset1:7
	ds_read2_b32 v[138:139], v230 offset0:16 offset1:17
	ds_read2_b32 v[140:141], v230 offset0:18 offset1:19
	ds_read2_b32 v[142:143], v230 offset0:20 offset1:21
	ds_read2_b32 v[144:145], v230 offset0:22 offset1:23
	s_waitcnt lgkmcnt(7)
	v_fma_f32 v18, v18, s14, v130
	v_fma_f32 v19, v19, s14, v131
	s_waitcnt lgkmcnt(6)
	v_fma_f32 v20, v20, s14, v132
	v_fma_f32 v21, v21, s14, v133
	s_waitcnt lgkmcnt(5)
	v_fma_f32 v22, v22, s14, v134
	v_fma_f32 v23, v23, s14, v135
	s_waitcnt lgkmcnt(4)
	v_fma_f32 v24, v24, s14, v136
	v_fma_f32 v25, v25, s14, v137
	s_waitcnt lgkmcnt(3)
	v_fma_f32 v26, v26, s14, v138
	v_fma_f32 v27, v27, s14, v139
	s_waitcnt lgkmcnt(2)
	v_fma_f32 v28, v28, s14, v140
	v_fma_f32 v29, v29, s14, v141
	s_waitcnt lgkmcnt(1)
	v_fma_f32 v30, v30, s14, v142
	v_fma_f32 v31, v31, s14, v143
	s_waitcnt lgkmcnt(0)
	v_fma_f32 v32, v32, s14, v144
	v_fma_f32 v33, v33, s14, v145
	s_add_i32 s62, s23, 5
	s_add_i32 s63, s62, 7
	v_sub_u32_e32 v217, s63, v206
	v_med3_i32 v217, v217, 0, 14
	v_mul_u32_u24_e32 v217, 31, v217
	v_add_u32_e32 v217, v217, v199
	v_lshlrev_b32_e32 v217, 2, v217
	v_add_u32_e32 v217, 110848, v217
	v_sub_u32_e32 v218, s62, v207
	v_cmp_gt_u32_e64 s[40:41], 8, v218
	s_nop 1
	v_cndmask_b32_e64 v230, v244, v217, s[40:41]
	ds_read2_b32 v[114:115], v230 offset0:0 offset1:1
	ds_read2_b32 v[116:117], v230 offset0:2 offset1:3
	ds_read2_b32 v[118:119], v230 offset0:4 offset1:5
	ds_read2_b32 v[120:121], v230 offset0:6 offset1:7
	ds_read2_b32 v[122:123], v230 offset0:16 offset1:17
	ds_read2_b32 v[124:125], v230 offset0:18 offset1:19
	ds_read2_b32 v[126:127], v230 offset0:20 offset1:21
	ds_read2_b32 v[128:129], v230 offset0:22 offset1:23
	s_waitcnt lgkmcnt(7)
	v_fma_f32 v34, v34, s14, v114
	v_fma_f32 v35, v35, s14, v115
	s_waitcnt lgkmcnt(6)
	v_fma_f32 v36, v36, s14, v116
	v_fma_f32 v37, v37, s14, v117
	s_waitcnt lgkmcnt(5)
	v_fma_f32 v38, v38, s14, v118
	v_fma_f32 v39, v39, s14, v119
	s_waitcnt lgkmcnt(4)
	v_fma_f32 v40, v40, s14, v120
	v_fma_f32 v41, v41, s14, v121
	s_waitcnt lgkmcnt(3)
	v_fma_f32 v42, v42, s14, v122
	v_fma_f32 v43, v43, s14, v123
	s_waitcnt lgkmcnt(2)
	v_fma_f32 v44, v44, s14, v124
	v_fma_f32 v45, v45, s14, v125
	s_waitcnt lgkmcnt(1)
	v_fma_f32 v46, v46, s14, v126
	v_fma_f32 v47, v47, s14, v127
	s_waitcnt lgkmcnt(0)
	v_fma_f32 v48, v48, s14, v128
	v_fma_f32 v49, v49, s14, v129
	v_max3_f32 v210, v2, v3, v4
	v_max3_f32 v219, v5, v6, v7
	v_max3_f32 v210, v210, v8, v9
	v_max3_f32 v219, v219, v10, v11
	v_max3_f32 v210, v210, v12, v13
	v_max3_f32 v219, v219, v14, v15
	v_max3_f32 v210, v210, v16, v17
	v_max3_f32 v219, v219, v18, v19
	v_max3_f32 v210, v210, v20, v21
	v_max3_f32 v219, v219, v22, v23
	v_max3_f32 v210, v210, v24, v25
	v_max3_f32 v219, v219, v26, v27
	v_max3_f32 v210, v210, v28, v29
	v_max3_f32 v219, v219, v30, v31
	v_max3_f32 v210, v210, v32, v33
	v_max3_f32 v219, v219, v34, v35
	v_max3_f32 v210, v210, v36, v37
	v_max3_f32 v219, v219, v38, v39
	v_max3_f32 v210, v210, v40, v41
	v_max3_f32 v219, v219, v42, v43
	v_max3_f32 v210, v210, v44, v45
	v_max3_f32 v219, v219, v46, v47
	v_max3_f32 v210, v210, v48, v49
	v_max_f32_e32 v210, v210, v219
	v_mov_b32_e32 v219, v210
	s_nop 1
	v_permlane32_swap_b32_e32 v210, v219
	v_max_f32_e32 v210, v210, v219
	v_max_f32_e32 v210, v210, v209
	v_sub_f32_e32 v211, v209, v210
	v_exp_f32_e32 v211, v211
	v_mov_b32_e32 v209, v210
	v_mul_f32_e32 v50, v50, v211
	v_mul_f32_e32 v51, v51, v211
	v_mul_f32_e32 v52, v52, v211
	v_mul_f32_e32 v53, v53, v211
	v_mul_f32_e32 v54, v54, v211
	v_mul_f32_e32 v55, v55, v211
	v_mul_f32_e32 v56, v56, v211
	v_mul_f32_e32 v57, v57, v211
	v_mul_f32_e32 v58, v58, v211
	v_mul_f32_e32 v59, v59, v211
	v_mul_f32_e32 v60, v60, v211
	v_mul_f32_e32 v61, v61, v211
	v_mul_f32_e32 v62, v62, v211
	v_mul_f32_e32 v63, v63, v211
	v_mul_f32_e32 v64, v64, v211
	v_mul_f32_e32 v65, v65, v211
	v_mul_f32_e32 v66, v66, v211
	v_mul_f32_e32 v67, v67, v211
	v_mul_f32_e32 v68, v68, v211
	v_mul_f32_e32 v69, v69, v211
	v_mul_f32_e32 v70, v70, v211
	v_mul_f32_e32 v71, v71, v211
	v_mul_f32_e32 v72, v72, v211
	v_mul_f32_e32 v73, v73, v211
	v_mul_f32_e32 v74, v74, v211
	v_mul_f32_e32 v75, v75, v211
	v_mul_f32_e32 v76, v76, v211
	v_mul_f32_e32 v77, v77, v211
	v_mul_f32_e32 v78, v78, v211
	v_mul_f32_e32 v79, v79, v211
	v_mul_f32_e32 v80, v80, v211
	v_mul_f32_e32 v81, v81, v211
	v_mul_f32_e32 v212, v212, v211
	v_mov_b32_e32 v213, 0
	v_mov_b32_e32 v214, 0
	v_mov_b32_e32 v215, 0
	v_mov_b32_e32 v216, 0
	v_sub_f32_e32 v2, v2, v209
	v_sub_f32_e32 v3, v3, v209
	v_exp_f32_e32 v2, v2
	v_exp_f32_e32 v3, v3
	v_add_f32_e32 v213, v213, v2
	v_add_f32_e32 v214, v214, v3
	v_cvt_pk_bf16_f32 v2, v2, v3
	v_sub_f32_e32 v4, v4, v209
	v_sub_f32_e32 v5, v5, v209
	v_exp_f32_e32 v4, v4
	v_exp_f32_e32 v5, v5
	v_add_f32_e32 v215, v215, v4
	v_add_f32_e32 v216, v216, v5
	v_cvt_pk_bf16_f32 v3, v4, v5
	v_sub_f32_e32 v6, v6, v209
	v_sub_f32_e32 v7, v7, v209
	v_exp_f32_e32 v6, v6
	v_exp_f32_e32 v7, v7
	v_add_f32_e32 v213, v213, v6
	v_add_f32_e32 v214, v214, v7
	v_cvt_pk_bf16_f32 v4, v6, v7
	v_sub_f32_e32 v8, v8, v209
	v_sub_f32_e32 v9, v9, v209
	v_exp_f32_e32 v8, v8
	v_exp_f32_e32 v9, v9
	v_add_f32_e32 v215, v215, v8
	v_add_f32_e32 v216, v216, v9
	v_cvt_pk_bf16_f32 v5, v8, v9
	v_sub_f32_e32 v10, v10, v209
	v_sub_f32_e32 v11, v11, v209
	v_exp_f32_e32 v10, v10
	v_exp_f32_e32 v11, v11
	v_add_f32_e32 v213, v213, v10
	v_add_f32_e32 v214, v214, v11
	v_cvt_pk_bf16_f32 v10, v10, v11
	v_sub_f32_e32 v12, v12, v209
	v_sub_f32_e32 v13, v13, v209
	v_exp_f32_e32 v12, v12
	v_exp_f32_e32 v13, v13
	v_add_f32_e32 v215, v215, v12
	v_add_f32_e32 v216, v216, v13
	v_cvt_pk_bf16_f32 v11, v12, v13
	v_sub_f32_e32 v14, v14, v209
	v_sub_f32_e32 v15, v15, v209
	v_exp_f32_e32 v14, v14
	v_exp_f32_e32 v15, v15
	v_add_f32_e32 v213, v213, v14
	v_add_f32_e32 v214, v214, v15
	v_cvt_pk_bf16_f32 v12, v14, v15
	v_sub_f32_e32 v16, v16, v209
	v_sub_f32_e32 v17, v17, v209
	v_exp_f32_e32 v16, v16
	v_exp_f32_e32 v17, v17
	v_add_f32_e32 v215, v215, v16
	v_add_f32_e32 v216, v216, v17
	v_cvt_pk_bf16_f32 v13, v16, v17
	v_sub_f32_e32 v18, v18, v209
	v_sub_f32_e32 v19, v19, v209
	v_exp_f32_e32 v18, v18
	v_exp_f32_e32 v19, v19
	v_add_f32_e32 v213, v213, v18
	v_add_f32_e32 v214, v214, v19
	v_cvt_pk_bf16_f32 v18, v18, v19
	v_sub_f32_e32 v20, v20, v209
	v_sub_f32_e32 v21, v21, v209
	v_exp_f32_e32 v20, v20
	v_exp_f32_e32 v21, v21
	v_add_f32_e32 v215, v215, v20
	v_add_f32_e32 v216, v216, v21
	v_cvt_pk_bf16_f32 v19, v20, v21
	v_sub_f32_e32 v22, v22, v209
	v_sub_f32_e32 v23, v23, v209
	v_exp_f32_e32 v22, v22
	v_exp_f32_e32 v23, v23
	v_add_f32_e32 v213, v213, v22
	v_add_f32_e32 v214, v214, v23
	v_cvt_pk_bf16_f32 v20, v22, v23
	v_sub_f32_e32 v24, v24, v209
	v_sub_f32_e32 v25, v25, v209
	v_exp_f32_e32 v24, v24
	v_exp_f32_e32 v25, v25
	v_add_f32_e32 v215, v215, v24
	v_add_f32_e32 v216, v216, v25
	v_cvt_pk_bf16_f32 v21, v24, v25
	v_sub_f32_e32 v26, v26, v209
	v_sub_f32_e32 v27, v27, v209
	v_exp_f32_e32 v26, v26
	v_exp_f32_e32 v27, v27
	v_add_f32_e32 v213, v213, v26
	v_add_f32_e32 v214, v214, v27
	v_cvt_pk_bf16_f32 v26, v26, v27
	v_sub_f32_e32 v28, v28, v209
	v_sub_f32_e32 v29, v29, v209
	v_exp_f32_e32 v28, v28
	v_exp_f32_e32 v29, v29
	v_add_f32_e32 v215, v215, v28
	v_add_f32_e32 v216, v216, v29
	v_cvt_pk_bf16_f32 v27, v28, v29
	v_sub_f32_e32 v30, v30, v209
	v_sub_f32_e32 v31, v31, v209
	v_exp_f32_e32 v30, v30
	v_exp_f32_e32 v31, v31
	v_add_f32_e32 v213, v213, v30
	v_add_f32_e32 v214, v214, v31
	v_cvt_pk_bf16_f32 v28, v30, v31
	v_sub_f32_e32 v32, v32, v209
	v_sub_f32_e32 v33, v33, v209
	v_exp_f32_e32 v32, v32
	v_exp_f32_e32 v33, v33
	v_add_f32_e32 v215, v215, v32
	v_add_f32_e32 v216, v216, v33
	v_cvt_pk_bf16_f32 v29, v32, v33
	v_sub_f32_e32 v34, v34, v209
	v_sub_f32_e32 v35, v35, v209
	v_exp_f32_e32 v34, v34
	v_exp_f32_e32 v35, v35
	v_add_f32_e32 v213, v213, v34
	v_add_f32_e32 v214, v214, v35
	v_cvt_pk_bf16_f32 v34, v34, v35
	v_sub_f32_e32 v36, v36, v209
	v_sub_f32_e32 v37, v37, v209
	v_exp_f32_e32 v36, v36
	v_exp_f32_e32 v37, v37
	v_add_f32_e32 v215, v215, v36
	v_add_f32_e32 v216, v216, v37
	v_cvt_pk_bf16_f32 v35, v36, v37
	v_sub_f32_e32 v38, v38, v209
	v_sub_f32_e32 v39, v39, v209
	v_exp_f32_e32 v38, v38
	v_exp_f32_e32 v39, v39
	v_add_f32_e32 v213, v213, v38
	v_add_f32_e32 v214, v214, v39
	v_cvt_pk_bf16_f32 v36, v38, v39
	v_sub_f32_e32 v40, v40, v209
	v_sub_f32_e32 v41, v41, v209
	v_exp_f32_e32 v40, v40
	v_exp_f32_e32 v41, v41
	v_add_f32_e32 v215, v215, v40
	v_add_f32_e32 v216, v216, v41
	v_cvt_pk_bf16_f32 v37, v40, v41
	v_sub_f32_e32 v42, v42, v209
	v_sub_f32_e32 v43, v43, v209
	v_exp_f32_e32 v42, v42
	v_exp_f32_e32 v43, v43
	v_add_f32_e32 v213, v213, v42
	v_add_f32_e32 v214, v214, v43
	v_cvt_pk_bf16_f32 v42, v42, v43
	v_sub_f32_e32 v44, v44, v209
	v_sub_f32_e32 v45, v45, v209
	v_exp_f32_e32 v44, v44
	v_exp_f32_e32 v45, v45
	v_add_f32_e32 v215, v215, v44
	v_add_f32_e32 v216, v216, v45
	v_cvt_pk_bf16_f32 v43, v44, v45
	v_sub_f32_e32 v46, v46, v209
	v_sub_f32_e32 v47, v47, v209
	v_exp_f32_e32 v46, v46
	v_exp_f32_e32 v47, v47
	v_add_f32_e32 v213, v213, v46
	v_add_f32_e32 v214, v214, v47
	v_cvt_pk_bf16_f32 v44, v46, v47
	v_sub_f32_e32 v48, v48, v209
	v_sub_f32_e32 v49, v49, v209
	v_exp_f32_e32 v48, v48
	v_exp_f32_e32 v49, v49
	v_add_f32_e32 v215, v215, v48
	v_add_f32_e32 v216, v216, v49
	v_cvt_pk_bf16_f32 v45, v48, v49
	v_add_f32_e32 v213, v213, v214
	v_add_f32_e32 v215, v215, v216
	v_add_f32_e32 v213, v213, v215
	v_add_f32_e32 v212, v212, v213
	ds_read_b64_tr_b16 v[114:115], v243 offset:9216
	ds_read_b64_tr_b16 v[116:117], v243 offset:9792
	ds_read_b64_tr_b16 v[118:119], v243 offset:9280
	ds_read_b64_tr_b16 v[120:121], v243 offset:9856
	ds_read_b64_tr_b16 v[122:123], v243 offset:11520
	ds_read_b64_tr_b16 v[124:125], v243 offset:12096
	ds_read_b64_tr_b16 v[126:127], v243 offset:11584
	ds_read_b64_tr_b16 v[128:129], v243 offset:12160
	ds_read_b64_tr_b16 v[130:131], v243 offset:27648
	ds_read_b64_tr_b16 v[132:133], v243 offset:28224
	ds_read_b64_tr_b16 v[134:135], v243 offset:27712
	ds_read_b64_tr_b16 v[136:137], v243 offset:28288
	s_waitcnt lgkmcnt(10)
	v_mfma_f32_32x32x16_bf16 v[50:65], v[114:117], v[2:5], v[50:65]
	s_waitcnt lgkmcnt(8)
	v_mfma_f32_32x32x16_bf16 v[66:81], v[118:121], v[2:5], v[66:81]
	ds_read_b64_tr_b16 v[138:139], v243 offset:29952
	ds_read_b64_tr_b16 v[140:141], v243 offset:30528
	ds_read_b64_tr_b16 v[142:143], v243 offset:30016
	ds_read_b64_tr_b16 v[144:145], v243 offset:30592
	s_waitcnt lgkmcnt(10)
	v_mfma_f32_32x32x16_bf16 v[50:65], v[122:125], v[10:13], v[50:65]
	s_waitcnt lgkmcnt(8)
	v_mfma_f32_32x32x16_bf16 v[66:81], v[126:129], v[10:13], v[66:81]
	ds_read_b64_tr_b16 v[114:115], v243 offset:46080
	ds_read_b64_tr_b16 v[116:117], v243 offset:46656
	ds_read_b64_tr_b16 v[118:119], v243 offset:46144
	ds_read_b64_tr_b16 v[120:121], v243 offset:46720
	s_waitcnt lgkmcnt(10)
	v_mfma_f32_32x32x16_bf16 v[50:65], v[130:133], v[18:21], v[50:65]
	s_waitcnt lgkmcnt(8)
	v_mfma_f32_32x32x16_bf16 v[66:81], v[134:137], v[18:21], v[66:81]
	ds_read_b64_tr_b16 v[122:123], v243 offset:48384
	ds_read_b64_tr_b16 v[124:125], v243 offset:48960
	ds_read_b64_tr_b16 v[126:127], v243 offset:48448
	ds_read_b64_tr_b16 v[128:129], v243 offset:49024
	s_waitcnt lgkmcnt(10)
	v_mfma_f32_32x32x16_bf16 v[50:65], v[138:141], v[26:29], v[50:65]
	s_waitcnt lgkmcnt(8)
	v_mfma_f32_32x32x16_bf16 v[66:81], v[142:145], v[26:29], v[66:81]
	s_waitcnt lgkmcnt(6)
	v_mfma_f32_32x32x16_bf16 v[50:65], v[114:117], v[34:37], v[50:65]
	s_waitcnt lgkmcnt(4)
	v_mfma_f32_32x32x16_bf16 v[66:81], v[118:121], v[34:37], v[66:81]
	s_waitcnt lgkmcnt(2)
	v_mfma_f32_32x32x16_bf16 v[50:65], v[122:125], v[42:45], v[50:65]
	s_waitcnt lgkmcnt(0)
	v_mfma_f32_32x32x16_bf16 v[66:81], v[126:129], v[42:45], v[66:81]
	s_branch .Lna_p1_end
.Lna_p1_d2:
	s_nop 7
	s_nop 4
	ds_read_b128 v[114:117], v200 offset:36864
	ds_read_b128 v[118:121], v200 offset:36896
	ds_read_b128 v[122:125], v200 offset:36928
	ds_read_b128 v[126:129], v200 offset:36960
	ds_read_b128 v[130:133], v242
	ds_read_b128 v[134:137], v242 offset:32
	ds_read_b128 v[138:141], v242 offset:64
	ds_read_b128 v[142:145], v242 offset:96
	s_waitcnt lgkmcnt(7)
	v_mfma_f32_32x32x16_bf16 v[2:17], v[114:117], v[82:85], v[98:113]
	s_waitcnt lgkmcnt(6)
	v_mfma_f32_32x32x16_bf16 v[2:17], v[118:121], v[86:89], v[2:17]
	s_waitcnt lgkmcnt(5)
	v_mfma_f32_32x32x16_bf16 v[2:17], v[122:125], v[90:93], v[2:17]
	s_waitcnt lgkmcnt(4)
	v_mfma_f32_32x32x16_bf16 v[2:17], v[126:129], v[94:97], v[2:17]
	ds_read_b128 v[114:117], v242 offset:18432
	ds_read_b128 v[118:121], v242 offset:18464
	ds_read_b128 v[122:125], v242 offset:18496
	ds_read_b128 v[126:129], v242 offset:18528
	s_waitcnt lgkmcnt(7)
	v_mfma_f32_32x32x16_bf16 v[18:33], v[130:133], v[82:85], v[98:113]
	s_waitcnt lgkmcnt(6)
	v_mfma_f32_32x32x16_bf16 v[18:33], v[134:137], v[86:89], v[18:33]
	s_waitcnt lgkmcnt(5)
	v_mfma_f32_32x32x16_bf16 v[18:33], v[138:141], v[90:93], v[18:33]
	s_waitcnt lgkmcnt(4)
	v_mfma_f32_32x32x16_bf16 v[18:33], v[142:145], v[94:97], v[18:33]
	s_waitcnt lgkmcnt(3)
	v_mfma_f32_32x32x16_bf16 v[34:49], v[114:117], v[82:85], v[98:113]
	s_waitcnt lgkmcnt(2)
	v_mfma_f32_32x32x16_bf16 v[34:49], v[118:121], v[86:89], v[34:49]
	s_waitcnt lgkmcnt(1)
	v_mfma_f32_32x32x16_bf16 v[34:49], v[122:125], v[90:93], v[34:49]
	s_waitcnt lgkmcnt(0)
	v_mfma_f32_32x32x16_bf16 v[34:49], v[126:129], v[94:97], v[34:49]
	s_add_i32 s62, s23, 0
	s_add_i32 s63, s62, 7
	v_sub_u32_e32 v217, s63, v206
	v_med3_i32 v217, v217, 0, 14
	v_mul_u32_u24_e32 v217, 31, v217
	v_add_u32_e32 v217, v217, v199
	v_lshlrev_b32_e32 v217, 2, v217
	v_add_u32_e32 v217, 110848, v217
	v_sub_u32_e32 v218, s62, v207
	v_cmp_gt_u32_e64 s[40:41], 8, v218
	s_nop 1
	v_cndmask_b32_e64 v230, v244, v217, s[40:41]
	ds_read2_b32 v[114:115], v230 offset0:0 offset1:1
	ds_read2_b32 v[116:117], v230 offset0:2 offset1:3
	ds_read2_b32 v[118:119], v230 offset0:4 offset1:5
	ds_read2_b32 v[120:121], v230 offset0:6 offset1:7
	ds_read2_b32 v[122:123], v230 offset0:16 offset1:17
	ds_read2_b32 v[124:125], v230 offset0:18 offset1:19
	ds_read2_b32 v[126:127], v230 offset0:20 offset1:21
	ds_read2_b32 v[128:129], v230 offset0:22 offset1:23
	s_waitcnt lgkmcnt(7)
	v_fma_f32 v2, v2, s14, v114
	v_fma_f32 v3, v3, s14, v115
	s_waitcnt lgkmcnt(6)
	v_fma_f32 v4, v4, s14, v116
	v_fma_f32 v5, v5, s14, v117
	s_waitcnt lgkmcnt(5)
	v_fma_f32 v6, v6, s14, v118
	v_fma_f32 v7, v7, s14, v119
	s_waitcnt lgkmcnt(4)
	v_fma_f32 v8, v8, s14, v120
	v_fma_f32 v9, v9, s14, v121
	s_waitcnt lgkmcnt(3)
	v_fma_f32 v10, v10, s14, v122
	v_fma_f32 v11, v11, s14, v123
	s_waitcnt lgkmcnt(2)
	v_fma_f32 v12, v12, s14, v124
	v_fma_f32 v13, v13, s14, v125
	s_waitcnt lgkmcnt(1)
	v_fma_f32 v14, v14, s14, v126
	v_fma_f32 v15, v15, s14, v127
	s_waitcnt lgkmcnt(0)
	v_fma_f32 v16, v16, s14, v128
	v_fma_f32 v17, v17, s14, v129
	s_add_i32 s62, s23, 1
	s_add_i32 s63, s62, 7
	v_sub_u32_e32 v217, s63, v206
	v_med3_i32 v217, v217, 0, 14
	v_mul_u32_u24_e32 v217, 31, v217
	v_add_u32_e32 v217, v217, v199
	v_lshlrev_b32_e32 v217, 2, v217
	v_add_u32_e32 v217, 110848, v217
	v_sub_u32_e32 v218, s62, v207
	v_cmp_gt_u32_e64 s[40:41], 8, v218
	s_nop 1
	v_cndmask_b32_e64 v230, v244, v217, s[40:41]
	ds_read2_b32 v[130:131], v230 offset0:0 offset1:1
	ds_read2_b32 v[132:133], v230 offset0:2 offset1:3
	ds_read2_b32 v[134:135], v230 offset0:4 offset1:5
	ds_read2_b32 v[136:137], v230 offset0:6 offset1:7
	ds_read2_b32 v[138:139], v230 offset0:16 offset1:17
	ds_read2_b32 v[140:141], v230 offset0:18 offset1:19
	ds_read2_b32 v[142:143], v230 offset0:20 offset1:21
	ds_read2_b32 v[144:145], v230 offset0:22 offset1:23
	s_waitcnt lgkmcnt(7)
	v_fma_f32 v18, v18, s14, v130
	v_fma_f32 v19, v19, s14, v131
	s_waitcnt lgkmcnt(6)
	v_fma_f32 v20, v20, s14, v132
	v_fma_f32 v21, v21, s14, v133
	s_waitcnt lgkmcnt(5)
	v_fma_f32 v22, v22, s14, v134
	v_fma_f32 v23, v23, s14, v135
	s_waitcnt lgkmcnt(4)
	v_fma_f32 v24, v24, s14, v136
	v_fma_f32 v25, v25, s14, v137
	s_waitcnt lgkmcnt(3)
	v_fma_f32 v26, v26, s14, v138
	v_fma_f32 v27, v27, s14, v139
	s_waitcnt lgkmcnt(2)
	v_fma_f32 v28, v28, s14, v140
	v_fma_f32 v29, v29, s14, v141
	s_waitcnt lgkmcnt(1)
	v_fma_f32 v30, v30, s14, v142
	v_fma_f32 v31, v31, s14, v143
	s_waitcnt lgkmcnt(0)
	v_fma_f32 v32, v32, s14, v144
	v_fma_f32 v33, v33, s14, v145
	s_add_i32 s62, s23, 2
	s_add_i32 s63, s62, 7
	v_sub_u32_e32 v217, s63, v206
	v_med3_i32 v217, v217, 0, 14
	v_mul_u32_u24_e32 v217, 31, v217
	v_add_u32_e32 v217, v217, v199
	v_lshlrev_b32_e32 v217, 2, v217
	v_add_u32_e32 v217, 110848, v217
	v_sub_u32_e32 v218, s62, v207
	v_cmp_gt_u32_e64 s[40:41], 8, v218
	s_nop 1
	v_cndmask_b32_e64 v230, v244, v217, s[40:41]
	ds_read2_b32 v[114:115], v230 offset0:0 offset1:1
	ds_read2_b32 v[116:117], v230 offset0:2 offset1:3
	ds_read2_b32 v[118:119], v230 offset0:4 offset1:5
	ds_read2_b32 v[120:121], v230 offset0:6 offset1:7
	ds_read2_b32 v[122:123], v230 offset0:16 offset1:17
	ds_read2_b32 v[124:125], v230 offset0:18 offset1:19
	ds_read2_b32 v[126:127], v230 offset0:20 offset1:21
	ds_read2_b32 v[128:129], v230 offset0:22 offset1:23
	s_waitcnt lgkmcnt(7)
	v_fma_f32 v34, v34, s14, v114
	v_fma_f32 v35, v35, s14, v115
	s_waitcnt lgkmcnt(6)
	v_fma_f32 v36, v36, s14, v116
	v_fma_f32 v37, v37, s14, v117
	s_waitcnt lgkmcnt(5)
	v_fma_f32 v38, v38, s14, v118
	v_fma_f32 v39, v39, s14, v119
	s_waitcnt lgkmcnt(4)
	v_fma_f32 v40, v40, s14, v120
	v_fma_f32 v41, v41, s14, v121
	s_waitcnt lgkmcnt(3)
	v_fma_f32 v42, v42, s14, v122
	v_fma_f32 v43, v43, s14, v123
	s_waitcnt lgkmcnt(2)
	v_fma_f32 v44, v44, s14, v124
	v_fma_f32 v45, v45, s14, v125
	s_waitcnt lgkmcnt(1)
	v_fma_f32 v46, v46, s14, v126
	v_fma_f32 v47, v47, s14, v127
	s_waitcnt lgkmcnt(0)
	v_fma_f32 v48, v48, s14, v128
	v_fma_f32 v49, v49, s14, v129
	v_max3_f32 v210, v2, v3, v4
	v_max3_f32 v219, v5, v6, v7
	v_max3_f32 v210, v210, v8, v9
	v_max3_f32 v219, v219, v10, v11
	v_max3_f32 v210, v210, v12, v13
	v_max3_f32 v219, v219, v14, v15
	v_max3_f32 v210, v210, v16, v17
	v_max3_f32 v219, v219, v18, v19
	v_max3_f32 v210, v210, v20, v21
	v_max3_f32 v219, v219, v22, v23
	v_max3_f32 v210, v210, v24, v25
	v_max3_f32 v219, v219, v26, v27
	v_max3_f32 v210, v210, v28, v29
	v_max3_f32 v219, v219, v30, v31
	v_max3_f32 v210, v210, v32, v33
	v_max3_f32 v219, v219, v34, v35
	v_max3_f32 v210, v210, v36, v37
	v_max3_f32 v219, v219, v38, v39
	v_max3_f32 v210, v210, v40, v41
	v_max3_f32 v219, v219, v42, v43
	v_max3_f32 v210, v210, v44, v45
	v_max3_f32 v219, v219, v46, v47
	v_max3_f32 v210, v210, v48, v49
	v_max_f32_e32 v210, v210, v219
	v_mov_b32_e32 v219, v210
	s_nop 1
	v_permlane32_swap_b32_e32 v210, v219
	v_max_f32_e32 v210, v210, v219
	v_max_f32_e32 v210, v210, v209
	v_mov_b32_e32 v209, v210
	v_mov_b32_e32 v213, 0
	v_mov_b32_e32 v214, 0
	v_mov_b32_e32 v215, 0
	v_mov_b32_e32 v216, 0
	v_sub_f32_e32 v2, v2, v209
	v_sub_f32_e32 v3, v3, v209
	v_exp_f32_e32 v2, v2
	v_exp_f32_e32 v3, v3
	v_add_f32_e32 v213, v213, v2
	v_add_f32_e32 v214, v214, v3
	v_cvt_pk_bf16_f32 v2, v2, v3
	v_sub_f32_e32 v4, v4, v209
	v_sub_f32_e32 v5, v5, v209
	v_exp_f32_e32 v4, v4
	v_exp_f32_e32 v5, v5
	v_add_f32_e32 v215, v215, v4
	v_add_f32_e32 v216, v216, v5
	v_cvt_pk_bf16_f32 v3, v4, v5
	v_sub_f32_e32 v6, v6, v209
	v_sub_f32_e32 v7, v7, v209
	v_exp_f32_e32 v6, v6
	v_exp_f32_e32 v7, v7
	v_add_f32_e32 v213, v213, v6
	v_add_f32_e32 v214, v214, v7
	v_cvt_pk_bf16_f32 v4, v6, v7
	v_sub_f32_e32 v8, v8, v209
	v_sub_f32_e32 v9, v9, v209
	v_exp_f32_e32 v8, v8
	v_exp_f32_e32 v9, v9
	v_add_f32_e32 v215, v215, v8
	v_add_f32_e32 v216, v216, v9
	v_cvt_pk_bf16_f32 v5, v8, v9
	v_sub_f32_e32 v10, v10, v209
	v_sub_f32_e32 v11, v11, v209
	v_exp_f32_e32 v10, v10
	v_exp_f32_e32 v11, v11
	v_add_f32_e32 v213, v213, v10
	v_add_f32_e32 v214, v214, v11
	v_cvt_pk_bf16_f32 v10, v10, v11
	v_sub_f32_e32 v12, v12, v209
	v_sub_f32_e32 v13, v13, v209
	v_exp_f32_e32 v12, v12
	v_exp_f32_e32 v13, v13
	v_add_f32_e32 v215, v215, v12
	v_add_f32_e32 v216, v216, v13
	v_cvt_pk_bf16_f32 v11, v12, v13
	v_sub_f32_e32 v14, v14, v209
	v_sub_f32_e32 v15, v15, v209
	v_exp_f32_e32 v14, v14
	v_exp_f32_e32 v15, v15
	v_add_f32_e32 v213, v213, v14
	v_add_f32_e32 v214, v214, v15
	v_cvt_pk_bf16_f32 v12, v14, v15
	v_sub_f32_e32 v16, v16, v209
	v_sub_f32_e32 v17, v17, v209
	v_exp_f32_e32 v16, v16
	v_exp_f32_e32 v17, v17
	v_add_f32_e32 v215, v215, v16
	v_add_f32_e32 v216, v216, v17
	v_cvt_pk_bf16_f32 v13, v16, v17
	v_sub_f32_e32 v18, v18, v209
	v_sub_f32_e32 v19, v19, v209
	v_exp_f32_e32 v18, v18
	v_exp_f32_e32 v19, v19
	v_add_f32_e32 v213, v213, v18
	v_add_f32_e32 v214, v214, v19
	v_cvt_pk_bf16_f32 v18, v18, v19
	v_sub_f32_e32 v20, v20, v209
	v_sub_f32_e32 v21, v21, v209
	v_exp_f32_e32 v20, v20
	v_exp_f32_e32 v21, v21
	v_add_f32_e32 v215, v215, v20
	v_add_f32_e32 v216, v216, v21
	v_cvt_pk_bf16_f32 v19, v20, v21
	v_sub_f32_e32 v22, v22, v209
	v_sub_f32_e32 v23, v23, v209
	v_exp_f32_e32 v22, v22
	v_exp_f32_e32 v23, v23
	v_add_f32_e32 v213, v213, v22
	v_add_f32_e32 v214, v214, v23
	v_cvt_pk_bf16_f32 v20, v22, v23
	v_sub_f32_e32 v24, v24, v209
	v_sub_f32_e32 v25, v25, v209
	v_exp_f32_e32 v24, v24
	v_exp_f32_e32 v25, v25
	v_add_f32_e32 v215, v215, v24
	v_add_f32_e32 v216, v216, v25
	v_cvt_pk_bf16_f32 v21, v24, v25
	v_sub_f32_e32 v26, v26, v209
	v_sub_f32_e32 v27, v27, v209
	v_exp_f32_e32 v26, v26
	v_exp_f32_e32 v27, v27
	v_add_f32_e32 v213, v213, v26
	v_add_f32_e32 v214, v214, v27
	v_cvt_pk_bf16_f32 v26, v26, v27
	v_sub_f32_e32 v28, v28, v209
	v_sub_f32_e32 v29, v29, v209
	v_exp_f32_e32 v28, v28
	v_exp_f32_e32 v29, v29
	v_add_f32_e32 v215, v215, v28
	v_add_f32_e32 v216, v216, v29
	v_cvt_pk_bf16_f32 v27, v28, v29
	v_sub_f32_e32 v30, v30, v209
	v_sub_f32_e32 v31, v31, v209
	v_exp_f32_e32 v30, v30
	v_exp_f32_e32 v31, v31
	v_add_f32_e32 v213, v213, v30
	v_add_f32_e32 v214, v214, v31
	v_cvt_pk_bf16_f32 v28, v30, v31
	v_sub_f32_e32 v32, v32, v209
	v_sub_f32_e32 v33, v33, v209
	v_exp_f32_e32 v32, v32
	v_exp_f32_e32 v33, v33
	v_add_f32_e32 v215, v215, v32
	v_add_f32_e32 v216, v216, v33
	v_cvt_pk_bf16_f32 v29, v32, v33
	v_sub_f32_e32 v34, v34, v209
	v_sub_f32_e32 v35, v35, v209
	v_exp_f32_e32 v34, v34
	v_exp_f32_e32 v35, v35
	v_add_f32_e32 v213, v213, v34
	v_add_f32_e32 v214, v214, v35
	v_cvt_pk_bf16_f32 v34, v34, v35
	v_sub_f32_e32 v36, v36, v209
	v_sub_f32_e32 v37, v37, v209
	v_exp_f32_e32 v36, v36
	v_exp_f32_e32 v37, v37
	v_add_f32_e32 v215, v215, v36
	v_add_f32_e32 v216, v216, v37
	v_cvt_pk_bf16_f32 v35, v36, v37
	v_sub_f32_e32 v38, v38, v209
	v_sub_f32_e32 v39, v39, v209
	v_exp_f32_e32 v38, v38
	v_exp_f32_e32 v39, v39
	v_add_f32_e32 v213, v213, v38
	v_add_f32_e32 v214, v214, v39
	v_cvt_pk_bf16_f32 v36, v38, v39
	v_sub_f32_e32 v40, v40, v209
	v_sub_f32_e32 v41, v41, v209
	v_exp_f32_e32 v40, v40
	v_exp_f32_e32 v41, v41
	v_add_f32_e32 v215, v215, v40
	v_add_f32_e32 v216, v216, v41
	v_cvt_pk_bf16_f32 v37, v40, v41
	v_sub_f32_e32 v42, v42, v209
	v_sub_f32_e32 v43, v43, v209
	v_exp_f32_e32 v42, v42
	v_exp_f32_e32 v43, v43
	v_add_f32_e32 v213, v213, v42
	v_add_f32_e32 v214, v214, v43
	v_cvt_pk_bf16_f32 v42, v42, v43
	v_sub_f32_e32 v44, v44, v209
	v_sub_f32_e32 v45, v45, v209
	v_exp_f32_e32 v44, v44
	v_exp_f32_e32 v45, v45
	v_add_f32_e32 v215, v215, v44
	v_add_f32_e32 v216, v216, v45
	v_cvt_pk_bf16_f32 v43, v44, v45
	v_sub_f32_e32 v46, v46, v209
	v_sub_f32_e32 v47, v47, v209
	v_exp_f32_e32 v46, v46
	v_exp_f32_e32 v47, v47
	v_add_f32_e32 v213, v213, v46
	v_add_f32_e32 v214, v214, v47
	v_cvt_pk_bf16_f32 v44, v46, v47
	v_sub_f32_e32 v48, v48, v209
	v_sub_f32_e32 v49, v49, v209
	v_exp_f32_e32 v48, v48
	v_exp_f32_e32 v49, v49
	v_add_f32_e32 v215, v215, v48
	v_add_f32_e32 v216, v216, v49
	v_cvt_pk_bf16_f32 v45, v48, v49
	v_add_f32_e32 v213, v213, v214
	v_add_f32_e32 v215, v215, v216
	v_add_f32_e32 v213, v213, v215
	v_mov_b32_e32 v212, v213
	ds_read_b64_tr_b16 v[114:115], v201 offset:46080
	ds_read_b64_tr_b16 v[116:117], v201 offset:46656
	ds_read_b64_tr_b16 v[118:119], v201 offset:46144
	ds_read_b64_tr_b16 v[120:121], v201 offset:46720
	ds_read_b64_tr_b16 v[122:123], v201 offset:48384
	ds_read_b64_tr_b16 v[124:125], v201 offset:48960
	ds_read_b64_tr_b16 v[126:127], v201 offset:48448
	ds_read_b64_tr_b16 v[128:129], v201 offset:49024
	ds_read_b64_tr_b16 v[130:131], v243 offset:9216
	ds_read_b64_tr_b16 v[132:133], v243 offset:9792
	ds_read_b64_tr_b16 v[134:135], v243 offset:9280
	ds_read_b64_tr_b16 v[136:137], v243 offset:9856
	s_waitcnt lgkmcnt(10)
	v_mfma_f32_32x32x16_bf16 v[50:65], v[114:117], v[2:5], 0
	s_waitcnt lgkmcnt(8)
	v_mfma_f32_32x32x16_bf16 v[66:81], v[118:121], v[2:5], 0
	ds_read_b64_tr_b16 v[138:139], v243 offset:11520
	ds_read_b64_tr_b16 v[140:141], v243 offset:12096
	ds_read_b64_tr_b16 v[142:143], v243 offset:11584
	ds_read_b64_tr_b16 v[144:145], v243 offset:12160
	s_waitcnt lgkmcnt(10)
	v_mfma_f32_32x32x16_bf16 v[50:65], v[122:125], v[10:13], v[50:65]
	s_waitcnt lgkmcnt(8)
	v_mfma_f32_32x32x16_bf16 v[66:81], v[126:129], v[10:13], v[66:81]
	ds_read_b64_tr_b16 v[114:115], v243 offset:27648
	ds_read_b64_tr_b16 v[116:117], v243 offset:28224
	ds_read_b64_tr_b16 v[118:119], v243 offset:27712
	ds_read_b64_tr_b16 v[120:121], v243 offset:28288
	s_waitcnt lgkmcnt(10)
	v_mfma_f32_32x32x16_bf16 v[50:65], v[130:133], v[18:21], v[50:65]
	s_waitcnt lgkmcnt(8)
	v_mfma_f32_32x32x16_bf16 v[66:81], v[134:137], v[18:21], v[66:81]
	ds_read_b64_tr_b16 v[122:123], v243 offset:29952
	ds_read_b64_tr_b16 v[124:125], v243 offset:30528
	ds_read_b64_tr_b16 v[126:127], v243 offset:30016
	ds_read_b64_tr_b16 v[128:129], v243 offset:30592
	s_waitcnt lgkmcnt(10)
	v_mfma_f32_32x32x16_bf16 v[50:65], v[138:141], v[26:29], v[50:65]
	s_waitcnt lgkmcnt(8)
	v_mfma_f32_32x32x16_bf16 v[66:81], v[142:145], v[26:29], v[66:81]
	s_waitcnt lgkmcnt(6)
	v_mfma_f32_32x32x16_bf16 v[50:65], v[114:117], v[34:37], v[50:65]
	s_waitcnt lgkmcnt(4)
	v_mfma_f32_32x32x16_bf16 v[66:81], v[118:121], v[34:37], v[66:81]
	s_waitcnt lgkmcnt(2)
	v_mfma_f32_32x32x16_bf16 v[50:65], v[122:125], v[42:45], v[50:65]
	s_waitcnt lgkmcnt(0)
	v_mfma_f32_32x32x16_bf16 v[66:81], v[126:129], v[42:45], v[66:81]
.Lna_p1_end:
	s_waitcnt vmcnt(0)
	s_barrier
	ds_write_b128 v202, v[146:149]
	ds_write_b128 v202, v[150:153] offset:9216
	ds_write_b128 v202, v[154:157] offset:18432
	ds_write_b128 v202, v[158:161] offset:27648
	ds_write_b128 v202, v[162:165] offset:36864
	ds_write_b128 v202, v[166:169] offset:46080
	ds_write_b128 v203, v[170:173]
	ds_write_b128 v203, v[174:177] offset:9216
	ds_write_b128 v203, v[178:181] offset:18432
	ds_write_b128 v203, v[182:185] offset:27648
	s_waitcnt lgkmcnt(0)
	s_barrier
	s_add_i32 s33, s21, 1
	s_cmp_le_u32 s20, 1
	s_cbranch_scc1 .Lna_nopf
	s_cmpk_gt_i32 s33, 0x7ff
	s_cbranch_scc1 .Lna_nopf
	s_lshr_b32 s6, s33, 6
	s_and_b32 s7, s33, 63
	s_lshr_b32 s8, s6, 4
	s_and_b32 s9, s6, 15
	s_lshl_b32 s10, s7, 2
	s_add_i32 s22, s10, -4
	s_max_i32 s22, s22, 0
	s_min_i32 s22, s22, 0xf8
	s_mul_i32 s11, s8, 0x6000000
	s_lshl_b32 s12, s9, 7
	s_add_u32 s4, s94, 0x7800000
	s_addc_u32 s5, s95, 0
	s_add_u32 s4, s4, s11
	s_addc_u32 s5, s5, 0
	s_add_u32 s4, s4, s12
	s_addc_u32 s5, s5, 0
	s_add_u32 s34, s4, 0x800
	s_addc_u32 s35, s5, 0
	s_add_u32 s36, s4, 0x1000
	s_addc_u32 s37, s5, 0
	s_mul_i32 s11, s9, 0x744
	s_add_u32 s38, s86, s11
	s_addc_u32 s39, s87, 0
	s_lshl_b32 s26, s30, 1
	s_add_i32 s26, s26, s10
	s_add_i32 s27, s22, 0
	s_min_i32 s27, s27, 0xff
	s_mul_i32 s27, s27, 0x60000
	v_add_u32_e32 v223, s27, v231
	global_load_dwordx4 v[146:149], v223, s[34:35]
	global_load_dwordx4 v[150:153], v223, s[36:37]
	s_add_i32 s27, s22, 1
	s_min_i32 s27, s27, 0xff
	s_mul_i32 s27, s27, 0x60000
	v_add_u32_e32 v224, s27, v231
	global_load_dwordx4 v[154:157], v224, s[34:35]
	global_load_dwordx4 v[158:161], v224, s[36:37]
	s_add_i32 s27, s22, 2
	s_min_i32 s27, s27, 0xff
	s_mul_i32 s27, s27, 0x60000
	v_add_u32_e32 v225, s27, v231
	global_load_dwordx4 v[162:165], v225, s[34:35]
	global_load_dwordx4 v[166:169], v225, s[36:37]
	s_add_i32 s27, s22, 3
	s_min_i32 s27, s27, 0xff
	s_mul_i32 s27, s27, 0x60000
	v_add_u32_e32 v226, s27, v231
	global_load_dwordx4 v[170:173], v226, s[34:35]
	global_load_dwordx4 v[174:177], v226, s[36:37]
	s_add_i32 s27, s22, 4
	s_min_i32 s27, s27, 0xff
	s_mul_i32 s27, s27, 0x60000
	v_add_u32_e32 v227, s27, v231
	global_load_dwordx4 v[178:181], v227, s[34:35]
	global_load_dwordx4 v[182:185], v227, s[36:37]
	s_add_i32 s27, s22, 5
	s_min_i32 s27, s27, 0xff
	s_mul_i32 s27, s27, 0x60000
	v_add_u32_e32 v228, s27, v231
	global_load_dwordx4 v[186:189], v228, s[34:35]
	global_load_dwordx4 v[190:193], v228, s[36:37]
	global_load_dword v194, v247, s[38:39]
	global_load_dword v195, v248, s[38:39]
.Lna_nopf:
	s_cmp_lg_u32 s24, 0
	s_cbranch_scc1 .Lna_p2_d2
	s_nop 7
	s_nop 4
	ds_read_b128 v[114:117], v200
	ds_read_b128 v[118:121], v200 offset:32
	ds_read_b128 v[122:125], v200 offset:64
	ds_read_b128 v[126:129], v200 offset:96
	ds_read_b128 v[130:133], v200 offset:18432
	ds_read_b128 v[134:137], v200 offset:18464
	ds_read_b128 v[138:141], v200 offset:18496
	ds_read_b128 v[142:145], v200 offset:18528
	s_waitcnt lgkmcnt(7)
	v_mfma_f32_32x32x16_bf16 v[2:17], v[114:117], v[82:85], v[98:113]
	s_waitcnt lgkmcnt(6)
	v_mfma_f32_32x32x16_bf16 v[2:17], v[118:121], v[86:89], v[2:17]
	s_waitcnt lgkmcnt(5)
	v_mfma_f32_32x32x16_bf16 v[2:17], v[122:125], v[90:93], v[2:17]
	s_waitcnt lgkmcnt(4)
	v_mfma_f32_32x32x16_bf16 v[2:17], v[126:129], v[94:97], v[2:17]
	ds_read_b128 v[114:117], v200 offset:36864
	ds_read_b128 v[118:121], v200 offset:36896
	ds_read_b128 v[122:125], v200 offset:36928
	ds_read_b128 v[126:129], v200 offset:36960
	s_waitcnt lgkmcnt(7)
	v_mfma_f32_32x32x16_bf16 v[18:33], v[130:133], v[82:85], v[98:113]
	s_waitcnt lgkmcnt(6)
	v_mfma_f32_32x32x16_bf16 v[18:33], v[134:137], v[86:89], v[18:33]
	s_waitcnt lgkmcnt(5)
	v_mfma_f32_32x32x16_bf16 v[18:33], v[138:141], v[90:93], v[18:33]
	s_waitcnt lgkmcnt(4)
	v_mfma_f32_32x32x16_bf16 v[18:33], v[142:145], v[94:97], v[18:33]
	s_waitcnt lgkmcnt(3)
	v_mfma_f32_32x32x16_bf16 v[34:49], v[114:117], v[82:85], v[98:113]
	s_waitcnt lgkmcnt(2)
	v_mfma_f32_32x32x16_bf16 v[34:49], v[118:121], v[86:89], v[34:49]
	s_waitcnt lgkmcnt(1)
	v_mfma_f32_32x32x16_bf16 v[34:49], v[122:125], v[90:93], v[34:49]
	s_waitcnt lgkmcnt(0)
	v_mfma_f32_32x32x16_bf16 v[34:49], v[126:129], v[94:97], v[34:49]
	s_add_i32 s62, s23, 6
	s_add_i32 s63, s62, 7
	v_sub_u32_e32 v217, s63, v206
	v_med3_i32 v217, v217, 0, 14
	v_mul_u32_u24_e32 v217, 31, v217
	v_add_u32_e32 v217, v217, v199
	v_lshlrev_b32_e32 v217, 2, v217
	v_add_u32_e32 v217, 110848, v217
	v_sub_u32_e32 v218, s62, v207
	v_cmp_gt_u32_e64 s[40:41], 8, v218
	s_nop 1
	v_cndmask_b32_e64 v230, v244, v217, s[40:41]
	ds_read2_b32 v[114:115], v230 offset0:0 offset1:1
	ds_read2_b32 v[116:117], v230 offset0:2 offset1:3
	ds_read2_b32 v[118:119], v230 offset0:4 offset1:5
	ds_read2_b32 v[120:121], v230 offset0:6 offset1:7
	ds_read2_b32 v[122:123], v230 offset0:16 offset1:17
	ds_read2_b32 v[124:125], v230 offset0:18 offset1:19
	ds_read2_b32 v[126:127], v230 offset0:20 offset1:21
	ds_read2_b32 v[128:129], v230 offset0:22 offset1:23
	s_waitcnt lgkmcnt(7)
	v_fma_f32 v2, v2, s14, v114
	v_fma_f32 v3, v3, s14, v115
	s_waitcnt lgkmcnt(6)
	v_fma_f32 v4, v4, s14, v116
	v_fma_f32 v5, v5, s14, v117
	s_waitcnt lgkmcnt(5)
	v_fma_f32 v6, v6, s14, v118
	v_fma_f32 v7, v7, s14, v119
	s_waitcnt lgkmcnt(4)
	v_fma_f32 v8, v8, s14, v120
	v_fma_f32 v9, v9, s14, v121
	s_waitcnt lgkmcnt(3)
	v_fma_f32 v10, v10, s14, v122
	v_fma_f32 v11, v11, s14, v123
	s_waitcnt lgkmcnt(2)
	v_fma_f32 v12, v12, s14, v124
	v_fma_f32 v13, v13, s14, v125
	s_waitcnt lgkmcnt(1)
	v_fma_f32 v14, v14, s14, v126
	v_fma_f32 v15, v15, s14, v127
	s_waitcnt lgkmcnt(0)
	v_fma_f32 v16, v16, s14, v128
	v_fma_f32 v17, v17, s14, v129
	s_add_i32 s62, s23, 7
	s_add_i32 s63, s62, 7
	v_sub_u32_e32 v217, s63, v206
	v_med3_i32 v217, v217, 0, 14
	v_mul_u32_u24_e32 v217, 31, v217
	v_add_u32_e32 v217, v217, v199
	v_lshlrev_b32_e32 v217, 2, v217
	v_add_u32_e32 v217, 110848, v217
	v_sub_u32_e32 v218, s62, v207
	v_cmp_gt_u32_e64 s[40:41], 8, v218
	s_nop 1
	v_cndmask_b32_e64 v230, v244, v217, s[40:41]
	ds_read2_b32 v[130:131], v230 offset0:0 offset1:1
	ds_read2_b32 v[132:133], v230 offset0:2 offset1:3
	ds_read2_b32 v[134:135], v230 offset0:4 offset1:5
	ds_read2_b32 v[136:137], v230 offset0:6 offset1:7
	ds_read2_b32 v[138:139], v230 offset0:16 offset1:17
	ds_read2_b32 v[140:141], v230 offset0:18 offset1:19
	ds_read2_b32 v[142:143], v230 offset0:20 offset1:21
	ds_read2_b32 v[144:145], v230 offset0:22 offset1:23
	s_waitcnt lgkmcnt(7)
	v_fma_f32 v18, v18, s14, v130
	v_fma_f32 v19, v19, s14, v131
	s_waitcnt lgkmcnt(6)
	v_fma_f32 v20, v20, s14, v132
	v_fma_f32 v21, v21, s14, v133
	s_waitcnt lgkmcnt(5)
	v_fma_f32 v22, v22, s14, v134
	v_fma_f32 v23, v23, s14, v135
	s_waitcnt lgkmcnt(4)
	v_fma_f32 v24, v24, s14, v136
	v_fma_f32 v25, v25, s14, v137
	s_waitcnt lgkmcnt(3)
	v_fma_f32 v26, v26, s14, v138
	v_fma_f32 v27, v27, s14, v139
	s_waitcnt lgkmcnt(2)
	v_fma_f32 v28, v28, s14, v140
	v_fma_f32 v29, v29, s14, v141
	s_waitcnt lgkmcnt(1)
	v_fma_f32 v30, v30, s14, v142
	v_fma_f32 v31, v31, s14, v143
	s_waitcnt lgkmcnt(0)
	v_fma_f32 v32, v32, s14, v144
	v_fma_f32 v33, v33, s14, v145
	s_add_i32 s62, s23, 8
	s_add_i32 s63, s62, 7
	v_sub_u32_e32 v217, s63, v206
	v_med3_i32 v217, v217, 0, 14
	v_mul_u32_u24_e32 v217, 31, v217
	v_add_u32_e32 v217, v217, v199
	v_lshlrev_b32_e32 v217, 2, v217
	v_add_u32_e32 v217, 110848, v217
	v_sub_u32_e32 v218, s62, v207
	v_cmp_gt_u32_e64 s[40:41], 8, v218
	s_nop 1
	v_cndmask_b32_e64 v230, v244, v217, s[40:41]
	ds_read2_b32 v[114:115], v230 offset0:0 offset1:1
	ds_read2_b32 v[116:117], v230 offset0:2 offset1:3
	ds_read2_b32 v[118:119], v230 offset0:4 offset1:5
	ds_read2_b32 v[120:121], v230 offset0:6 offset1:7
	ds_read2_b32 v[122:123], v230 offset0:16 offset1:17
	ds_read2_b32 v[124:125], v230 offset0:18 offset1:19
	ds_read2_b32 v[126:127], v230 offset0:20 offset1:21
	ds_read2_b32 v[128:129], v230 offset0:22 offset1:23
	s_waitcnt lgkmcnt(7)
	v_fma_f32 v34, v34, s14, v114
	v_fma_f32 v35, v35, s14, v115
	s_waitcnt lgkmcnt(6)
	v_fma_f32 v36, v36, s14, v116
	v_fma_f32 v37, v37, s14, v117
	s_waitcnt lgkmcnt(5)
	v_fma_f32 v38, v38, s14, v118
	v_fma_f32 v39, v39, s14, v119
	s_waitcnt lgkmcnt(4)
	v_fma_f32 v40, v40, s14, v120
	v_fma_f32 v41, v41, s14, v121
	s_waitcnt lgkmcnt(3)
	v_fma_f32 v42, v42, s14, v122
	v_fma_f32 v43, v43, s14, v123
	s_waitcnt lgkmcnt(2)
	v_fma_f32 v44, v44, s14, v124
	v_fma_f32 v45, v45, s14, v125
	s_waitcnt lgkmcnt(1)
	v_fma_f32 v46, v46, s14, v126
	v_fma_f32 v47, v47, s14, v127
	s_waitcnt lgkmcnt(0)
	v_fma_f32 v48, v48, s14, v128
	v_fma_f32 v49, v49, s14, v129
	v_max3_f32 v210, v2, v3, v4
	v_max3_f32 v219, v5, v6, v7
	v_max3_f32 v210, v210, v8, v9
	v_max3_f32 v219, v219, v10, v11
	v_max3_f32 v210, v210, v12, v13
	v_max3_f32 v219, v219, v14, v15
	v_max3_f32 v210, v210, v16, v17
	v_max3_f32 v219, v219, v18, v19
	v_max3_f32 v210, v210, v20, v21
	v_max3_f32 v219, v219, v22, v23
	v_max3_f32 v210, v210, v24, v25
	v_max3_f32 v219, v219, v26, v27
	v_max3_f32 v210, v210, v28, v29
	v_max3_f32 v219, v219, v30, v31
	v_max3_f32 v210, v210, v32, v33
	v_max3_f32 v219, v219, v34, v35
	v_max3_f32 v210, v210, v36, v37
	v_max3_f32 v219, v219, v38, v39
	v_max3_f32 v210, v210, v40, v41
	v_max3_f32 v219, v219, v42, v43
	v_max3_f32 v210, v210, v44, v45
	v_max3_f32 v219, v219, v46, v47
	v_max3_f32 v210, v210, v48, v49
	v_max_f32_e32 v210, v210, v219
	v_mov_b32_e32 v219, v210
	s_nop 1
	v_permlane32_swap_b32_e32 v210, v219
	v_max_f32_e32 v210, v210, v219
	v_max_f32_e32 v210, v210, v209
	v_sub_f32_e32 v211, v209, v210
	v_exp_f32_e32 v211, v211
	v_mov_b32_e32 v209, v210
	v_mul_f32_e32 v50, v50, v211
	v_mul_f32_e32 v51, v51, v211
	v_mul_f32_e32 v52, v52, v211
	v_mul_f32_e32 v53, v53, v211
	v_mul_f32_e32 v54, v54, v211
	v_mul_f32_e32 v55, v55, v211
	v_mul_f32_e32 v56, v56, v211
	v_mul_f32_e32 v57, v57, v211
	v_mul_f32_e32 v58, v58, v211
	v_mul_f32_e32 v59, v59, v211
	v_mul_f32_e32 v60, v60, v211
	v_mul_f32_e32 v61, v61, v211
	v_mul_f32_e32 v62, v62, v211
	v_mul_f32_e32 v63, v63, v211
	v_mul_f32_e32 v64, v64, v211
	v_mul_f32_e32 v65, v65, v211
	v_mul_f32_e32 v66, v66, v211
	v_mul_f32_e32 v67, v67, v211
	v_mul_f32_e32 v68, v68, v211
	v_mul_f32_e32 v69, v69, v211
	v_mul_f32_e32 v70, v70, v211
	v_mul_f32_e32 v71, v71, v211
	v_mul_f32_e32 v72, v72, v211
	v_mul_f32_e32 v73, v73, v211
	v_mul_f32_e32 v74, v74, v211
	v_mul_f32_e32 v75, v75, v211
	v_mul_f32_e32 v76, v76, v211
	v_mul_f32_e32 v77, v77, v211
	v_mul_f32_e32 v78, v78, v211
	v_mul_f32_e32 v79, v79, v211
	v_mul_f32_e32 v80, v80, v211
	v_mul_f32_e32 v81, v81, v211
	v_mul_f32_e32 v212, v212, v211
	v_mov_b32_e32 v213, 0
	v_mov_b32_e32 v214, 0
	v_mov_b32_e32 v215, 0
	v_mov_b32_e32 v216, 0
	v_sub_f32_e32 v2, v2, v209
	v_sub_f32_e32 v3, v3, v209
	v_exp_f32_e32 v2, v2
	v_exp_f32_e32 v3, v3
	v_add_f32_e32 v213, v213, v2
	v_add_f32_e32 v214, v214, v3
	v_cvt_pk_bf16_f32 v2, v2, v3
	v_sub_f32_e32 v4, v4, v209
	v_sub_f32_e32 v5, v5, v209
	v_exp_f32_e32 v4, v4
	v_exp_f32_e32 v5, v5
	v_add_f32_e32 v215, v215, v4
	v_add_f32_e32 v216, v216, v5
	v_cvt_pk_bf16_f32 v3, v4, v5
	v_sub_f32_e32 v6, v6, v209
	v_sub_f32_e32 v7, v7, v209
	v_exp_f32_e32 v6, v6
	v_exp_f32_e32 v7, v7
	v_add_f32_e32 v213, v213, v6
	v_add_f32_e32 v214, v214, v7
	v_cvt_pk_bf16_f32 v4, v6, v7
	v_sub_f32_e32 v8, v8, v209
	v_sub_f32_e32 v9, v9, v209
	v_exp_f32_e32 v8, v8
	v_exp_f32_e32 v9, v9
	v_add_f32_e32 v215, v215, v8
	v_add_f32_e32 v216, v216, v9
	v_cvt_pk_bf16_f32 v5, v8, v9
	v_sub_f32_e32 v10, v10, v209
	v_sub_f32_e32 v11, v11, v209
	v_exp_f32_e32 v10, v10
	v_exp_f32_e32 v11, v11
	v_add_f32_e32 v213, v213, v10
	v_add_f32_e32 v214, v214, v11
	v_cvt_pk_bf16_f32 v10, v10, v11
	v_sub_f32_e32 v12, v12, v209
	v_sub_f32_e32 v13, v13, v209
	v_exp_f32_e32 v12, v12
	v_exp_f32_e32 v13, v13
	v_add_f32_e32 v215, v215, v12
	v_add_f32_e32 v216, v216, v13
	v_cvt_pk_bf16_f32 v11, v12, v13
	v_sub_f32_e32 v14, v14, v209
	v_sub_f32_e32 v15, v15, v209
	v_exp_f32_e32 v14, v14
	v_exp_f32_e32 v15, v15
	v_add_f32_e32 v213, v213, v14
	v_add_f32_e32 v214, v214, v15
	v_cvt_pk_bf16_f32 v12, v14, v15
	v_sub_f32_e32 v16, v16, v209
	v_sub_f32_e32 v17, v17, v209
	v_exp_f32_e32 v16, v16
	v_exp_f32_e32 v17, v17
	v_add_f32_e32 v215, v215, v16
	v_add_f32_e32 v216, v216, v17
	v_cvt_pk_bf16_f32 v13, v16, v17
	v_sub_f32_e32 v18, v18, v209
	v_sub_f32_e32 v19, v19, v209
	v_exp_f32_e32 v18, v18
	v_exp_f32_e32 v19, v19
	v_add_f32_e32 v213, v213, v18
	v_add_f32_e32 v214, v214, v19
	v_cvt_pk_bf16_f32 v18, v18, v19
	v_sub_f32_e32 v20, v20, v209
	v_sub_f32_e32 v21, v21, v209
	v_exp_f32_e32 v20, v20
	v_exp_f32_e32 v21, v21
	v_add_f32_e32 v215, v215, v20
	v_add_f32_e32 v216, v216, v21
	v_cvt_pk_bf16_f32 v19, v20, v21
	v_sub_f32_e32 v22, v22, v209
	v_sub_f32_e32 v23, v23, v209
	v_exp_f32_e32 v22, v22
	v_exp_f32_e32 v23, v23
	v_add_f32_e32 v213, v213, v22
	v_add_f32_e32 v214, v214, v23
	v_cvt_pk_bf16_f32 v20, v22, v23
	v_sub_f32_e32 v24, v24, v209
	v_sub_f32_e32 v25, v25, v209
	v_exp_f32_e32 v24, v24
	v_exp_f32_e32 v25, v25
	v_add_f32_e32 v215, v215, v24
	v_add_f32_e32 v216, v216, v25
	v_cvt_pk_bf16_f32 v21, v24, v25
	v_sub_f32_e32 v26, v26, v209
	v_sub_f32_e32 v27, v27, v209
	v_exp_f32_e32 v26, v26
	v_exp_f32_e32 v27, v27
	v_add_f32_e32 v213, v213, v26
	v_add_f32_e32 v214, v214, v27
	v_cvt_pk_bf16_f32 v26, v26, v27
	v_sub_f32_e32 v28, v28, v209
	v_sub_f32_e32 v29, v29, v209
	v_exp_f32_e32 v28, v28
	v_exp_f32_e32 v29, v29
	v_add_f32_e32 v215, v215, v28
	v_add_f32_e32 v216, v216, v29
	v_cvt_pk_bf16_f32 v27, v28, v29
	v_sub_f32_e32 v30, v30, v209
	v_sub_f32_e32 v31, v31, v209
	v_exp_f32_e32 v30, v30
	v_exp_f32_e32 v31, v31
	v_add_f32_e32 v213, v213, v30
	v_add_f32_e32 v214, v214, v31
	v_cvt_pk_bf16_f32 v28, v30, v31
	v_sub_f32_e32 v32, v32, v209
	v_sub_f32_e32 v33, v33, v209
	v_exp_f32_e32 v32, v32
	v_exp_f32_e32 v33, v33
	v_add_f32_e32 v215, v215, v32
	v_add_f32_e32 v216, v216, v33
	v_cvt_pk_bf16_f32 v29, v32, v33
	v_sub_f32_e32 v34, v34, v209
	v_sub_f32_e32 v35, v35, v209
	v_exp_f32_e32 v34, v34
	v_exp_f32_e32 v35, v35
	v_add_f32_e32 v213, v213, v34
	v_add_f32_e32 v214, v214, v35
	v_cvt_pk_bf16_f32 v34, v34, v35
	v_sub_f32_e32 v36, v36, v209
	v_sub_f32_e32 v37, v37, v209
	v_exp_f32_e32 v36, v36
	v_exp_f32_e32 v37, v37
	v_add_f32_e32 v215, v215, v36
	v_add_f32_e32 v216, v216, v37
	v_cvt_pk_bf16_f32 v35, v36, v37
	v_sub_f32_e32 v38, v38, v209
	v_sub_f32_e32 v39, v39, v209
	v_exp_f32_e32 v38, v38
	v_exp_f32_e32 v39, v39
	v_add_f32_e32 v213, v213, v38
	v_add_f32_e32 v214, v214, v39
	v_cvt_pk_bf16_f32 v36, v38, v39
	v_sub_f32_e32 v40, v40, v209
	v_sub_f32_e32 v41, v41, v209
	v_exp_f32_e32 v40, v40
	v_exp_f32_e32 v41, v41
	v_add_f32_e32 v215, v215, v40
	v_add_f32_e32 v216, v216, v41
	v_cvt_pk_bf16_f32 v37, v40, v41
	v_sub_f32_e32 v42, v42, v209
	v_sub_f32_e32 v43, v43, v209
	v_exp_f32_e32 v42, v42
	v_exp_f32_e32 v43, v43
	v_add_f32_e32 v213, v213, v42
	v_add_f32_e32 v214, v214, v43
	v_cvt_pk_bf16_f32 v42, v42, v43
	v_sub_f32_e32 v44, v44, v209
	v_sub_f32_e32 v45, v45, v209
	v_exp_f32_e32 v44, v44
	v_exp_f32_e32 v45, v45
	v_add_f32_e32 v215, v215, v44
	v_add_f32_e32 v216, v216, v45
	v_cvt_pk_bf16_f32 v43, v44, v45
	v_sub_f32_e32 v46, v46, v209
	v_sub_f32_e32 v47, v47, v209
	v_exp_f32_e32 v46, v46
	v_exp_f32_e32 v47, v47
	v_add_f32_e32 v213, v213, v46
	v_add_f32_e32 v214, v214, v47
	v_cvt_pk_bf16_f32 v44, v46, v47
	v_sub_f32_e32 v48, v48, v209
	v_sub_f32_e32 v49, v49, v209
	v_exp_f32_e32 v48, v48
	v_exp_f32_e32 v49, v49
	v_add_f32_e32 v215, v215, v48
	v_add_f32_e32 v216, v216, v49
	v_cvt_pk_bf16_f32 v45, v48, v49
	v_add_f32_e32 v213, v213, v214
	v_add_f32_e32 v215, v215, v216
	v_add_f32_e32 v213, v213, v215
	v_add_f32_e32 v212, v212, v213
	ds_read_b64_tr_b16 v[114:115], v201 offset:9216
	ds_read_b64_tr_b16 v[116:117], v201 offset:9792
	ds_read_b64_tr_b16 v[118:119], v201 offset:9280
	ds_read_b64_tr_b16 v[120:121], v201 offset:9856
	ds_read_b64_tr_b16 v[122:123], v201 offset:11520
	ds_read_b64_tr_b16 v[124:125], v201 offset:12096
	ds_read_b64_tr_b16 v[126:127], v201 offset:11584
	ds_read_b64_tr_b16 v[128:129], v201 offset:12160
	ds_read_b64_tr_b16 v[130:131], v201 offset:27648
	ds_read_b64_tr_b16 v[132:133], v201 offset:28224
	ds_read_b64_tr_b16 v[134:135], v201 offset:27712
	ds_read_b64_tr_b16 v[136:137], v201 offset:28288
	s_waitcnt lgkmcnt(10)
	v_mfma_f32_32x32x16_bf16 v[50:65], v[114:117], v[2:5], v[50:65]
	s_waitcnt lgkmcnt(8)
	v_mfma_f32_32x32x16_bf16 v[66:81], v[118:121], v[2:5], v[66:81]
	ds_read_b64_tr_b16 v[138:139], v201 offset:29952
	ds_read_b64_tr_b16 v[140:141], v201 offset:30528
	ds_read_b64_tr_b16 v[142:143], v201 offset:30016
	ds_read_b64_tr_b16 v[144:145], v201 offset:30592
	s_waitcnt lgkmcnt(10)
	v_mfma_f32_32x32x16_bf16 v[50:65], v[122:125], v[10:13], v[50:65]
	s_waitcnt lgkmcnt(8)
	v_mfma_f32_32x32x16_bf16 v[66:81], v[126:129], v[10:13], v[66:81]
	ds_read_b64_tr_b16 v[114:115], v201 offset:46080
	ds_read_b64_tr_b16 v[116:117], v201 offset:46656
	ds_read_b64_tr_b16 v[118:119], v201 offset:46144
	ds_read_b64_tr_b16 v[120:121], v201 offset:46720
	s_waitcnt lgkmcnt(10)
	v_mfma_f32_32x32x16_bf16 v[50:65], v[130:133], v[18:21], v[50:65]
	s_waitcnt lgkmcnt(8)
	v_mfma_f32_32x32x16_bf16 v[66:81], v[134:137], v[18:21], v[66:81]
	ds_read_b64_tr_b16 v[122:123], v201 offset:48384
	ds_read_b64_tr_b16 v[124:125], v201 offset:48960
	ds_read_b64_tr_b16 v[126:127], v201 offset:48448
	ds_read_b64_tr_b16 v[128:129], v201 offset:49024
	s_waitcnt lgkmcnt(10)
	v_mfma_f32_32x32x16_bf16 v[50:65], v[138:141], v[26:29], v[50:65]
	s_waitcnt lgkmcnt(8)
	v_mfma_f32_32x32x16_bf16 v[66:81], v[142:145], v[26:29], v[66:81]
	s_waitcnt lgkmcnt(6)
	v_mfma_f32_32x32x16_bf16 v[50:65], v[114:117], v[34:37], v[50:65]
	s_waitcnt lgkmcnt(4)
	v_mfma_f32_32x32x16_bf16 v[66:81], v[118:121], v[34:37], v[66:81]
	s_waitcnt lgkmcnt(2)
	v_mfma_f32_32x32x16_bf16 v[50:65], v[122:125], v[42:45], v[50:65]
	s_waitcnt lgkmcnt(0)
	v_mfma_f32_32x32x16_bf16 v[66:81], v[126:129], v[42:45], v[66:81]
	s_branch .Lna_p2_end
.Lna_p2_d2:
	s_nop 7
	s_nop 4
	ds_read_b128 v[114:117], v242 offset:36864
	ds_read_b128 v[118:121], v242 offset:36896
	ds_read_b128 v[122:125], v242 offset:36928
	ds_read_b128 v[126:129], v242 offset:36960
	ds_read_b128 v[130:133], v200
	ds_read_b128 v[134:137], v200 offset:32
	ds_read_b128 v[138:141], v200 offset:64
	ds_read_b128 v[142:145], v200 offset:96
	s_waitcnt lgkmcnt(7)
	v_mfma_f32_32x32x16_bf16 v[2:17], v[114:117], v[82:85], v[98:113]
	s_waitcnt lgkmcnt(6)
	v_mfma_f32_32x32x16_bf16 v[2:17], v[118:121], v[86:89], v[2:17]
	s_waitcnt lgkmcnt(5)
	v_mfma_f32_32x32x16_bf16 v[2:17], v[122:125], v[90:93], v[2:17]
	s_waitcnt lgkmcnt(4)
	v_mfma_f32_32x32x16_bf16 v[2:17], v[126:129], v[94:97], v[2:17]
	ds_read_b128 v[114:117], v200 offset:18432
	ds_read_b128 v[118:121], v200 offset:18464
	ds_read_b128 v[122:125], v200 offset:18496
	ds_read_b128 v[126:129], v200 offset:18528
	s_waitcnt lgkmcnt(7)
	v_mfma_f32_32x32x16_bf16 v[18:33], v[130:133], v[82:85], v[98:113]
	s_waitcnt lgkmcnt(6)
	v_mfma_f32_32x32x16_bf16 v[18:33], v[134:137], v[86:89], v[18:33]
	s_waitcnt lgkmcnt(5)
	v_mfma_f32_32x32x16_bf16 v[18:33], v[138:141], v[90:93], v[18:33]
	s_waitcnt lgkmcnt(4)
	v_mfma_f32_32x32x16_bf16 v[18:33], v[142:145], v[94:97], v[18:33]
	s_waitcnt lgkmcnt(3)
	v_mfma_f32_32x32x16_bf16 v[34:49], v[114:117], v[82:85], v[98:113]
	s_waitcnt lgkmcnt(2)
	v_mfma_f32_32x32x16_bf16 v[34:49], v[118:121], v[86:89], v[34:49]
	s_waitcnt lgkmcnt(1)
	v_mfma_f32_32x32x16_bf16 v[34:49], v[122:125], v[90:93], v[34:49]
	s_waitcnt lgkmcnt(0)
	v_mfma_f32_32x32x16_bf16 v[34:49], v[126:129], v[94:97], v[34:49]
	s_add_i32 s62, s23, 3
	s_add_i32 s63, s62, 7
	v_sub_u32_e32 v217, s63, v206
	v_med3_i32 v217, v217, 0, 14
	v_mul_u32_u24_e32 v217, 31, v217
	v_add_u32_e32 v217, v217, v199
	v_lshlrev_b32_e32 v217, 2, v217
	v_add_u32_e32 v217, 110848, v217
	v_sub_u32_e32 v218, s62, v207
	v_cmp_gt_u32_e64 s[40:41], 8, v218
	s_nop 1
	v_cndmask_b32_e64 v230, v244, v217, s[40:41]
	ds_read2_b32 v[114:115], v230 offset0:0 offset1:1
	ds_read2_b32 v[116:117], v230 offset0:2 offset1:3
	ds_read2_b32 v[118:119], v230 offset0:4 offset1:5
	ds_read2_b32 v[120:121], v230 offset0:6 offset1:7
	ds_read2_b32 v[122:123], v230 offset0:16 offset1:17
	ds_read2_b32 v[124:125], v230 offset0:18 offset1:19
	ds_read2_b32 v[126:127], v230 offset0:20 offset1:21
	ds_read2_b32 v[128:129], v230 offset0:22 offset1:23
	s_waitcnt lgkmcnt(7)
	v_fma_f32 v2, v2, s14, v114
	v_fma_f32 v3, v3, s14, v115
	s_waitcnt lgkmcnt(6)
	v_fma_f32 v4, v4, s14, v116
	v_fma_f32 v5, v5, s14, v117
	s_waitcnt lgkmcnt(5)
	v_fma_f32 v6, v6, s14, v118
	v_fma_f32 v7, v7, s14, v119
	s_waitcnt lgkmcnt(4)
	v_fma_f32 v8, v8, s14, v120
	v_fma_f32 v9, v9, s14, v121
	s_waitcnt lgkmcnt(3)
	v_fma_f32 v10, v10, s14, v122
	v_fma_f32 v11, v11, s14, v123
	s_waitcnt lgkmcnt(2)
	v_fma_f32 v12, v12, s14, v124
	v_fma_f32 v13, v13, s14, v125
	s_waitcnt lgkmcnt(1)
	v_fma_f32 v14, v14, s14, v126
	v_fma_f32 v15, v15, s14, v127
	s_waitcnt lgkmcnt(0)
	v_fma_f32 v16, v16, s14, v128
	v_fma_f32 v17, v17, s14, v129
	s_add_i32 s62, s23, 4
	s_add_i32 s63, s62, 7
	v_sub_u32_e32 v217, s63, v206
	v_med3_i32 v217, v217, 0, 14
	v_mul_u32_u24_e32 v217, 31, v217
	v_add_u32_e32 v217, v217, v199
	v_lshlrev_b32_e32 v217, 2, v217
	v_add_u32_e32 v217, 110848, v217
	v_sub_u32_e32 v218, s62, v207
	v_cmp_gt_u32_e64 s[40:41], 8, v218
	s_nop 1
	v_cndmask_b32_e64 v230, v244, v217, s[40:41]
	ds_read2_b32 v[130:131], v230 offset0:0 offset1:1
	ds_read2_b32 v[132:133], v230 offset0:2 offset1:3
	ds_read2_b32 v[134:135], v230 offset0:4 offset1:5
	ds_read2_b32 v[136:137], v230 offset0:6 offset1:7
	ds_read2_b32 v[138:139], v230 offset0:16 offset1:17
	ds_read2_b32 v[140:141], v230 offset0:18 offset1:19
	ds_read2_b32 v[142:143], v230 offset0:20 offset1:21
	ds_read2_b32 v[144:145], v230 offset0:22 offset1:23
	s_waitcnt lgkmcnt(7)
	v_fma_f32 v18, v18, s14, v130
	v_fma_f32 v19, v19, s14, v131
	s_waitcnt lgkmcnt(6)
	v_fma_f32 v20, v20, s14, v132
	v_fma_f32 v21, v21, s14, v133
	s_waitcnt lgkmcnt(5)
	v_fma_f32 v22, v22, s14, v134
	v_fma_f32 v23, v23, s14, v135
	s_waitcnt lgkmcnt(4)
	v_fma_f32 v24, v24, s14, v136
	v_fma_f32 v25, v25, s14, v137
	s_waitcnt lgkmcnt(3)
	v_fma_f32 v26, v26, s14, v138
	v_fma_f32 v27, v27, s14, v139
	s_waitcnt lgkmcnt(2)
	v_fma_f32 v28, v28, s14, v140
	v_fma_f32 v29, v29, s14, v141
	s_waitcnt lgkmcnt(1)
	v_fma_f32 v30, v30, s14, v142
	v_fma_f32 v31, v31, s14, v143
	s_waitcnt lgkmcnt(0)
	v_fma_f32 v32, v32, s14, v144
	v_fma_f32 v33, v33, s14, v145
	s_add_i32 s62, s23, 5
	s_add_i32 s63, s62, 7
	v_sub_u32_e32 v217, s63, v206
	v_med3_i32 v217, v217, 0, 14
	v_mul_u32_u24_e32 v217, 31, v217
	v_add_u32_e32 v217, v217, v199
	v_lshlrev_b32_e32 v217, 2, v217
	v_add_u32_e32 v217, 110848, v217
	v_sub_u32_e32 v218, s62, v207
	v_cmp_gt_u32_e64 s[40:41], 8, v218
	s_nop 1
	v_cndmask_b32_e64 v230, v244, v217, s[40:41]
	ds_read2_b32 v[114:115], v230 offset0:0 offset1:1
	ds_read2_b32 v[116:117], v230 offset0:2 offset1:3
	ds_read2_b32 v[118:119], v230 offset0:4 offset1:5
	ds_read2_b32 v[120:121], v230 offset0:6 offset1:7
	ds_read2_b32 v[122:123], v230 offset0:16 offset1:17
	ds_read2_b32 v[124:125], v230 offset0:18 offset1:19
	ds_read2_b32 v[126:127], v230 offset0:20 offset1:21
	ds_read2_b32 v[128:129], v230 offset0:22 offset1:23
	s_waitcnt lgkmcnt(7)
	v_fma_f32 v34, v34, s14, v114
	v_fma_f32 v35, v35, s14, v115
	s_waitcnt lgkmcnt(6)
	v_fma_f32 v36, v36, s14, v116
	v_fma_f32 v37, v37, s14, v117
	s_waitcnt lgkmcnt(5)
	v_fma_f32 v38, v38, s14, v118
	v_fma_f32 v39, v39, s14, v119
	s_waitcnt lgkmcnt(4)
	v_fma_f32 v40, v40, s14, v120
	v_fma_f32 v41, v41, s14, v121
	s_waitcnt lgkmcnt(3)
	v_fma_f32 v42, v42, s14, v122
	v_fma_f32 v43, v43, s14, v123
	s_waitcnt lgkmcnt(2)
	v_fma_f32 v44, v44, s14, v124
	v_fma_f32 v45, v45, s14, v125
	s_waitcnt lgkmcnt(1)
	v_fma_f32 v46, v46, s14, v126
	v_fma_f32 v47, v47, s14, v127
	s_waitcnt lgkmcnt(0)
	v_fma_f32 v48, v48, s14, v128
	v_fma_f32 v49, v49, s14, v129
	v_max3_f32 v210, v2, v3, v4
	v_max3_f32 v219, v5, v6, v7
	v_max3_f32 v210, v210, v8, v9
	v_max3_f32 v219, v219, v10, v11
	v_max3_f32 v210, v210, v12, v13
	v_max3_f32 v219, v219, v14, v15
	v_max3_f32 v210, v210, v16, v17
	v_max3_f32 v219, v219, v18, v19
	v_max3_f32 v210, v210, v20, v21
	v_max3_f32 v219, v219, v22, v23
	v_max3_f32 v210, v210, v24, v25
	v_max3_f32 v219, v219, v26, v27
	v_max3_f32 v210, v210, v28, v29
	v_max3_f32 v219, v219, v30, v31
	v_max3_f32 v210, v210, v32, v33
	v_max3_f32 v219, v219, v34, v35
	v_max3_f32 v210, v210, v36, v37
	v_max3_f32 v219, v219, v38, v39
	v_max3_f32 v210, v210, v40, v41
	v_max3_f32 v219, v219, v42, v43
	v_max3_f32 v210, v210, v44, v45
	v_max3_f32 v219, v219, v46, v47
	v_max3_f32 v210, v210, v48, v49
	v_max_f32_e32 v210, v210, v219
	v_mov_b32_e32 v219, v210
	s_nop 1
	v_permlane32_swap_b32_e32 v210, v219
	v_max_f32_e32 v210, v210, v219
	v_max_f32_e32 v210, v210, v209
	v_sub_f32_e32 v211, v209, v210
	v_exp_f32_e32 v211, v211
	v_mov_b32_e32 v209, v210
	v_mul_f32_e32 v50, v50, v211
	v_mul_f32_e32 v51, v51, v211
	v_mul_f32_e32 v52, v52, v211
	v_mul_f32_e32 v53, v53, v211
	v_mul_f32_e32 v54, v54, v211
	v_mul_f32_e32 v55, v55, v211
	v_mul_f32_e32 v56, v56, v211
	v_mul_f32_e32 v57, v57, v211
	v_mul_f32_e32 v58, v58, v211
	v_mul_f32_e32 v59, v59, v211
	v_mul_f32_e32 v60, v60, v211
	v_mul_f32_e32 v61, v61, v211
	v_mul_f32_e32 v62, v62, v211
	v_mul_f32_e32 v63, v63, v211
	v_mul_f32_e32 v64, v64, v211
	v_mul_f32_e32 v65, v65, v211
	v_mul_f32_e32 v66, v66, v211
	v_mul_f32_e32 v67, v67, v211
	v_mul_f32_e32 v68, v68, v211
	v_mul_f32_e32 v69, v69, v211
	v_mul_f32_e32 v70, v70, v211
	v_mul_f32_e32 v71, v71, v211
	v_mul_f32_e32 v72, v72, v211
	v_mul_f32_e32 v73, v73, v211
	v_mul_f32_e32 v74, v74, v211
	v_mul_f32_e32 v75, v75, v211
	v_mul_f32_e32 v76, v76, v211
	v_mul_f32_e32 v77, v77, v211
	v_mul_f32_e32 v78, v78, v211
	v_mul_f32_e32 v79, v79, v211
	v_mul_f32_e32 v80, v80, v211
	v_mul_f32_e32 v81, v81, v211
	v_mul_f32_e32 v212, v212, v211
	v_mov_b32_e32 v213, 0
	v_mov_b32_e32 v214, 0
	v_mov_b32_e32 v215, 0
	v_mov_b32_e32 v216, 0
	v_sub_f32_e32 v2, v2, v209
	v_sub_f32_e32 v3, v3, v209
	v_exp_f32_e32 v2, v2
	v_exp_f32_e32 v3, v3
	v_add_f32_e32 v213, v213, v2
	v_add_f32_e32 v214, v214, v3
	v_cvt_pk_bf16_f32 v2, v2, v3
	v_sub_f32_e32 v4, v4, v209
	v_sub_f32_e32 v5, v5, v209
	v_exp_f32_e32 v4, v4
	v_exp_f32_e32 v5, v5
	v_add_f32_e32 v215, v215, v4
	v_add_f32_e32 v216, v216, v5
	v_cvt_pk_bf16_f32 v3, v4, v5
	v_sub_f32_e32 v6, v6, v209
	v_sub_f32_e32 v7, v7, v209
	v_exp_f32_e32 v6, v6
	v_exp_f32_e32 v7, v7
	v_add_f32_e32 v213, v213, v6
	v_add_f32_e32 v214, v214, v7
	v_cvt_pk_bf16_f32 v4, v6, v7
	v_sub_f32_e32 v8, v8, v209
	v_sub_f32_e32 v9, v9, v209
	v_exp_f32_e32 v8, v8
	v_exp_f32_e32 v9, v9
	v_add_f32_e32 v215, v215, v8
	v_add_f32_e32 v216, v216, v9
	v_cvt_pk_bf16_f32 v5, v8, v9
	v_sub_f32_e32 v10, v10, v209
	v_sub_f32_e32 v11, v11, v209
	v_exp_f32_e32 v10, v10
	v_exp_f32_e32 v11, v11
	v_add_f32_e32 v213, v213, v10
	v_add_f32_e32 v214, v214, v11
	v_cvt_pk_bf16_f32 v10, v10, v11
	v_sub_f32_e32 v12, v12, v209
	v_sub_f32_e32 v13, v13, v209
	v_exp_f32_e32 v12, v12
	v_exp_f32_e32 v13, v13
	v_add_f32_e32 v215, v215, v12
	v_add_f32_e32 v216, v216, v13
	v_cvt_pk_bf16_f32 v11, v12, v13
	v_sub_f32_e32 v14, v14, v209
	v_sub_f32_e32 v15, v15, v209
	v_exp_f32_e32 v14, v14
	v_exp_f32_e32 v15, v15
	v_add_f32_e32 v213, v213, v14
	v_add_f32_e32 v214, v214, v15
	v_cvt_pk_bf16_f32 v12, v14, v15
	v_sub_f32_e32 v16, v16, v209
	v_sub_f32_e32 v17, v17, v209
	v_exp_f32_e32 v16, v16
	v_exp_f32_e32 v17, v17
	v_add_f32_e32 v215, v215, v16
	v_add_f32_e32 v216, v216, v17
	v_cvt_pk_bf16_f32 v13, v16, v17
	v_sub_f32_e32 v18, v18, v209
	v_sub_f32_e32 v19, v19, v209
	v_exp_f32_e32 v18, v18
	v_exp_f32_e32 v19, v19
	v_add_f32_e32 v213, v213, v18
	v_add_f32_e32 v214, v214, v19
	v_cvt_pk_bf16_f32 v18, v18, v19
	v_sub_f32_e32 v20, v20, v209
	v_sub_f32_e32 v21, v21, v209
	v_exp_f32_e32 v20, v20
	v_exp_f32_e32 v21, v21
	v_add_f32_e32 v215, v215, v20
	v_add_f32_e32 v216, v216, v21
	v_cvt_pk_bf16_f32 v19, v20, v21
	v_sub_f32_e32 v22, v22, v209
	v_sub_f32_e32 v23, v23, v209
	v_exp_f32_e32 v22, v22
	v_exp_f32_e32 v23, v23
	v_add_f32_e32 v213, v213, v22
	v_add_f32_e32 v214, v214, v23
	v_cvt_pk_bf16_f32 v20, v22, v23
	v_sub_f32_e32 v24, v24, v209
	v_sub_f32_e32 v25, v25, v209
	v_exp_f32_e32 v24, v24
	v_exp_f32_e32 v25, v25
	v_add_f32_e32 v215, v215, v24
	v_add_f32_e32 v216, v216, v25
	v_cvt_pk_bf16_f32 v21, v24, v25
	v_sub_f32_e32 v26, v26, v209
	v_sub_f32_e32 v27, v27, v209
	v_exp_f32_e32 v26, v26
	v_exp_f32_e32 v27, v27
	v_add_f32_e32 v213, v213, v26
	v_add_f32_e32 v214, v214, v27
	v_cvt_pk_bf16_f32 v26, v26, v27
	v_sub_f32_e32 v28, v28, v209
	v_sub_f32_e32 v29, v29, v209
	v_exp_f32_e32 v28, v28
	v_exp_f32_e32 v29, v29
	v_add_f32_e32 v215, v215, v28
	v_add_f32_e32 v216, v216, v29
	v_cvt_pk_bf16_f32 v27, v28, v29
	v_sub_f32_e32 v30, v30, v209
	v_sub_f32_e32 v31, v31, v209
	v_exp_f32_e32 v30, v30
	v_exp_f32_e32 v31, v31
	v_add_f32_e32 v213, v213, v30
	v_add_f32_e32 v214, v214, v31
	v_cvt_pk_bf16_f32 v28, v30, v31
	v_sub_f32_e32 v32, v32, v209
	v_sub_f32_e32 v33, v33, v209
	v_exp_f32_e32 v32, v32
	v_exp_f32_e32 v33, v33
	v_add_f32_e32 v215, v215, v32
	v_add_f32_e32 v216, v216, v33
	v_cvt_pk_bf16_f32 v29, v32, v33
	v_sub_f32_e32 v34, v34, v209
	v_sub_f32_e32 v35, v35, v209
	v_exp_f32_e32 v34, v34
	v_exp_f32_e32 v35, v35
	v_add_f32_e32 v213, v213, v34
	v_add_f32_e32 v214, v214, v35
	v_cvt_pk_bf16_f32 v34, v34, v35
	v_sub_f32_e32 v36, v36, v209
	v_sub_f32_e32 v37, v37, v209
	v_exp_f32_e32 v36, v36
	v_exp_f32_e32 v37, v37
	v_add_f32_e32 v215, v215, v36
	v_add_f32_e32 v216, v216, v37
	v_cvt_pk_bf16_f32 v35, v36, v37
	v_sub_f32_e32 v38, v38, v209
	v_sub_f32_e32 v39, v39, v209
	v_exp_f32_e32 v38, v38
	v_exp_f32_e32 v39, v39
	v_add_f32_e32 v213, v213, v38
	v_add_f32_e32 v214, v214, v39
	v_cvt_pk_bf16_f32 v36, v38, v39
	v_sub_f32_e32 v40, v40, v209
	v_sub_f32_e32 v41, v41, v209
	v_exp_f32_e32 v40, v40
	v_exp_f32_e32 v41, v41
	v_add_f32_e32 v215, v215, v40
	v_add_f32_e32 v216, v216, v41
	v_cvt_pk_bf16_f32 v37, v40, v41
	v_sub_f32_e32 v42, v42, v209
	v_sub_f32_e32 v43, v43, v209
	v_exp_f32_e32 v42, v42
	v_exp_f32_e32 v43, v43
	v_add_f32_e32 v213, v213, v42
	v_add_f32_e32 v214, v214, v43
	v_cvt_pk_bf16_f32 v42, v42, v43
	v_sub_f32_e32 v44, v44, v209
	v_sub_f32_e32 v45, v45, v209
	v_exp_f32_e32 v44, v44
	v_exp_f32_e32 v45, v45
	v_add_f32_e32 v215, v215, v44
	v_add_f32_e32 v216, v216, v45
	v_cvt_pk_bf16_f32 v43, v44, v45
	v_sub_f32_e32 v46, v46, v209
	v_sub_f32_e32 v47, v47, v209
	v_exp_f32_e32 v46, v46
	v_exp_f32_e32 v47, v47
	v_add_f32_e32 v213, v213, v46
	v_add_f32_e32 v214, v214, v47
	v_cvt_pk_bf16_f32 v44, v46, v47
	v_sub_f32_e32 v48, v48, v209
	v_sub_f32_e32 v49, v49, v209
	v_exp_f32_e32 v48, v48
	v_exp_f32_e32 v49, v49
	v_add_f32_e32 v215, v215, v48
	v_add_f32_e32 v216, v216, v49
	v_cvt_pk_bf16_f32 v45, v48, v49
	v_add_f32_e32 v213, v213, v214
	v_add_f32_e32 v215, v215, v216
	v_add_f32_e32 v213, v213, v215
	v_add_f32_e32 v212, v212, v213
	ds_read_b64_tr_b16 v[114:115], v243 offset:46080
	ds_read_b64_tr_b16 v[116:117], v243 offset:46656
	ds_read_b64_tr_b16 v[118:119], v243 offset:46144
	ds_read_b64_tr_b16 v[120:121], v243 offset:46720
	ds_read_b64_tr_b16 v[122:123], v243 offset:48384
	ds_read_b64_tr_b16 v[124:125], v243 offset:48960
	ds_read_b64_tr_b16 v[126:127], v243 offset:48448
	ds_read_b64_tr_b16 v[128:129], v243 offset:49024
	ds_read_b64_tr_b16 v[130:131], v201 offset:9216
	ds_read_b64_tr_b16 v[132:133], v201 offset:9792
	ds_read_b64_tr_b16 v[134:135], v201 offset:9280
	ds_read_b64_tr_b16 v[136:137], v201 offset:9856
	s_waitcnt lgkmcnt(10)
	v_mfma_f32_32x32x16_bf16 v[50:65], v[114:117], v[2:5], v[50:65]
	s_waitcnt lgkmcnt(8)
	v_mfma_f32_32x32x16_bf16 v[66:81], v[118:121], v[2:5], v[66:81]
	ds_read_b64_tr_b16 v[138:139], v201 offset:11520
	ds_read_b64_tr_b16 v[140:141], v201 offset:12096
	ds_read_b64_tr_b16 v[142:143], v201 offset:11584
	ds_read_b64_tr_b16 v[144:145], v201 offset:12160
	s_waitcnt lgkmcnt(10)
	v_mfma_f32_32x32x16_bf16 v[50:65], v[122:125], v[10:13], v[50:65]
	s_waitcnt lgkmcnt(8)
	v_mfma_f32_32x32x16_bf16 v[66:81], v[126:129], v[10:13], v[66:81]
	ds_read_b64_tr_b16 v[114:115], v201 offset:27648
	ds_read_b64_tr_b16 v[116:117], v201 offset:28224
	ds_read_b64_tr_b16 v[118:119], v201 offset:27712
	ds_read_b64_tr_b16 v[120:121], v201 offset:28288
	s_waitcnt lgkmcnt(10)
	v_mfma_f32_32x32x16_bf16 v[50:65], v[130:133], v[18:21], v[50:65]
	s_waitcnt lgkmcnt(8)
	v_mfma_f32_32x32x16_bf16 v[66:81], v[134:137], v[18:21], v[66:81]
	ds_read_b64_tr_b16 v[122:123], v201 offset:29952
	ds_read_b64_tr_b16 v[124:125], v201 offset:30528
	ds_read_b64_tr_b16 v[126:127], v201 offset:30016
	ds_read_b64_tr_b16 v[128:129], v201 offset:30592
	s_waitcnt lgkmcnt(10)
	v_mfma_f32_32x32x16_bf16 v[50:65], v[138:141], v[26:29], v[50:65]
	s_waitcnt lgkmcnt(8)
	v_mfma_f32_32x32x16_bf16 v[66:81], v[142:145], v[26:29], v[66:81]
	s_waitcnt lgkmcnt(6)
	v_mfma_f32_32x32x16_bf16 v[50:65], v[114:117], v[34:37], v[50:65]
	s_waitcnt lgkmcnt(4)
	v_mfma_f32_32x32x16_bf16 v[66:81], v[118:121], v[34:37], v[66:81]
	s_waitcnt lgkmcnt(2)
	v_mfma_f32_32x32x16_bf16 v[50:65], v[122:125], v[42:45], v[50:65]
	s_waitcnt lgkmcnt(0)
	v_mfma_f32_32x32x16_bf16 v[66:81], v[126:129], v[42:45], v[66:81]
	s_nop 7
	s_nop 4
	ds_read_b128 v[114:117], v200 offset:36864
	ds_read_b128 v[118:121], v200 offset:36896
	ds_read_b128 v[122:125], v200 offset:36928
	ds_read_b128 v[126:129], v200 offset:36960
	ds_read_b128 v[130:133], v242
	ds_read_b128 v[134:137], v242 offset:32
	ds_read_b128 v[138:141], v242 offset:64
	ds_read_b128 v[142:145], v242 offset:96
	s_waitcnt lgkmcnt(7)
	v_mfma_f32_32x32x16_bf16 v[2:17], v[114:117], v[82:85], v[98:113]
	s_waitcnt lgkmcnt(6)
	v_mfma_f32_32x32x16_bf16 v[2:17], v[118:121], v[86:89], v[2:17]
	s_waitcnt lgkmcnt(5)
	v_mfma_f32_32x32x16_bf16 v[2:17], v[122:125], v[90:93], v[2:17]
	s_waitcnt lgkmcnt(4)
	v_mfma_f32_32x32x16_bf16 v[2:17], v[126:129], v[94:97], v[2:17]
	ds_read_b128 v[114:117], v242 offset:18432
	ds_read_b128 v[118:121], v242 offset:18464
	ds_read_b128 v[122:125], v242 offset:18496
	ds_read_b128 v[126:129], v242 offset:18528
	s_waitcnt lgkmcnt(7)
	v_mfma_f32_32x32x16_bf16 v[18:33], v[130:133], v[82:85], v[98:113]
	s_waitcnt lgkmcnt(6)
	v_mfma_f32_32x32x16_bf16 v[18:33], v[134:137], v[86:89], v[18:33]
	s_waitcnt lgkmcnt(5)
	v_mfma_f32_32x32x16_bf16 v[18:33], v[138:141], v[90:93], v[18:33]
	s_waitcnt lgkmcnt(4)
	v_mfma_f32_32x32x16_bf16 v[18:33], v[142:145], v[94:97], v[18:33]
	s_waitcnt lgkmcnt(3)
	v_mfma_f32_32x32x16_bf16 v[34:49], v[114:117], v[82:85], v[98:113]
	s_waitcnt lgkmcnt(2)
	v_mfma_f32_32x32x16_bf16 v[34:49], v[118:121], v[86:89], v[34:49]
	s_waitcnt lgkmcnt(1)
	v_mfma_f32_32x32x16_bf16 v[34:49], v[122:125], v[90:93], v[34:49]
	s_waitcnt lgkmcnt(0)
	v_mfma_f32_32x32x16_bf16 v[34:49], v[126:129], v[94:97], v[34:49]
	s_add_i32 s62, s23, 6
	s_add_i32 s63, s62, 7
	v_sub_u32_e32 v217, s63, v206
	v_med3_i32 v217, v217, 0, 14
	v_mul_u32_u24_e32 v217, 31, v217
	v_add_u32_e32 v217, v217, v199
	v_lshlrev_b32_e32 v217, 2, v217
	v_add_u32_e32 v217, 110848, v217
	v_sub_u32_e32 v218, s62, v207
	v_cmp_gt_u32_e64 s[40:41], 8, v218
	s_nop 1
	v_cndmask_b32_e64 v230, v244, v217, s[40:41]
	ds_read2_b32 v[114:115], v230 offset0:0 offset1:1
	ds_read2_b32 v[116:117], v230 offset0:2 offset1:3
	ds_read2_b32 v[118:119], v230 offset0:4 offset1:5
	ds_read2_b32 v[120:121], v230 offset0:6 offset1:7
	ds_read2_b32 v[122:123], v230 offset0:16 offset1:17
	ds_read2_b32 v[124:125], v230 offset0:18 offset1:19
	ds_read2_b32 v[126:127], v230 offset0:20 offset1:21
	ds_read2_b32 v[128:129], v230 offset0:22 offset1:23
	s_waitcnt lgkmcnt(7)
	v_fma_f32 v2, v2, s14, v114
	v_fma_f32 v3, v3, s14, v115
	s_waitcnt lgkmcnt(6)
	v_fma_f32 v4, v4, s14, v116
	v_fma_f32 v5, v5, s14, v117
	s_waitcnt lgkmcnt(5)
	v_fma_f32 v6, v6, s14, v118
	v_fma_f32 v7, v7, s14, v119
	s_waitcnt lgkmcnt(4)
	v_fma_f32 v8, v8, s14, v120
	v_fma_f32 v9, v9, s14, v121
	s_waitcnt lgkmcnt(3)
	v_fma_f32 v10, v10, s14, v122
	v_fma_f32 v11, v11, s14, v123
	s_waitcnt lgkmcnt(2)
	v_fma_f32 v12, v12, s14, v124
	v_fma_f32 v13, v13, s14, v125
	s_waitcnt lgkmcnt(1)
	v_fma_f32 v14, v14, s14, v126
	v_fma_f32 v15, v15, s14, v127
	s_waitcnt lgkmcnt(0)
	v_fma_f32 v16, v16, s14, v128
	v_fma_f32 v17, v17, s14, v129
	s_add_i32 s62, s23, 7
	s_add_i32 s63, s62, 7
	v_sub_u32_e32 v217, s63, v206
	v_med3_i32 v217, v217, 0, 14
	v_mul_u32_u24_e32 v217, 31, v217
	v_add_u32_e32 v217, v217, v199
	v_lshlrev_b32_e32 v217, 2, v217
	v_add_u32_e32 v217, 110848, v217
	v_sub_u32_e32 v218, s62, v207
	v_cmp_gt_u32_e64 s[40:41], 8, v218
	s_nop 1
	v_cndmask_b32_e64 v230, v244, v217, s[40:41]
	ds_read2_b32 v[130:131], v230 offset0:0 offset1:1
	ds_read2_b32 v[132:133], v230 offset0:2 offset1:3
	ds_read2_b32 v[134:135], v230 offset0:4 offset1:5
	ds_read2_b32 v[136:137], v230 offset0:6 offset1:7
	ds_read2_b32 v[138:139], v230 offset0:16 offset1:17
	ds_read2_b32 v[140:141], v230 offset0:18 offset1:19
	ds_read2_b32 v[142:143], v230 offset0:20 offset1:21
	ds_read2_b32 v[144:145], v230 offset0:22 offset1:23
	s_waitcnt lgkmcnt(7)
	v_fma_f32 v18, v18, s14, v130
	v_fma_f32 v19, v19, s14, v131
	s_waitcnt lgkmcnt(6)
	v_fma_f32 v20, v20, s14, v132
	v_fma_f32 v21, v21, s14, v133
	s_waitcnt lgkmcnt(5)
	v_fma_f32 v22, v22, s14, v134
	v_fma_f32 v23, v23, s14, v135
	s_waitcnt lgkmcnt(4)
	v_fma_f32 v24, v24, s14, v136
	v_fma_f32 v25, v25, s14, v137
	s_waitcnt lgkmcnt(3)
	v_fma_f32 v26, v26, s14, v138
	v_fma_f32 v27, v27, s14, v139
	s_waitcnt lgkmcnt(2)
	v_fma_f32 v28, v28, s14, v140
	v_fma_f32 v29, v29, s14, v141
	s_waitcnt lgkmcnt(1)
	v_fma_f32 v30, v30, s14, v142
	v_fma_f32 v31, v31, s14, v143
	s_waitcnt lgkmcnt(0)
	v_fma_f32 v32, v32, s14, v144
	v_fma_f32 v33, v33, s14, v145
	s_add_i32 s62, s23, 8
	s_add_i32 s63, s62, 7
	v_sub_u32_e32 v217, s63, v206
	v_med3_i32 v217, v217, 0, 14
	v_mul_u32_u24_e32 v217, 31, v217
	v_add_u32_e32 v217, v217, v199
	v_lshlrev_b32_e32 v217, 2, v217
	v_add_u32_e32 v217, 110848, v217
	v_sub_u32_e32 v218, s62, v207
	v_cmp_gt_u32_e64 s[40:41], 8, v218
	s_nop 1
	v_cndmask_b32_e64 v230, v244, v217, s[40:41]
	ds_read2_b32 v[114:115], v230 offset0:0 offset1:1
	ds_read2_b32 v[116:117], v230 offset0:2 offset1:3
	ds_read2_b32 v[118:119], v230 offset0:4 offset1:5
	ds_read2_b32 v[120:121], v230 offset0:6 offset1:7
	ds_read2_b32 v[122:123], v230 offset0:16 offset1:17
	ds_read2_b32 v[124:125], v230 offset0:18 offset1:19
	ds_read2_b32 v[126:127], v230 offset0:20 offset1:21
	ds_read2_b32 v[128:129], v230 offset0:22 offset1:23
	s_waitcnt lgkmcnt(7)
	v_fma_f32 v34, v34, s14, v114
	v_fma_f32 v35, v35, s14, v115
	s_waitcnt lgkmcnt(6)
	v_fma_f32 v36, v36, s14, v116
	v_fma_f32 v37, v37, s14, v117
	s_waitcnt lgkmcnt(5)
	v_fma_f32 v38, v38, s14, v118
	v_fma_f32 v39, v39, s14, v119
	s_waitcnt lgkmcnt(4)
	v_fma_f32 v40, v40, s14, v120
	v_fma_f32 v41, v41, s14, v121
	s_waitcnt lgkmcnt(3)
	v_fma_f32 v42, v42, s14, v122
	v_fma_f32 v43, v43, s14, v123
	s_waitcnt lgkmcnt(2)
	v_fma_f32 v44, v44, s14, v124
	v_fma_f32 v45, v45, s14, v125
	s_waitcnt lgkmcnt(1)
	v_fma_f32 v46, v46, s14, v126
	v_fma_f32 v47, v47, s14, v127
	s_waitcnt lgkmcnt(0)
	v_fma_f32 v48, v48, s14, v128
	v_fma_f32 v49, v49, s14, v129
	v_max3_f32 v210, v2, v3, v4
	v_max3_f32 v219, v5, v6, v7
	v_max3_f32 v210, v210, v8, v9
	v_max3_f32 v219, v219, v10, v11
	v_max3_f32 v210, v210, v12, v13
	v_max3_f32 v219, v219, v14, v15
	v_max3_f32 v210, v210, v16, v17
	v_max3_f32 v219, v219, v18, v19
	v_max3_f32 v210, v210, v20, v21
	v_max3_f32 v219, v219, v22, v23
	v_max3_f32 v210, v210, v24, v25
	v_max3_f32 v219, v219, v26, v27
	v_max3_f32 v210, v210, v28, v29
	v_max3_f32 v219, v219, v30, v31
	v_max3_f32 v210, v210, v32, v33
	v_max3_f32 v219, v219, v34, v35
	v_max3_f32 v210, v210, v36, v37
	v_max3_f32 v219, v219, v38, v39
	v_max3_f32 v210, v210, v40, v41
	v_max3_f32 v219, v219, v42, v43
	v_max3_f32 v210, v210, v44, v45
	v_max3_f32 v219, v219, v46, v47
	v_max3_f32 v210, v210, v48, v49
	v_max_f32_e32 v210, v210, v219
	v_mov_b32_e32 v219, v210
	s_nop 1
	v_permlane32_swap_b32_e32 v210, v219
	v_max_f32_e32 v210, v210, v219
	v_max_f32_e32 v210, v210, v209
	v_sub_f32_e32 v211, v209, v210
	v_exp_f32_e32 v211, v211
	v_mov_b32_e32 v209, v210
	v_mul_f32_e32 v50, v50, v211
	v_mul_f32_e32 v51, v51, v211
	v_mul_f32_e32 v52, v52, v211
	v_mul_f32_e32 v53, v53, v211
	v_mul_f32_e32 v54, v54, v211
	v_mul_f32_e32 v55, v55, v211
	v_mul_f32_e32 v56, v56, v211
	v_mul_f32_e32 v57, v57, v211
	v_mul_f32_e32 v58, v58, v211
	v_mul_f32_e32 v59, v59, v211
	v_mul_f32_e32 v60, v60, v211
	v_mul_f32_e32 v61, v61, v211
	v_mul_f32_e32 v62, v62, v211
	v_mul_f32_e32 v63, v63, v211
	v_mul_f32_e32 v64, v64, v211
	v_mul_f32_e32 v65, v65, v211
	v_mul_f32_e32 v66, v66, v211
	v_mul_f32_e32 v67, v67, v211
	v_mul_f32_e32 v68, v68, v211
	v_mul_f32_e32 v69, v69, v211
	v_mul_f32_e32 v70, v70, v211
	v_mul_f32_e32 v71, v71, v211
	v_mul_f32_e32 v72, v72, v211
	v_mul_f32_e32 v73, v73, v211
	v_mul_f32_e32 v74, v74, v211
	v_mul_f32_e32 v75, v75, v211
	v_mul_f32_e32 v76, v76, v211
	v_mul_f32_e32 v77, v77, v211
	v_mul_f32_e32 v78, v78, v211
	v_mul_f32_e32 v79, v79, v211
	v_mul_f32_e32 v80, v80, v211
	v_mul_f32_e32 v81, v81, v211
	v_mul_f32_e32 v212, v212, v211
	v_mov_b32_e32 v213, 0
	v_mov_b32_e32 v214, 0
	v_mov_b32_e32 v215, 0
	v_mov_b32_e32 v216, 0
	v_sub_f32_e32 v2, v2, v209
	v_sub_f32_e32 v3, v3, v209
	v_exp_f32_e32 v2, v2
	v_exp_f32_e32 v3, v3
	v_add_f32_e32 v213, v213, v2
	v_add_f32_e32 v214, v214, v3
	v_cvt_pk_bf16_f32 v2, v2, v3
	v_sub_f32_e32 v4, v4, v209
	v_sub_f32_e32 v5, v5, v209
	v_exp_f32_e32 v4, v4
	v_exp_f32_e32 v5, v5
	v_add_f32_e32 v215, v215, v4
	v_add_f32_e32 v216, v216, v5
	v_cvt_pk_bf16_f32 v3, v4, v5
	v_sub_f32_e32 v6, v6, v209
	v_sub_f32_e32 v7, v7, v209
	v_exp_f32_e32 v6, v6
	v_exp_f32_e32 v7, v7
	v_add_f32_e32 v213, v213, v6
	v_add_f32_e32 v214, v214, v7
	v_cvt_pk_bf16_f32 v4, v6, v7
	v_sub_f32_e32 v8, v8, v209
	v_sub_f32_e32 v9, v9, v209
	v_exp_f32_e32 v8, v8
	v_exp_f32_e32 v9, v9
	v_add_f32_e32 v215, v215, v8
	v_add_f32_e32 v216, v216, v9
	v_cvt_pk_bf16_f32 v5, v8, v9
	v_sub_f32_e32 v10, v10, v209
	v_sub_f32_e32 v11, v11, v209
	v_exp_f32_e32 v10, v10
	v_exp_f32_e32 v11, v11
	v_add_f32_e32 v213, v213, v10
	v_add_f32_e32 v214, v214, v11
	v_cvt_pk_bf16_f32 v10, v10, v11
	v_sub_f32_e32 v12, v12, v209
	v_sub_f32_e32 v13, v13, v209
	v_exp_f32_e32 v12, v12
	v_exp_f32_e32 v13, v13
	v_add_f32_e32 v215, v215, v12
	v_add_f32_e32 v216, v216, v13
	v_cvt_pk_bf16_f32 v11, v12, v13
	v_sub_f32_e32 v14, v14, v209
	v_sub_f32_e32 v15, v15, v209
	v_exp_f32_e32 v14, v14
	v_exp_f32_e32 v15, v15
	v_add_f32_e32 v213, v213, v14
	v_add_f32_e32 v214, v214, v15
	v_cvt_pk_bf16_f32 v12, v14, v15
	v_sub_f32_e32 v16, v16, v209
	v_sub_f32_e32 v17, v17, v209
	v_exp_f32_e32 v16, v16
	v_exp_f32_e32 v17, v17
	v_add_f32_e32 v215, v215, v16
	v_add_f32_e32 v216, v216, v17
	v_cvt_pk_bf16_f32 v13, v16, v17
	v_sub_f32_e32 v18, v18, v209
	v_sub_f32_e32 v19, v19, v209
	v_exp_f32_e32 v18, v18
	v_exp_f32_e32 v19, v19
	v_add_f32_e32 v213, v213, v18
	v_add_f32_e32 v214, v214, v19
	v_cvt_pk_bf16_f32 v18, v18, v19
	v_sub_f32_e32 v20, v20, v209
	v_sub_f32_e32 v21, v21, v209
	v_exp_f32_e32 v20, v20
	v_exp_f32_e32 v21, v21
	v_add_f32_e32 v215, v215, v20
	v_add_f32_e32 v216, v216, v21
	v_cvt_pk_bf16_f32 v19, v20, v21
	v_sub_f32_e32 v22, v22, v209
	v_sub_f32_e32 v23, v23, v209
	v_exp_f32_e32 v22, v22
	v_exp_f32_e32 v23, v23
	v_add_f32_e32 v213, v213, v22
	v_add_f32_e32 v214, v214, v23
	v_cvt_pk_bf16_f32 v20, v22, v23
	v_sub_f32_e32 v24, v24, v209
	v_sub_f32_e32 v25, v25, v209
	v_exp_f32_e32 v24, v24
	v_exp_f32_e32 v25, v25
	v_add_f32_e32 v215, v215, v24
	v_add_f32_e32 v216, v216, v25
	v_cvt_pk_bf16_f32 v21, v24, v25
	v_sub_f32_e32 v26, v26, v209
	v_sub_f32_e32 v27, v27, v209
	v_exp_f32_e32 v26, v26
	v_exp_f32_e32 v27, v27
	v_add_f32_e32 v213, v213, v26
	v_add_f32_e32 v214, v214, v27
	v_cvt_pk_bf16_f32 v26, v26, v27
	v_sub_f32_e32 v28, v28, v209
	v_sub_f32_e32 v29, v29, v209
	v_exp_f32_e32 v28, v28
	v_exp_f32_e32 v29, v29
	v_add_f32_e32 v215, v215, v28
	v_add_f32_e32 v216, v216, v29
	v_cvt_pk_bf16_f32 v27, v28, v29
	v_sub_f32_e32 v30, v30, v209
	v_sub_f32_e32 v31, v31, v209
	v_exp_f32_e32 v30, v30
	v_exp_f32_e32 v31, v31
	v_add_f32_e32 v213, v213, v30
	v_add_f32_e32 v214, v214, v31
	v_cvt_pk_bf16_f32 v28, v30, v31
	v_sub_f32_e32 v32, v32, v209
	v_sub_f32_e32 v33, v33, v209
	v_exp_f32_e32 v32, v32
	v_exp_f32_e32 v33, v33
	v_add_f32_e32 v215, v215, v32
	v_add_f32_e32 v216, v216, v33
	v_cvt_pk_bf16_f32 v29, v32, v33
	v_sub_f32_e32 v34, v34, v209
	v_sub_f32_e32 v35, v35, v209
	v_exp_f32_e32 v34, v34
	v_exp_f32_e32 v35, v35
	v_add_f32_e32 v213, v213, v34
	v_add_f32_e32 v214, v214, v35
	v_cvt_pk_bf16_f32 v34, v34, v35
	v_sub_f32_e32 v36, v36, v209
	v_sub_f32_e32 v37, v37, v209
	v_exp_f32_e32 v36, v36
	v_exp_f32_e32 v37, v37
	v_add_f32_e32 v215, v215, v36
	v_add_f32_e32 v216, v216, v37
	v_cvt_pk_bf16_f32 v35, v36, v37
	v_sub_f32_e32 v38, v38, v209
	v_sub_f32_e32 v39, v39, v209
	v_exp_f32_e32 v38, v38
	v_exp_f32_e32 v39, v39
	v_add_f32_e32 v213, v213, v38
	v_add_f32_e32 v214, v214, v39
	v_cvt_pk_bf16_f32 v36, v38, v39
	v_sub_f32_e32 v40, v40, v209
	v_sub_f32_e32 v41, v41, v209
	v_exp_f32_e32 v40, v40
	v_exp_f32_e32 v41, v41
	v_add_f32_e32 v215, v215, v40
	v_add_f32_e32 v216, v216, v41
	v_cvt_pk_bf16_f32 v37, v40, v41
	v_sub_f32_e32 v42, v42, v209
	v_sub_f32_e32 v43, v43, v209
	v_exp_f32_e32 v42, v42
	v_exp_f32_e32 v43, v43
	v_add_f32_e32 v213, v213, v42
	v_add_f32_e32 v214, v214, v43
	v_cvt_pk_bf16_f32 v42, v42, v43
	v_sub_f32_e32 v44, v44, v209
	v_sub_f32_e32 v45, v45, v209
	v_exp_f32_e32 v44, v44
	v_exp_f32_e32 v45, v45
	v_add_f32_e32 v215, v215, v44
	v_add_f32_e32 v216, v216, v45
	v_cvt_pk_bf16_f32 v43, v44, v45
	v_sub_f32_e32 v46, v46, v209
	v_sub_f32_e32 v47, v47, v209
	v_exp_f32_e32 v46, v46
	v_exp_f32_e32 v47, v47
	v_add_f32_e32 v213, v213, v46
	v_add_f32_e32 v214, v214, v47
	v_cvt_pk_bf16_f32 v44, v46, v47
	v_sub_f32_e32 v48, v48, v209
	v_sub_f32_e32 v49, v49, v209
	v_exp_f32_e32 v48, v48
	v_exp_f32_e32 v49, v49
	v_add_f32_e32 v215, v215, v48
	v_add_f32_e32 v216, v216, v49
	v_cvt_pk_bf16_f32 v45, v48, v49
	v_add_f32_e32 v213, v213, v214
	v_add_f32_e32 v215, v215, v216
	v_add_f32_e32 v213, v213, v215
	v_add_f32_e32 v212, v212, v213
	ds_read_b64_tr_b16 v[114:115], v201 offset:46080
	ds_read_b64_tr_b16 v[116:117], v201 offset:46656
	ds_read_b64_tr_b16 v[118:119], v201 offset:46144
	ds_read_b64_tr_b16 v[120:121], v201 offset:46720
	ds_read_b64_tr_b16 v[122:123], v201 offset:48384
	ds_read_b64_tr_b16 v[124:125], v201 offset:48960
	ds_read_b64_tr_b16 v[126:127], v201 offset:48448
	ds_read_b64_tr_b16 v[128:129], v201 offset:49024
	ds_read_b64_tr_b16 v[130:131], v243 offset:9216
	ds_read_b64_tr_b16 v[132:133], v243 offset:9792
	ds_read_b64_tr_b16 v[134:135], v243 offset:9280
	ds_read_b64_tr_b16 v[136:137], v243 offset:9856
	s_waitcnt lgkmcnt(10)
	v_mfma_f32_32x32x16_bf16 v[50:65], v[114:117], v[2:5], v[50:65]
	s_waitcnt lgkmcnt(8)
	v_mfma_f32_32x32x16_bf16 v[66:81], v[118:121], v[2:5], v[66:81]
	ds_read_b64_tr_b16 v[138:139], v243 offset:11520
	ds_read_b64_tr_b16 v[140:141], v243 offset:12096
	ds_read_b64_tr_b16 v[142:143], v243 offset:11584
	ds_read_b64_tr_b16 v[144:145], v243 offset:12160
	s_waitcnt lgkmcnt(10)
	v_mfma_f32_32x32x16_bf16 v[50:65], v[122:125], v[10:13], v[50:65]
	s_waitcnt lgkmcnt(8)
	v_mfma_f32_32x32x16_bf16 v[66:81], v[126:129], v[10:13], v[66:81]
	ds_read_b64_tr_b16 v[114:115], v243 offset:27648
	ds_read_b64_tr_b16 v[116:117], v243 offset:28224
	ds_read_b64_tr_b16 v[118:119], v243 offset:27712
	ds_read_b64_tr_b16 v[120:121], v243 offset:28288
	s_waitcnt lgkmcnt(10)
	v_mfma_f32_32x32x16_bf16 v[50:65], v[130:133], v[18:21], v[50:65]
	s_waitcnt lgkmcnt(8)
	v_mfma_f32_32x32x16_bf16 v[66:81], v[134:137], v[18:21], v[66:81]
	ds_read_b64_tr_b16 v[122:123], v243 offset:29952
	ds_read_b64_tr_b16 v[124:125], v243 offset:30528
	ds_read_b64_tr_b16 v[126:127], v243 offset:30016
	ds_read_b64_tr_b16 v[128:129], v243 offset:30592
	s_waitcnt lgkmcnt(10)
	v_mfma_f32_32x32x16_bf16 v[50:65], v[138:141], v[26:29], v[50:65]
	s_waitcnt lgkmcnt(8)
	v_mfma_f32_32x32x16_bf16 v[66:81], v[142:145], v[26:29], v[66:81]
	s_waitcnt lgkmcnt(6)
	v_mfma_f32_32x32x16_bf16 v[50:65], v[114:117], v[34:37], v[50:65]
	s_waitcnt lgkmcnt(4)
	v_mfma_f32_32x32x16_bf16 v[66:81], v[118:121], v[34:37], v[66:81]
	s_waitcnt lgkmcnt(2)
	v_mfma_f32_32x32x16_bf16 v[50:65], v[122:125], v[42:45], v[50:65]
	s_waitcnt lgkmcnt(0)
	v_mfma_f32_32x32x16_bf16 v[66:81], v[126:129], v[42:45], v[66:81]
.Lna_p2_end:
	s_cmp_le_u32 s20, 1
	s_cbranch_scc1 .Lna_noq
	s_cmpk_gt_i32 s33, 0x7ff
	s_cbranch_scc1 .Lna_noq
	v_lshrrev_b32_e32 v217, 4, v196
	v_add_u32_e32 v217, s26, v217
	v_lshl_add_u32 v217, v217, 6, v198
	v_mul_u32_u24_e32 v217, 0x1800, v217
	v_lshl_add_u32 v217, v197, 4, v217
	global_load_dwordx4 v[82:85], v217, s[4:5]
	global_load_dwordx4 v[86:89], v217, s[4:5] offset:32
	global_load_dwordx4 v[90:93], v217, s[4:5] offset:64
	global_load_dwordx4 v[94:97], v217, s[4:5] offset:96
.Lna_noq:
	s_nop 7
	s_nop 4
	v_mov_b32_e32 v214, v212
	s_nop 1
	v_permlane32_swap_b32_e32 v212, v214
	v_add_f32_e32 v212, v212, v214
	v_rcp_f32_e32 v214, v212
	s_nop 0
	v_fma_f32 v216, -v212, v214, 2.0
	v_mul_f32_e32 v214, v214, v216
	v_mul_f32_e32 v50, v50, v214
	v_mul_f32_e32 v51, v51, v214
	v_mul_f32_e32 v52, v52, v214
	v_mul_f32_e32 v53, v53, v214
	v_mul_f32_e32 v54, v54, v214
	v_mul_f32_e32 v55, v55, v214
	v_mul_f32_e32 v56, v56, v214
	v_mul_f32_e32 v57, v57, v214
	v_mul_f32_e32 v58, v58, v214
	v_mul_f32_e32 v59, v59, v214
	v_mul_f32_e32 v60, v60, v214
	v_mul_f32_e32 v61, v61, v214
	v_mul_f32_e32 v62, v62, v214
	v_mul_f32_e32 v63, v63, v214
	v_mul_f32_e32 v64, v64, v214
	v_mul_f32_e32 v65, v65, v214
	v_mul_f32_e32 v66, v66, v214
	v_mul_f32_e32 v67, v67, v214
	v_mul_f32_e32 v68, v68, v214
	v_mul_f32_e32 v69, v69, v214
	v_mul_f32_e32 v70, v70, v214
	v_mul_f32_e32 v71, v71, v214
	v_mul_f32_e32 v72, v72, v214
	v_mul_f32_e32 v73, v73, v214
	v_mul_f32_e32 v74, v74, v214
	v_mul_f32_e32 v75, v75, v214
	v_mul_f32_e32 v76, v76, v214
	v_mul_f32_e32 v77, v77, v214
	v_mul_f32_e32 v78, v78, v214
	v_mul_f32_e32 v79, v79, v214
	v_mul_f32_e32 v80, v80, v214
	v_mul_f32_e32 v81, v81, v214
	v_lshlrev_b32_e32 v217, 11, v208
	v_lshl_add_u32 v217, v197, 4, v217
	v_cvt_pk_bf16_f32 v234, v50, v51
	v_cvt_pk_bf16_f32 v235, v52, v53
	v_cvt_pk_bf16_f32 v236, v54, v55
	v_cvt_pk_bf16_f32 v237, v56, v57
	s_nop 1
	v_permlane32_swap_b32_e32 v234, v236
	v_permlane32_swap_b32_e32 v235, v237
	global_store_dwordx4 v217, v[234:237], s[16:17] offset:0
	v_cvt_pk_bf16_f32 v238, v58, v59
	v_cvt_pk_bf16_f32 v239, v60, v61
	v_cvt_pk_bf16_f32 v240, v62, v63
	v_cvt_pk_bf16_f32 v241, v64, v65
	s_nop 1
	v_permlane32_swap_b32_e32 v238, v240
	v_permlane32_swap_b32_e32 v239, v241
	global_store_dwordx4 v217, v[238:241], s[16:17] offset:32
	v_cvt_pk_bf16_f32 v234, v66, v67
	v_cvt_pk_bf16_f32 v235, v68, v69
	v_cvt_pk_bf16_f32 v236, v70, v71
	v_cvt_pk_bf16_f32 v237, v72, v73
	s_nop 1
	v_permlane32_swap_b32_e32 v234, v236
	v_permlane32_swap_b32_e32 v235, v237
	global_store_dwordx4 v217, v[234:237], s[16:17] offset:64
	v_cvt_pk_bf16_f32 v238, v74, v75
	v_cvt_pk_bf16_f32 v239, v76, v77
	v_cvt_pk_bf16_f32 v240, v78, v79
	v_cvt_pk_bf16_f32 v241, v80, v81
	s_nop 1
	v_permlane32_swap_b32_e32 v238, v240
	v_permlane32_swap_b32_e32 v239, v241
	global_store_dwordx4 v217, v[238:241], s[16:17] offset:96
	s_add_i32 s21, s21, 1
	s_add_i32 s20, s20, -1
	s_cmp_eq_u32 s20, 0
	s_cbranch_scc1 .Lna_done
	s_cmpk_gt_i32 s21, 0x7ff
	s_cbranch_scc0 .Lna_unit
.Lna_done:
.LBB0_963:
	s_cmp_lt_i32 s73, 15
	s_cbranch_scc1 .LBB0_1013
	s_waitcnt vmcnt(0)
	v_cmp_eq_u32_e32 vcc, 0, v0
	s_waitcnt vmcnt(0) lgkmcnt(0)
	s_barrier
	s_and_saveexec_b64 s[0:1], vcc
	s_cbranch_execz .LBB0_1012
	s_add_i32 s3, 0, 0x21000
	v_mov_b32_e32 v1, s3
	s_waitcnt vmcnt(0) expcnt(0) lgkmcnt(0)
	ds_read_b32 v3, v1
	s_add_i32 s3, 0, 0x21004
	v_mov_b32_e32 v1, s3
	ds_read_b32 v1, v1
	s_waitcnt lgkmcnt(1)
	v_cmp_ne_u32_e32 vcc, 0, v3
	s_cbranch_vccnz .LBB0_980
	s_add_u32 s4, s94, 0x40200
	s_addc_u32 s5, s95, 0
	s_add_u32 s6, s94, 0x40400
	s_addc_u32 s7, s95, 0
	s_add_u32 s8, s94, 0x40500
	s_addc_u32 s9, s95, 0
	s_add_u32 s10, s94, 0x40600
	s_addc_u32 s11, s95, 0
	s_add_u32 s12, s94, 0x40700
	s_addc_u32 s13, s95, 0
	s_add_u32 s14, s94, 0x40800
	s_addc_u32 s15, s95, 0
	s_add_u32 s16, s94, 0x40900
	s_addc_u32 s17, s95, 0
	s_add_u32 s18, s94, 0x40a00
	s_addc_u32 s19, s95, 0
	s_add_u32 s20, s94, 0x40b00
	s_addc_u32 s21, s95, 0
	s_add_u32 s22, s94, 0x40c00
	s_addc_u32 s23, s95, 0
	s_add_u32 s24, s94, 0x40d00
	s_addc_u32 s25, s95, 0
	s_add_u32 s26, s94, 0x40e00
	s_addc_u32 s27, s95, 0
	s_add_u32 s28, s94, 0x40f00
	s_addc_u32 s29, s95, 0
	s_add_u32 s30, s94, 0x41000
	s_addc_u32 s31, s95, 0
	s_add_u32 s34, s94, 0x41100
	s_addc_u32 s35, s95, 0
	s_add_u32 s36, s94, 0x41200
	v_readlane_b32 s3, v233, 0
	s_addc_u32 s37, s95, 0
	s_mul_i32 s3, s75, s3
	s_add_u32 s38, s94, 0x41300
	s_mul_i32 s3, s3, s74
	s_addc_u32 s39, s95, 0
	s_mov_b32 s33, 1
	v_mov_b32_e32 v17, 0
	s_branch .LBB0_968
